# v94 + GEMM phases: static s_setprio 1 for the trailing wave half at phase entry, all per-segment s_setprio toggles removed from the K-loops
# baseline (speedup 1.0000x reference)
; __device__ __forceinline__ int opaque_tid() { int t = (int)threadIdx.x; asm volatile("" : "+v"(t)); return t; }
; #define PG8_STAGE(bufoff, gbase, voff) do { _Pragma("unroll") for (int _i = 0; _i < 2; ++_i) \
;         __builtin_amdgcn_global_load_lds((const unsigned*)((const char*)(gbase) + (voff)[_i]), (PG8_LAS unsigned*)(lds + (bufoff) + ldsw + _i * 8192), 16, 0, 0); } while (0)
; template <class Epi, class Sched, bool ALIGN_EPI = false, bool SP2 = false>
; __device__ __forceinline__ void gemm_phase(PG8_LAS unsigned char* lds, const Gemm g, const Sched& S, const Epi& E) {
;     const int tid = opaque_tid(), wid = __builtin_amdgcn_readfirstlane(tid >> 6), lane = tid & 63, wr = wid >> 2, wc = wid & 3, fr = lane & 15, fq = lane >> 4;
;     const int K = g.K, nt = K / BK;
;     unsigned voffA[2], voffB[2];
; #pragma unroll
;     for (int i = 0; i < 2; ++i) { int R, C; stage_rc(tid * 16 + i * 8192, R, C); const int Rb = Epi::PERM ? ((R & ~31) + perm32(R & 31)) : R;
;         voffA[i] = (unsigned)(R * K + C) * 2u; voffB[i] = (unsigned)(Rb * K + C) * 2u; }
;     const size_t kstep = (size_t)(BK * 2);
;     const size_t hstep = (size_t)HALF * K * 2;
;     const size_t tstep = 2 * hstep;
;     const unsigned ldsw = (unsigned)wid * 1024u;
;     const int aoff = lds_byte(wr * 64 + fr, fq * 8), boff = lds_byte(wc * 32 + fr, fq * 8);
;     ...
;     const char* cA = (const char*)g.A + (size_t)cur.pm * tstep; const char* cB = (const char*)g.Bt + (size_t)cur.pn * tstep;
;     S.a_ready(cur);
;     if constexpr (SP2) {
;         PG8_STAGE(PG8_SB(0, 0), cB, voffB); PG8_STAGE(PG8_SB(0, 1), cB + hstep, voffB); PG8_STAGE(PG8_SA(0, 0), cA, voffA); PG8_STAGE(PG8_SA(0, 1), cA + hstep, voffA);
;         if (wr == 1) PG8_BAR;
;         PG8_WAIT_V(2); PG8_BAR;
;         PG8_STAGE(PG8_SB(1, 0), cB + kstep, voffB); PG8_STAGE(PG8_SA(1, 0), cA + kstep, voffA); PG8_STAGE(PG8_SB(1, 1), cB + hstep + kstep, voffB);
;         PG8_WAIT_V(6); PG8_BAR;
;     } else {
;         PG8_STAGE(PG8_SB(0, 0), cB, voffB); PG8_STAGE(PG8_SA(0, 0), cA, voffA); PG8_STAGE(PG8_SB(0, 1), cB + hstep, voffB); PG8_STAGE(PG8_SA(0, 1), cA + hstep, voffA);
;         if (wr == 1) PG8_BAR;
;         PG8_WAIT_V(4); PG8_BAR;
;         PG8_STAGE(PG8_SB(1, 0), cB + kstep, voffB); PG8_STAGE(PG8_SA(1, 0), cA + kstep, voffA); PG8_STAGE(PG8_SB(1, 1), cB + hstep + kstep, voffB);
;         PG8_WAIT_V(6); PG8_BAR;
;     }
.LBB0_94:
	s_add_u32 s48, s4, 0xa400000
	s_addc_u32 s49, s5, 0
	s_lshl_b32 s7, s78, 7
	s_and_b32 s7, s7, 0x100
	s_add_u32 s22, s16, s7
	s_addc_u32 s23, s17, 0
	s_add_u32 s7, s14, s7
	s_addc_u32 s11, s15, 0
	s_and_b32 s21, s19, 3
	s_add_i32 m0, s42, 0x18000
	v_lshl_add_u64 v[10:11], v[10:11], 0, s[82:83]
	s_lshl_b32 s16, s20, 13
	s_lshl_b32 s17, s21, 12
	s_waitcnt vmcnt(2)
	s_barrier
	global_load_lds_dwordx4 v[10:11], off
	v_lshl_add_u64 v[8:9], v[8:9], 0, s[82:83]
	s_add_i32 m0, s42, 0x1a000
	s_add_i32 s50, s42, 0x8000
	s_add_i32 s51, s42, 0xa000
	global_load_lds_dwordx4 v[8:9], off
	v_lshl_add_u64 v[4:5], v[4:5], 0, s[82:83]
	s_mov_b32 m0, s50
	s_add_u32 s14, s28, 0x40080
	global_load_lds_dwordx4 v[4:5], off
	v_lshl_add_u64 v[4:5], v[6:7], 0, s[82:83]
	s_mov_b32 m0, s51
	s_addc_u32 s15, s29, 0
	global_load_lds_dwordx4 v[4:5], off
	s_add_i32 m0, s42, 0x1c000
	v_lshl_add_u64 v[4:5], s[14:15], 0, v[168:169]
	global_load_lds_dwordx4 v[4:5], off
	v_lshl_add_u64 v[4:5], s[14:15], 0, v[172:173]
	s_add_i32 m0, s42, 0x1e000
	v_bfe_u32 v6, v12, 4, 2
	global_load_lds_dwordx4 v[4:5], off
	v_and_b32_e32 v5, 15, v12
	v_lshlrev_b32_e32 v4, 4, v6
	v_lshlrev_b32_e32 v7, 2, v12
	v_lshl_or_b32 v3, s20, 6, v5
	v_lshl_or_b32 v5, v5, 6, v4
	v_and_b32_e32 v7, 32, v7
	s_cmpk_lt_u32 s18, 0x100
	v_bitop3_b32 v9, v5, s16, v7 bitop3:0xde
	v_bitop3_b32 v204, v5, s17, v7 bitop3:0xde
	v_add_u32_e32 v204, 0x10000, v204
	s_cselect_b64 s[14:15], -1, 0
	s_ashr_i32 s52, s34, 31
	v_mov_b32_e32 v5, v2
	s_cmp_lg_u32 s3, 0
	v_lshl_add_u64 v[4:5], s[4:5], 0, v[4:5]
	s_mov_b64 s[2:3], 0x1a400000
	v_lshl_add_u64 v[176:177], v[4:5], 0, s[2:3]
	v_lshlrev_b32_e32 v5, 14, v13
	v_lshlrev_b32_e32 v8, 3, v6
	v_lshlrev_b32_e32 v6, 5, v6
	v_mov_b32_e32 v7, v2
	v_and_b32_e32 v5, 0xffff8000, v5
	v_lshl_add_u64 v[174:175], s[22:23], 0, v[6:7]
	v_lshl_add_u32 v5, v14, 11, v5
	v_and_b32_e32 v6, 1, v13
	v_lshl_or_b32 v5, v6, 6, v5
	v_lshl_add_u32 v178, v15, 1, v5
	v_lshlrev_b32_e32 v5, 14, v16
	v_and_b32_e32 v5, 0xffff8000, v5
	s_waitcnt vmcnt(6)
	s_cselect_b64 s[16:17], -1, 0
	s_sub_u32 s18, s7, s22
	v_lshl_add_u32 v5, v17, 11, v5
	v_and_b32_e32 v6, 1, v16
	s_subb_u32 s19, s11, s23
	v_lshl_or_b32 v4, s21, 6, v8
	v_lshl_or_b32 v5, v6, 6, v5
	s_mov_b32 s72, 0
	s_ashr_i64 s[18:19], s[18:19], 2
	v_mov_b32_e32 v179, v2
	v_lshl_add_u32 v180, v18, 1, v5
	v_mov_b32_e32 v181, v2
	v_add_u32_e32 v205, 0, v9
	v_lshlrev_b32_e32 v206, 1, v4
	s_barrier
	v_readfirstlane_b32 s100, v197
	s_cmp_lt_u32 s100, 0x100
	s_cbranch_scc1 .Lsp_0
	s_setprio 1
.Lsp_0:
	s_branch .LBB0_97
.LBB0_95:
	s_mov_b64 s[4:5], 0

; #define PG8_STAGE(bufoff, gbase, voff) do { _Pragma("unroll") for (int _i = 0; _i < 2; ++_i) \
;         __builtin_amdgcn_global_load_lds((const unsigned*)((const char*)(gbase) + (voff)[_i]), (PG8_LAS unsigned*)(lds + (bufoff) + ldsw + _i * 8192), 16, 0, 0); } while (0)
; #define PG8_LDA(dst, b, h) do { _Pragma("unroll") for (int m = 0; m < 4; ++m) _Pragma("unroll") for (int k = 0; k < 2; ++k) dst[m][k] = *(const PG8_LAS bf16x8*)(lds + PG8_SA(b, h) + aoff + m * 2048 + k * 1024); } while (0)
; #define PG8_LDB(dst, b, h) do { _Pragma("unroll") for (int n = 0; n < 2; ++n) _Pragma("unroll") for (int k = 0; k < 2; ++k) dst[n][k] = *(const PG8_LAS bf16x8*)(lds + PG8_SB(b, h) + boff + n * 2048 + k * 1024); } while (0)
; #define PG8_WAIT_V(n) asm volatile("s_waitcnt vmcnt(" #n ")" ::: "memory")
; #define PG8_WAIT_L(n) asm volatile("s_waitcnt lgkmcnt(" #n ")" ::: "memory")
; #define PG8_BAR __builtin_amdgcn_s_barrier()
; #define PG8_SCHED __builtin_amdgcn_sched_barrier(0)
; template <class Epi, class Sched, bool ALIGN_EPI = false, bool SP2 = false>
; __device__ __forceinline__ void gemm_phase(PG8_LAS unsigned char* lds, const Gemm g, const Sched& S, const Epi& E) {
;     ...
;         const bool has_next = S.next(ui + 1, nxt);
;         const char* nA = has_next ? (const char*)g.A + (size_t)nxt.pm * tstep : cA; const char* nB = has_next ? (const char*)g.Bt + (size_t)nxt.pn * tstep : cB;
;         for (int t = 0; t < nt; t += 2) {
;             const bool last = (t == nt - 2);
;             const char* a1 = cA + (size_t)(t + 1) * kstep;
;             const char* a2 = last ? nA : cA + (size_t)(t + 2) * kstep; const char* b2 = last ? nB : cB + (size_t)(t + 2) * kstep;
;             const char* a3 = a2 + kstep; const char* b3 = b2 + kstep;
;             if (last && has_next) S.a_ready(nxt);
;             if constexpr (SP2) {
;             PG8_LDB(B0, 0, 0); PG8_LDB(B1, 0, 1); PG8_SCHED; PG8_LDA(At, 0, 0); PG8_STAGE(PG8_SA(1, 1), a1 + hstep, voffA);
;             PG8_WAIT_V(8); PG8_WAIT_L(0); PG8_BAR; PG8_MMA(0, 0, At, B0); PG8_MMA(0, 1, At, B1); PG8_BAR; PG8_SCHED;
;             PG8_LDA(At, 0, 1); PG8_STAGE(PG8_SB(0, 0), b2, voffB); PG8_STAGE(PG8_SB(0, 1), b2 + hstep, voffB); PG8_STAGE(PG8_SA(0, 0), a2, voffA);
;             PG8_WAIT_V(8); PG8_WAIT_L(0); PG8_BAR; PG8_MMA(1, 0, At, B0); PG8_MMA(1, 1, At, B1); PG8_BAR; PG8_SCHED;
.LBB0_99:
	s_ashr_i32 s21, s20, 31
	s_lshl_b64 s[24:25], s[20:21], 19
	s_add_u32 s24, s35, s24
	s_addc_u32 s25, s38, s25
	s_and_b64 s[26:27], s[4:5], exec
	s_cselect_b32 s3, s25, s9
	s_cselect_b32 s7, s24, s8
	s_ashr_i32 s23, s22, 31
	s_lshl_b64 s[26:27], s[22:23], 19
	s_add_u32 s26, s39, s26
	s_addc_u32 s27, s40, s27
	s_and_b64 s[30:31], s[4:5], exec
	s_cselect_b32 s11, s27, s29
	s_cselect_b32 s21, s26, s28
	s_add_u32 s8, s8, 0x40080
	s_addc_u32 s9, s9, 0
	s_add_u32 s23, s28, 0x100
	s_addc_u32 s44, s29, 0
	s_mov_b32 s45, -2
	s_add_u32 s28, s8, 0xfffc0080
	s_addc_u32 s29, s9, -1
	s_cmp_eq_u32 s45, 12
	s_cselect_b32 s31, s3, s29
	s_cselect_b32 s30, s7, s28
	s_cselect_b32 s29, s11, s44
	s_cselect_b32 s28, s21, s23
	ds_read_b128 v[132:135], v204
	ds_read_b128 v[136:139], v204 offset:1024
	ds_read_b128 v[140:143], v204 offset:2048
	ds_read_b128 v[144:147], v204 offset:3072
	ds_read_b128 v[148:151], v204 offset:16384
	ds_read_b128 v[152:155], v204 offset:17408
	ds_read_b128 v[156:159], v204 offset:18432
	ds_read_b128 v[160:163], v204 offset:19456
	v_lshl_add_u64 v[194:195], s[8:9], 0, v[178:179]
	s_add_i32 m0, s42, 0xc000
	ds_read_b128 v[164:167], v205
	ds_read_b128 v[182:185], v205 offset:1024
	ds_read_b128 v[186:189], v205 offset:2048
	ds_read_b128 v[190:193], v205 offset:3072
	ds_read_b128 v[208:211], v205 offset:4096
	ds_read_b128 v[212:215], v205 offset:5120
	ds_read_b128 v[216:219], v205 offset:6144
	ds_read_b128 v[220:223], v205 offset:7168
	global_load_lds_dwordx4 v[194:195], off
	s_add_i32 m0, s42, 0xe000
	v_lshl_add_u64 v[194:195], s[8:9], 0, v[180:181]
	global_load_lds_dwordx4 v[194:195], off
	s_waitcnt vmcnt(8) lgkmcnt(0)
	s_barrier
	v_mfma_f32_16x16x32_bf16 v[128:131], v[132:135], v[164:167], 0
	v_mfma_f32_16x16x32_bf16 v[124:127], v[140:143], v[164:167], 0
	v_mfma_f32_16x16x32_bf16 v[112:115], v[132:135], v[186:189], 0
	v_mfma_f32_16x16x32_bf16 v[108:111], v[140:143], v[186:189], 0
	v_mfma_f32_16x16x32_bf16 v[96:99], v[132:135], v[208:211], 0
	v_mfma_f32_16x16x32_bf16 v[92:95], v[140:143], v[208:211], 0
	v_mfma_f32_16x16x32_bf16 v[80:83], v[132:135], v[216:219], 0
	v_mfma_f32_16x16x32_bf16 v[76:79], v[140:143], v[216:219], 0
	v_mfma_f32_16x16x32_bf16 v[128:131], v[136:139], v[182:185], v[128:131]
	v_mfma_f32_16x16x32_bf16 v[124:127], v[144:147], v[182:185], v[124:127]
	v_mfma_f32_16x16x32_bf16 v[112:115], v[136:139], v[190:193], v[112:115]
	v_mfma_f32_16x16x32_bf16 v[108:111], v[144:147], v[190:193], v[108:111]
	v_mfma_f32_16x16x32_bf16 v[96:99], v[136:139], v[212:215], v[96:99]
	v_mfma_f32_16x16x32_bf16 v[92:95], v[144:147], v[212:215], v[92:95]
	v_mfma_f32_16x16x32_bf16 v[80:83], v[136:139], v[220:223], v[80:83]
	v_mfma_f32_16x16x32_bf16 v[76:79], v[144:147], v[220:223], v[76:79]
	v_mfma_f32_16x16x32_bf16 v[120:123], v[148:151], v[164:167], 0
	v_mfma_f32_16x16x32_bf16 v[116:119], v[156:159], v[164:167], 0
	v_mfma_f32_16x16x32_bf16 v[104:107], v[148:151], v[186:189], 0
	v_mfma_f32_16x16x32_bf16 v[100:103], v[156:159], v[186:189], 0
	v_mfma_f32_16x16x32_bf16 v[88:91], v[148:151], v[208:211], 0
	v_mfma_f32_16x16x32_bf16 v[84:87], v[156:159], v[208:211], 0
	v_mfma_f32_16x16x32_bf16 v[72:75], v[148:151], v[216:219], 0
	v_mfma_f32_16x16x32_bf16 v[68:71], v[156:159], v[216:219], 0
	v_mfma_f32_16x16x32_bf16 v[120:123], v[152:155], v[182:185], v[120:123]
	v_mfma_f32_16x16x32_bf16 v[116:119], v[160:163], v[182:185], v[116:119]
	v_mfma_f32_16x16x32_bf16 v[104:107], v[152:155], v[190:193], v[104:107]
	v_mfma_f32_16x16x32_bf16 v[100:103], v[160:163], v[190:193], v[100:103]
	v_mfma_f32_16x16x32_bf16 v[88:91], v[152:155], v[212:215], v[88:91]
	v_mfma_f32_16x16x32_bf16 v[84:87], v[160:163], v[212:215], v[84:87]
	v_mfma_f32_16x16x32_bf16 v[72:75], v[152:155], v[220:223], v[72:75]
	v_mfma_f32_16x16x32_bf16 v[68:71], v[160:163], v[220:223], v[68:71]
	s_barrier
	v_lshl_add_u64 v[194:195], s[28:29], 0, v[168:169]
	s_add_i32 m0, s41, 0x10000
	ds_read_b128 v[164:167], v205 offset:16384
	ds_read_b128 v[182:185], v205 offset:17408
	ds_read_b128 v[186:189], v205 offset:18432
	ds_read_b128 v[190:193], v205 offset:19456
	ds_read_b128 v[208:211], v205 offset:20480
	ds_read_b128 v[212:215], v205 offset:21504
	ds_read_b128 v[216:219], v205 offset:22528
	ds_read_b128 v[220:223], v205 offset:23552
	global_load_lds_dwordx4 v[194:195], off
	s_add_i32 m0, s41, 0x12000
	s_add_u32 s54, s28, 0x40000
	v_lshl_add_u64 v[202:203], s[28:29], 0, v[172:173]
	s_addc_u32 s55, s29, 0
	global_load_lds_dwordx4 v[202:203], off
	v_lshl_add_u64 v[224:225], s[54:55], 0, v[168:169]
	s_add_i32 m0, s41, 0x14000
	v_lshl_add_u64 v[226:227], s[30:31], 0, v[170:171]
	global_load_lds_dwordx4 v[224:225], off
	s_add_i32 m0, s41, 0x16000
	v_lshl_add_u64 v[224:225], s[54:55], 0, v[172:173]
	global_load_lds_dwordx4 v[224:225], off
	s_mov_b32 m0, s42
	v_lshl_add_u64 v[224:225], s[30:31], 0, v[0:1]
	global_load_lds_dwordx4 v[224:225], off
	s_mov_b32 m0, s43
	s_add_i32 s53, 0, 0x18000
	global_load_lds_dwordx4 v[226:227], off
	s_waitcnt vmcnt(8) lgkmcnt(0)
	s_barrier
; #define PG8_STAGE(bufoff, gbase, voff) do { _Pragma("unroll") for (int _i = 0; _i < 2; ++_i) \
;         __builtin_amdgcn_global_load_lds((const unsigned*)((const char*)(gbase) + (voff)[_i]), (PG8_LAS unsigned*)(lds + (bufoff) + ldsw + _i * 8192), 16, 0, 0); } while (0)
; #define PG8_LDA(dst, b, h) do { _Pragma("unroll") for (int m = 0; m < 4; ++m) _Pragma("unroll") for (int k = 0; k < 2; ++k) dst[m][k] = *(const PG8_LAS bf16x8*)(lds + PG8_SA(b, h) + aoff + m * 2048 + k * 1024); } while (0)
; #define PG8_LDB(dst, b, h) do { _Pragma("unroll") for (int n = 0; n < 2; ++n) _Pragma("unroll") for (int k = 0; k < 2; ++k) dst[n][k] = *(const PG8_LAS bf16x8*)(lds + PG8_SB(b, h) + boff + n * 2048 + k * 1024); } while (0)
; #define PG8_MMA(ai, bj, At, Bt) do { __builtin_amdgcn_s_setprio(1); _Pragma("unroll") for (int m = 0; m < 4; ++m) _Pragma("unroll") for (int n = 0; n < 2; ++n) _Pragma("unroll") for (int k = 0; k < 2; ++k) \
;         acc[ai][bj][m][n] = __builtin_amdgcn_mfma_f32_16x16x32_bf16(Bt[n][k], At[m][k], acc[ai][bj][m][n], 0, 0, 0); __builtin_amdgcn_s_setprio(0); } while (0)
; #define PG8_WAIT_V(n) asm volatile("s_waitcnt vmcnt(" #n ")" ::: "memory")
; #define PG8_WAIT_L(n) asm volatile("s_waitcnt lgkmcnt(" #n ")" ::: "memory")
; #define PG8_BAR __builtin_amdgcn_s_barrier()
; #define PG8_SCHED __builtin_amdgcn_sched_barrier(0)
; template <class Epi, class Sched, bool ALIGN_EPI = false, bool SP2 = false>
; __device__ __forceinline__ void gemm_phase(PG8_LAS unsigned char* lds, const Gemm g, const Sched& S, const Epi& E) {
;     ...
;             PG8_LDB(B0, 0, 0); PG8_LDB(B1, 0, 1); PG8_SCHED; PG8_LDA(At, 0, 0); PG8_STAGE(PG8_SA(1, 1), a1 + hstep, voffA);
;             PG8_WAIT_V(8); PG8_WAIT_L(0); PG8_BAR; PG8_MMA(0, 0, At, B0); PG8_MMA(0, 1, At, B1); PG8_BAR; PG8_SCHED;
;             PG8_LDA(At, 0, 1); PG8_STAGE(PG8_SB(0, 0), b2, voffB); PG8_STAGE(PG8_SB(0, 1), b2 + hstep, voffB); PG8_STAGE(PG8_SA(0, 0), a2, voffA);
;             PG8_WAIT_V(8); PG8_WAIT_L(0); PG8_BAR; PG8_MMA(1, 0, At, B0); PG8_MMA(1, 1, At, B1); PG8_BAR; PG8_SCHED;
	v_mfma_f32_16x16x32_bf16 v[64:67], v[132:135], v[164:167], 0
	v_mfma_f32_16x16x32_bf16 v[60:63], v[140:143], v[164:167], 0
	v_mfma_f32_16x16x32_bf16 v[48:51], v[132:135], v[186:189], 0
	v_mfma_f32_16x16x32_bf16 v[44:47], v[140:143], v[186:189], 0
	v_mfma_f32_16x16x32_bf16 v[32:35], v[132:135], v[208:211], 0
	v_mfma_f32_16x16x32_bf16 v[28:31], v[140:143], v[208:211], 0
	v_mfma_f32_16x16x32_bf16 v[16:19], v[132:135], v[216:219], 0
	v_mfma_f32_16x16x32_bf16 v[12:15], v[140:143], v[216:219], 0
	v_mfma_f32_16x16x32_bf16 v[64:67], v[136:139], v[182:185], v[64:67]
	v_mfma_f32_16x16x32_bf16 v[60:63], v[144:147], v[182:185], v[60:63]
	v_mfma_f32_16x16x32_bf16 v[48:51], v[136:139], v[190:193], v[48:51]
	v_mfma_f32_16x16x32_bf16 v[44:47], v[144:147], v[190:193], v[44:47]
	v_mfma_f32_16x16x32_bf16 v[32:35], v[136:139], v[212:215], v[32:35]
	v_mfma_f32_16x16x32_bf16 v[28:31], v[144:147], v[212:215], v[28:31]
	v_mfma_f32_16x16x32_bf16 v[16:19], v[136:139], v[220:223], v[16:19]
	v_mfma_f32_16x16x32_bf16 v[12:15], v[144:147], v[220:223], v[12:15]
	v_mfma_f32_16x16x32_bf16 v[56:59], v[148:151], v[164:167], 0
	v_mfma_f32_16x16x32_bf16 v[52:55], v[156:159], v[164:167], 0
	v_mfma_f32_16x16x32_bf16 v[40:43], v[148:151], v[186:189], 0
	v_mfma_f32_16x16x32_bf16 v[36:39], v[156:159], v[186:189], 0
	v_mfma_f32_16x16x32_bf16 v[24:27], v[148:151], v[208:211], 0
	v_mfma_f32_16x16x32_bf16 v[20:23], v[156:159], v[208:211], 0
	v_mfma_f32_16x16x32_bf16 v[8:11], v[148:151], v[216:219], 0
	v_mfma_f32_16x16x32_bf16 v[4:7], v[156:159], v[216:219], 0
	v_mfma_f32_16x16x32_bf16 v[56:59], v[152:155], v[182:185], v[56:59]
	v_mfma_f32_16x16x32_bf16 v[52:55], v[160:163], v[182:185], v[52:55]
	v_mfma_f32_16x16x32_bf16 v[40:43], v[152:155], v[190:193], v[40:43]
	v_mfma_f32_16x16x32_bf16 v[36:39], v[160:163], v[190:193], v[36:39]
	v_mfma_f32_16x16x32_bf16 v[24:27], v[152:155], v[212:215], v[24:27]
	v_mfma_f32_16x16x32_bf16 v[20:23], v[160:163], v[212:215], v[20:23]
	v_mfma_f32_16x16x32_bf16 v[8:11], v[152:155], v[220:223], v[8:11]
	v_mfma_f32_16x16x32_bf16 v[4:7], v[160:163], v[220:223], v[4:7]
	s_barrier
	s_branch .Lkmid_0
.LBB0_100:
	s_add_u32 s28, s8, 0xfffc0080
	s_addc_u32 s29, s9, -1
	s_cmp_eq_u32 s45, 12
	s_cselect_b32 s31, s3, s29
	s_cselect_b32 s30, s7, s28
	s_cselect_b32 s29, s11, s44
	s_cselect_b32 s28, s21, s23
	ds_read_b128 v[132:135], v204
	ds_read_b128 v[136:139], v204 offset:1024
	ds_read_b128 v[140:143], v204 offset:2048
	ds_read_b128 v[144:147], v204 offset:3072
	ds_read_b128 v[148:151], v204 offset:16384
	ds_read_b128 v[152:155], v204 offset:17408
	ds_read_b128 v[156:159], v204 offset:18432
	ds_read_b128 v[160:163], v204 offset:19456
	v_lshl_add_u64 v[194:195], s[8:9], 0, v[178:179]
	s_add_i32 m0, s42, 0xc000
	ds_read_b128 v[164:167], v205
	ds_read_b128 v[182:185], v205 offset:1024
	ds_read_b128 v[186:189], v205 offset:2048
	ds_read_b128 v[190:193], v205 offset:3072
	ds_read_b128 v[208:211], v205 offset:4096
	ds_read_b128 v[212:215], v205 offset:5120
	ds_read_b128 v[216:219], v205 offset:6144
	ds_read_b128 v[220:223], v205 offset:7168
	global_load_lds_dwordx4 v[194:195], off
	s_add_i32 m0, s42, 0xe000
	v_lshl_add_u64 v[194:195], s[8:9], 0, v[180:181]
	global_load_lds_dwordx4 v[194:195], off
	s_waitcnt vmcnt(8) lgkmcnt(0)
	s_barrier
	v_mfma_f32_16x16x32_bf16 v[128:131], v[132:135], v[164:167], v[128:131]
	v_mfma_f32_16x16x32_bf16 v[124:127], v[140:143], v[164:167], v[124:127]
	v_mfma_f32_16x16x32_bf16 v[112:115], v[132:135], v[186:189], v[112:115]
	v_mfma_f32_16x16x32_bf16 v[108:111], v[140:143], v[186:189], v[108:111]
	v_mfma_f32_16x16x32_bf16 v[96:99], v[132:135], v[208:211], v[96:99]
	v_mfma_f32_16x16x32_bf16 v[92:95], v[140:143], v[208:211], v[92:95]
	v_mfma_f32_16x16x32_bf16 v[80:83], v[132:135], v[216:219], v[80:83]
	v_mfma_f32_16x16x32_bf16 v[76:79], v[140:143], v[216:219], v[76:79]
	v_mfma_f32_16x16x32_bf16 v[128:131], v[136:139], v[182:185], v[128:131]
	v_mfma_f32_16x16x32_bf16 v[124:127], v[144:147], v[182:185], v[124:127]
	v_mfma_f32_16x16x32_bf16 v[112:115], v[136:139], v[190:193], v[112:115]
	v_mfma_f32_16x16x32_bf16 v[108:111], v[144:147], v[190:193], v[108:111]
	v_mfma_f32_16x16x32_bf16 v[96:99], v[136:139], v[212:215], v[96:99]
	v_mfma_f32_16x16x32_bf16 v[92:95], v[144:147], v[212:215], v[92:95]
	v_mfma_f32_16x16x32_bf16 v[80:83], v[136:139], v[220:223], v[80:83]
	v_mfma_f32_16x16x32_bf16 v[76:79], v[144:147], v[220:223], v[76:79]
	v_mfma_f32_16x16x32_bf16 v[120:123], v[148:151], v[164:167], v[120:123]
	v_mfma_f32_16x16x32_bf16 v[116:119], v[156:159], v[164:167], v[116:119]
	v_mfma_f32_16x16x32_bf16 v[104:107], v[148:151], v[186:189], v[104:107]
	v_mfma_f32_16x16x32_bf16 v[100:103], v[156:159], v[186:189], v[100:103]
	v_mfma_f32_16x16x32_bf16 v[88:91], v[148:151], v[208:211], v[88:91]
	v_mfma_f32_16x16x32_bf16 v[84:87], v[156:159], v[208:211], v[84:87]
	v_mfma_f32_16x16x32_bf16 v[72:75], v[148:151], v[216:219], v[72:75]
	v_mfma_f32_16x16x32_bf16 v[68:71], v[156:159], v[216:219], v[68:71]
	v_mfma_f32_16x16x32_bf16 v[120:123], v[152:155], v[182:185], v[120:123]
	v_mfma_f32_16x16x32_bf16 v[116:119], v[160:163], v[182:185], v[116:119]
	v_mfma_f32_16x16x32_bf16 v[104:107], v[152:155], v[190:193], v[104:107]
	v_mfma_f32_16x16x32_bf16 v[100:103], v[160:163], v[190:193], v[100:103]
	v_mfma_f32_16x16x32_bf16 v[88:91], v[152:155], v[212:215], v[88:91]
	v_mfma_f32_16x16x32_bf16 v[84:87], v[160:163], v[212:215], v[84:87]
	v_mfma_f32_16x16x32_bf16 v[72:75], v[152:155], v[220:223], v[72:75]
	v_mfma_f32_16x16x32_bf16 v[68:71], v[160:163], v[220:223], v[68:71]
	s_barrier
; #define PG8_STAGE(bufoff, gbase, voff) do { _Pragma("unroll") for (int _i = 0; _i < 2; ++_i) \
;         __builtin_amdgcn_global_load_lds((const unsigned*)((const char*)(gbase) + (voff)[_i]), (PG8_LAS unsigned*)(lds + (bufoff) + ldsw + _i * 8192), 16, 0, 0); } while (0)
; #define PG8_LDA(dst, b, h) do { _Pragma("unroll") for (int m = 0; m < 4; ++m) _Pragma("unroll") for (int k = 0; k < 2; ++k) dst[m][k] = *(const PG8_LAS bf16x8*)(lds + PG8_SA(b, h) + aoff + m * 2048 + k * 1024); } while (0)
; #define PG8_MMA(ai, bj, At, Bt) do { __builtin_amdgcn_s_setprio(1); _Pragma("unroll") for (int m = 0; m < 4; ++m) _Pragma("unroll") for (int n = 0; n < 2; ++n) _Pragma("unroll") for (int k = 0; k < 2; ++k) \
;         acc[ai][bj][m][n] = __builtin_amdgcn_mfma_f32_16x16x32_bf16(Bt[n][k], At[m][k], acc[ai][bj][m][n], 0, 0, 0); __builtin_amdgcn_s_setprio(0); } while (0)
; #define PG8_WAIT_V(n) asm volatile("s_waitcnt vmcnt(" #n ")" ::: "memory")
; #define PG8_WAIT_L(n) asm volatile("s_waitcnt lgkmcnt(" #n ")" ::: "memory")
; #define PG8_BAR __builtin_amdgcn_s_barrier()
; #define PG8_SCHED __builtin_amdgcn_sched_barrier(0)
; template <class Epi, class Sched, bool ALIGN_EPI = false, bool SP2 = false>
; __device__ __forceinline__ void gemm_phase(PG8_LAS unsigned char* lds, const Gemm g, const Sched& S, const Epi& E) {
;     ...
;             PG8_LDA(At, 0, 1); PG8_STAGE(PG8_SB(0, 0), b2, voffB); PG8_STAGE(PG8_SB(0, 1), b2 + hstep, voffB); PG8_STAGE(PG8_SA(0, 0), a2, voffA);
;             PG8_WAIT_V(8); PG8_WAIT_L(0); PG8_BAR; PG8_MMA(1, 0, At, B0); PG8_MMA(1, 1, At, B1); PG8_BAR; PG8_SCHED;
	v_lshl_add_u64 v[194:195], s[28:29], 0, v[168:169]
	s_add_i32 m0, s41, 0x10000
	ds_read_b128 v[164:167], v205 offset:16384
	ds_read_b128 v[182:185], v205 offset:17408
	ds_read_b128 v[186:189], v205 offset:18432
	ds_read_b128 v[190:193], v205 offset:19456
	ds_read_b128 v[208:211], v205 offset:20480
	ds_read_b128 v[212:215], v205 offset:21504
	ds_read_b128 v[216:219], v205 offset:22528
	ds_read_b128 v[220:223], v205 offset:23552
	global_load_lds_dwordx4 v[194:195], off
	s_add_i32 m0, s41, 0x12000
	s_add_u32 s54, s28, 0x40000
	v_lshl_add_u64 v[202:203], s[28:29], 0, v[172:173]
	s_addc_u32 s55, s29, 0
	global_load_lds_dwordx4 v[202:203], off
	v_lshl_add_u64 v[224:225], s[54:55], 0, v[168:169]
	s_add_i32 m0, s41, 0x14000
	v_lshl_add_u64 v[226:227], s[30:31], 0, v[170:171]
	global_load_lds_dwordx4 v[224:225], off
	s_add_i32 m0, s41, 0x16000
	v_lshl_add_u64 v[224:225], s[54:55], 0, v[172:173]
	global_load_lds_dwordx4 v[224:225], off
	s_mov_b32 m0, s42
	v_lshl_add_u64 v[224:225], s[30:31], 0, v[0:1]
	global_load_lds_dwordx4 v[224:225], off
	s_mov_b32 m0, s43
	s_add_i32 s53, 0, 0x18000
	global_load_lds_dwordx4 v[226:227], off
	s_waitcnt vmcnt(8) lgkmcnt(0)
	s_barrier
	v_mfma_f32_16x16x32_bf16 v[64:67], v[132:135], v[164:167], v[64:67]
	v_mfma_f32_16x16x32_bf16 v[60:63], v[140:143], v[164:167], v[60:63]
	v_mfma_f32_16x16x32_bf16 v[48:51], v[132:135], v[186:189], v[48:51]
	v_mfma_f32_16x16x32_bf16 v[44:47], v[140:143], v[186:189], v[44:47]
	v_mfma_f32_16x16x32_bf16 v[32:35], v[132:135], v[208:211], v[32:35]
	v_mfma_f32_16x16x32_bf16 v[28:31], v[140:143], v[208:211], v[28:31]
	v_mfma_f32_16x16x32_bf16 v[16:19], v[132:135], v[216:219], v[16:19]
	v_mfma_f32_16x16x32_bf16 v[12:15], v[140:143], v[216:219], v[12:15]
	v_mfma_f32_16x16x32_bf16 v[64:67], v[136:139], v[182:185], v[64:67]
	v_mfma_f32_16x16x32_bf16 v[60:63], v[144:147], v[182:185], v[60:63]
	v_mfma_f32_16x16x32_bf16 v[48:51], v[136:139], v[190:193], v[48:51]
	v_mfma_f32_16x16x32_bf16 v[44:47], v[144:147], v[190:193], v[44:47]
	v_mfma_f32_16x16x32_bf16 v[32:35], v[136:139], v[212:215], v[32:35]
	v_mfma_f32_16x16x32_bf16 v[28:31], v[144:147], v[212:215], v[28:31]
	v_mfma_f32_16x16x32_bf16 v[16:19], v[136:139], v[220:223], v[16:19]
	v_mfma_f32_16x16x32_bf16 v[12:15], v[144:147], v[220:223], v[12:15]
	v_mfma_f32_16x16x32_bf16 v[56:59], v[148:151], v[164:167], v[56:59]
	v_mfma_f32_16x16x32_bf16 v[52:55], v[156:159], v[164:167], v[52:55]
	v_mfma_f32_16x16x32_bf16 v[40:43], v[148:151], v[186:189], v[40:43]
	v_mfma_f32_16x16x32_bf16 v[36:39], v[156:159], v[186:189], v[36:39]
	v_mfma_f32_16x16x32_bf16 v[24:27], v[148:151], v[208:211], v[24:27]
	v_mfma_f32_16x16x32_bf16 v[20:23], v[156:159], v[208:211], v[20:23]
	v_mfma_f32_16x16x32_bf16 v[8:11], v[148:151], v[216:219], v[8:11]
	v_mfma_f32_16x16x32_bf16 v[4:7], v[156:159], v[216:219], v[4:7]
	v_mfma_f32_16x16x32_bf16 v[56:59], v[152:155], v[182:185], v[56:59]
	v_mfma_f32_16x16x32_bf16 v[52:55], v[160:163], v[182:185], v[52:55]
	v_mfma_f32_16x16x32_bf16 v[40:43], v[152:155], v[190:193], v[40:43]
	v_mfma_f32_16x16x32_bf16 v[36:39], v[160:163], v[190:193], v[36:39]
	v_mfma_f32_16x16x32_bf16 v[24:27], v[152:155], v[212:215], v[24:27]
	v_mfma_f32_16x16x32_bf16 v[20:23], v[160:163], v[212:215], v[20:23]
	v_mfma_f32_16x16x32_bf16 v[8:11], v[152:155], v[220:223], v[8:11]
	v_mfma_f32_16x16x32_bf16 v[4:7], v[160:163], v[220:223], v[4:7]
	s_barrier
; #define PG8_STAGE(bufoff, gbase, voff) do { _Pragma("unroll") for (int _i = 0; _i < 2; ++_i) \
;         __builtin_amdgcn_global_load_lds((const unsigned*)((const char*)(gbase) + (voff)[_i]), (PG8_LAS unsigned*)(lds + (bufoff) + ldsw + _i * 8192), 16, 0, 0); } while (0)
; #define PG8_LDA(dst, b, h) do { _Pragma("unroll") for (int m = 0; m < 4; ++m) _Pragma("unroll") for (int k = 0; k < 2; ++k) dst[m][k] = *(const PG8_LAS bf16x8*)(lds + PG8_SA(b, h) + aoff + m * 2048 + k * 1024); } while (0)
; #define PG8_LDB(dst, b, h) do { _Pragma("unroll") for (int n = 0; n < 2; ++n) _Pragma("unroll") for (int k = 0; k < 2; ++k) dst[n][k] = *(const PG8_LAS bf16x8*)(lds + PG8_SB(b, h) + boff + n * 2048 + k * 1024); } while (0)
; #define PG8_MMA(ai, bj, At, Bt) do { __builtin_amdgcn_s_setprio(1); _Pragma("unroll") for (int m = 0; m < 4; ++m) _Pragma("unroll") for (int n = 0; n < 2; ++n) _Pragma("unroll") for (int k = 0; k < 2; ++k) \
;         acc[ai][bj][m][n] = __builtin_amdgcn_mfma_f32_16x16x32_bf16(Bt[n][k], At[m][k], acc[ai][bj][m][n], 0, 0, 0); __builtin_amdgcn_s_setprio(0); } while (0)
; #define PG8_WAIT_V(n) asm volatile("s_waitcnt vmcnt(" #n ")" ::: "memory")
; #define PG8_WAIT_L(n) asm volatile("s_waitcnt lgkmcnt(" #n ")" ::: "memory")
; #define PG8_BAR __builtin_amdgcn_s_barrier()
; #define PG8_SCHED __builtin_amdgcn_sched_barrier(0)
; template <class Epi, class Sched, bool ALIGN_EPI = false, bool SP2 = false>
; __device__ __forceinline__ void gemm_phase(PG8_LAS unsigned char* lds, const Gemm g, const Sched& S, const Epi& E) {
;     ...
;             PG8_LDB(B0, 1, 0); PG8_LDB(B1, 1, 1); PG8_SCHED; PG8_LDA(At, 1, 0); PG8_STAGE(PG8_SA(0, 1), a2 + hstep, voffA);
;             PG8_WAIT_V(8); PG8_WAIT_L(0); PG8_BAR; PG8_MMA(0, 0, At, B0); PG8_MMA(0, 1, At, B1); PG8_BAR; PG8_SCHED;
;             PG8_LDA(At, 1, 1); PG8_STAGE(PG8_SB(1, 0), b3, voffB); PG8_STAGE(PG8_SB(1, 1), b3 + hstep, voffB); PG8_STAGE(PG8_SA(1, 0), a3, voffA);
;             PG8_WAIT_V(8); PG8_WAIT_L(0); PG8_BAR; PG8_MMA(1, 0, At, B0); PG8_MMA(1, 1, At, B1); PG8_BAR; PG8_SCHED;
;     ...
;         if constexpr (ALIGN_EPI) { if (wr == 0) PG8_BAR; }
.Lkmid_0:
	ds_read_b128 v[132:135], v204 offset:32768
	ds_read_b128 v[136:139], v204 offset:33792
	ds_read_b128 v[140:143], v204 offset:34816
	ds_read_b128 v[144:147], v204 offset:35840
	ds_read_b128 v[148:151], v204 offset:49152
	ds_read_b128 v[152:155], v204 offset:50176
	ds_read_b128 v[156:159], v204 offset:51200
	ds_read_b128 v[160:163], v204 offset:52224
	s_add_u32 s30, s30, 0x40000
	s_addc_u32 s31, s31, 0
	s_mov_b32 m0, s46
	v_lshl_add_u64 v[228:229], s[30:31], 0, v[0:1]
	ds_read_b128 v[164:167], v205 offset:32768
	ds_read_b128 v[182:185], v205 offset:33792
	ds_read_b128 v[186:189], v205 offset:34816
	ds_read_b128 v[190:193], v205 offset:35840
	ds_read_b128 v[208:211], v205 offset:36864
	ds_read_b128 v[212:215], v205 offset:37888
	ds_read_b128 v[216:219], v205 offset:38912
	ds_read_b128 v[220:223], v205 offset:39936
	global_load_lds_dwordx4 v[228:229], off
	s_mov_b32 m0, s47
	v_lshl_add_u64 v[228:229], s[30:31], 0, v[170:171]
	global_load_lds_dwordx4 v[228:229], off
	s_waitcnt vmcnt(8) lgkmcnt(0)
	s_barrier
	v_mfma_f32_16x16x32_bf16 v[128:131], v[132:135], v[164:167], v[128:131]
	v_mfma_f32_16x16x32_bf16 v[124:127], v[140:143], v[164:167], v[124:127]
	v_mfma_f32_16x16x32_bf16 v[112:115], v[132:135], v[186:189], v[112:115]
	v_mfma_f32_16x16x32_bf16 v[108:111], v[140:143], v[186:189], v[108:111]
	v_mfma_f32_16x16x32_bf16 v[96:99], v[132:135], v[208:211], v[96:99]
	v_mfma_f32_16x16x32_bf16 v[92:95], v[140:143], v[208:211], v[92:95]
	v_mfma_f32_16x16x32_bf16 v[80:83], v[132:135], v[216:219], v[80:83]
	v_mfma_f32_16x16x32_bf16 v[76:79], v[140:143], v[216:219], v[76:79]
	v_mfma_f32_16x16x32_bf16 v[128:131], v[136:139], v[182:185], v[128:131]
	v_mfma_f32_16x16x32_bf16 v[124:127], v[144:147], v[182:185], v[124:127]
	v_mfma_f32_16x16x32_bf16 v[112:115], v[136:139], v[190:193], v[112:115]
	v_mfma_f32_16x16x32_bf16 v[108:111], v[144:147], v[190:193], v[108:111]
	v_mfma_f32_16x16x32_bf16 v[96:99], v[136:139], v[212:215], v[96:99]
	v_mfma_f32_16x16x32_bf16 v[92:95], v[144:147], v[212:215], v[92:95]
	v_mfma_f32_16x16x32_bf16 v[80:83], v[136:139], v[220:223], v[80:83]
	v_mfma_f32_16x16x32_bf16 v[76:79], v[144:147], v[220:223], v[76:79]
	v_mfma_f32_16x16x32_bf16 v[120:123], v[148:151], v[164:167], v[120:123]
	v_mfma_f32_16x16x32_bf16 v[116:119], v[156:159], v[164:167], v[116:119]
	v_mfma_f32_16x16x32_bf16 v[104:107], v[148:151], v[186:189], v[104:107]
	v_mfma_f32_16x16x32_bf16 v[100:103], v[156:159], v[186:189], v[100:103]
	v_mfma_f32_16x16x32_bf16 v[88:91], v[148:151], v[208:211], v[88:91]
	v_mfma_f32_16x16x32_bf16 v[84:87], v[156:159], v[208:211], v[84:87]
	v_mfma_f32_16x16x32_bf16 v[72:75], v[148:151], v[216:219], v[72:75]
	v_mfma_f32_16x16x32_bf16 v[68:71], v[156:159], v[216:219], v[68:71]
	v_mfma_f32_16x16x32_bf16 v[120:123], v[152:155], v[182:185], v[120:123]
	v_mfma_f32_16x16x32_bf16 v[116:119], v[160:163], v[182:185], v[116:119]
	v_mfma_f32_16x16x32_bf16 v[104:107], v[152:155], v[190:193], v[104:107]
	v_mfma_f32_16x16x32_bf16 v[100:103], v[160:163], v[190:193], v[100:103]
	v_mfma_f32_16x16x32_bf16 v[88:91], v[152:155], v[212:215], v[88:91]
	v_mfma_f32_16x16x32_bf16 v[84:87], v[160:163], v[212:215], v[84:87]
	v_mfma_f32_16x16x32_bf16 v[72:75], v[152:155], v[220:223], v[72:75]
	v_mfma_f32_16x16x32_bf16 v[68:71], v[160:163], v[220:223], v[68:71]
	s_barrier
	s_add_i32 m0, s41, 0x17f80
	ds_read_b128 v[164:167], v205 offset:49152
	ds_read_b128 v[182:185], v205 offset:50176
	ds_read_b128 v[186:189], v205 offset:51200
	ds_read_b128 v[190:193], v205 offset:52224
	ds_read_b128 v[208:211], v205 offset:53248
	ds_read_b128 v[212:215], v205 offset:54272
	ds_read_b128 v[216:219], v205 offset:55296
	ds_read_b128 v[220:223], v205 offset:56320
	global_load_lds_dwordx4 v[194:195], off offset:128
	s_add_i32 m0, s41, 0x19f80
	s_add_u32 s28, s28, 0x40080
	s_addc_u32 s29, s29, 0
	global_load_lds_dwordx4 v[202:203], off offset:128
	s_add_i32 m0, s41, 0x1c000
	v_lshl_add_u64 v[194:195], s[28:29], 0, v[168:169]
	global_load_lds_dwordx4 v[194:195], off
	s_add_i32 m0, s41, 0x1e000
	v_lshl_add_u64 v[194:195], s[28:29], 0, v[172:173]
	global_load_lds_dwordx4 v[194:195], off
	s_add_i32 m0, s50, 0xffffff80
	s_add_u32 s8, s8, 0x100
	s_addc_u32 s9, s9, 0
	global_load_lds_dwordx4 v[224:225], off offset:128
	s_add_i32 m0, s51, 0xffffff80
	s_add_u32 s23, s23, 0x100
	s_addc_u32 s44, s44, 0
	global_load_lds_dwordx4 v[226:227], off offset:128
	s_waitcnt vmcnt(8) lgkmcnt(0)
	s_barrier
	v_mfma_f32_16x16x32_bf16 v[64:67], v[132:135], v[164:167], v[64:67]
	v_mfma_f32_16x16x32_bf16 v[60:63], v[140:143], v[164:167], v[60:63]
	v_mfma_f32_16x16x32_bf16 v[48:51], v[132:135], v[186:189], v[48:51]
	v_mfma_f32_16x16x32_bf16 v[44:47], v[140:143], v[186:189], v[44:47]
	v_mfma_f32_16x16x32_bf16 v[32:35], v[132:135], v[208:211], v[32:35]
	v_mfma_f32_16x16x32_bf16 v[28:31], v[140:143], v[208:211], v[28:31]
	v_mfma_f32_16x16x32_bf16 v[16:19], v[132:135], v[216:219], v[16:19]
	v_mfma_f32_16x16x32_bf16 v[12:15], v[140:143], v[216:219], v[12:15]
	v_mfma_f32_16x16x32_bf16 v[64:67], v[136:139], v[182:185], v[64:67]
	v_mfma_f32_16x16x32_bf16 v[60:63], v[144:147], v[182:185], v[60:63]
	v_mfma_f32_16x16x32_bf16 v[48:51], v[136:139], v[190:193], v[48:51]
	v_mfma_f32_16x16x32_bf16 v[44:47], v[144:147], v[190:193], v[44:47]
	v_mfma_f32_16x16x32_bf16 v[32:35], v[136:139], v[212:215], v[32:35]
	v_mfma_f32_16x16x32_bf16 v[28:31], v[144:147], v[212:215], v[28:31]
	v_mfma_f32_16x16x32_bf16 v[16:19], v[136:139], v[220:223], v[16:19]
	v_mfma_f32_16x16x32_bf16 v[12:15], v[144:147], v[220:223], v[12:15]
	v_mfma_f32_16x16x32_bf16 v[56:59], v[148:151], v[164:167], v[56:59]
	v_mfma_f32_16x16x32_bf16 v[52:55], v[156:159], v[164:167], v[52:55]
	v_mfma_f32_16x16x32_bf16 v[40:43], v[148:151], v[186:189], v[40:43]
	v_mfma_f32_16x16x32_bf16 v[36:39], v[156:159], v[186:189], v[36:39]
	v_mfma_f32_16x16x32_bf16 v[24:27], v[148:151], v[208:211], v[24:27]
	v_mfma_f32_16x16x32_bf16 v[20:23], v[156:159], v[208:211], v[20:23]
	v_mfma_f32_16x16x32_bf16 v[8:11], v[148:151], v[216:219], v[8:11]
	v_mfma_f32_16x16x32_bf16 v[4:7], v[156:159], v[216:219], v[4:7]
	v_mfma_f32_16x16x32_bf16 v[56:59], v[152:155], v[182:185], v[56:59]
	v_mfma_f32_16x16x32_bf16 v[52:55], v[160:163], v[182:185], v[52:55]
	v_mfma_f32_16x16x32_bf16 v[40:43], v[152:155], v[190:193], v[40:43]
	v_mfma_f32_16x16x32_bf16 v[36:39], v[160:163], v[190:193], v[36:39]
	v_mfma_f32_16x16x32_bf16 v[24:27], v[152:155], v[212:215], v[24:27]
	v_mfma_f32_16x16x32_bf16 v[20:23], v[160:163], v[212:215], v[20:23]
	v_mfma_f32_16x16x32_bf16 v[8:11], v[152:155], v[220:223], v[8:11]
	v_mfma_f32_16x16x32_bf16 v[4:7], v[160:163], v[220:223], v[4:7]
	s_barrier
	s_add_i32 s45, s45, 2
	s_cmp_gt_u32 s45, 13
	s_cbranch_scc0 .LBB0_100
	s_and_b64 vcc, exec, s[14:15]
	s_cbranch_vccz .LBB0_103
	s_barrier

; #define PG8_WAIT_V(n) asm volatile("s_waitcnt vmcnt(" #n ")" ::: "memory")
; #define PG8_BAR __builtin_amdgcn_s_barrier()
; template <class Epi, class Sched, bool ALIGN_EPI = false, bool SP2 = false>
; __device__ __forceinline__ void gemm_phase(PG8_LAS unsigned char* lds, const Gemm g, const Sched& S, const Epi& E) {
;     ...
;     PG8_WAIT_V(0);
;     if constexpr (!ALIGN_EPI) { if (wr == 0) PG8_BAR; }
;     PG8_BAR;
; __device__ __forceinline__ void xcd_barrier(const XcdBarrier& b) {
;     asm volatile("s_waitcnt vmcnt(0)" ::: "memory");
;     __syncthreads();
;     if (threadIdx.x == 0) {
;         unsigned* bar = b.bar; unsigned bx_ = b.x;
;         asm volatile("" : "+s"(bar), "+s"(bx_));
;         __builtin_amdgcn_s_waitcnt(0);
;         unsigned nloc = b.st[0], nx = b.st[1];
;         if (nloc == 0u) { xcd_barrier_complete(bar, bx_, nloc, nx); b.st[0] = nloc; b.st[1] = nx; }
.LBB0_131:
	s_setprio 0
	s_waitcnt vmcnt(0)
	s_waitcnt lgkmcnt(0)
	s_barrier
	s_and_saveexec_b64 s[38:39], s[62:63]
	s_cbranch_execz .LBB0_175
	s_mov_b64 s[40:41], s[58:59]
	s_mov_b32 s3, s99
	v_mov_b32_e32 v0, s70
	s_waitcnt vmcnt(0) expcnt(0) lgkmcnt(0)
	ds_read_b32 v4, v0
	v_mov_b32_e32 v0, s71
	ds_read_b32 v0, v0
	s_waitcnt lgkmcnt(1)
	v_cmp_ne_u32_e32 vcc, 0, v4
	s_cbranch_vccnz .LBB0_146
	s_add_u32 s4, s40, 0x1000
	s_addc_u32 s5, s41, 0
	s_add_u32 s6, s40, 0x1100
	s_addc_u32 s7, s41, 0
	s_add_u32 s8, s40, 0x1200
	s_addc_u32 s9, s41, 0
	s_add_u32 s10, s40, 0x1300
	s_addc_u32 s11, s41, 0
	s_mov_b32 s30, 1
	s_mov_b64 s[12:13], 0
	s_branch .LBB0_136

; __device__ __forceinline__ int opaque_tid() { int t = (int)threadIdx.x; asm volatile("" : "+v"(t)); return t; }
; #define PG8_STAGE(bufoff, gbase, voff) do { _Pragma("unroll") for (int _i = 0; _i < 2; ++_i) \
;         __builtin_amdgcn_global_load_lds((const unsigned*)((const char*)(gbase) + (voff)[_i]), (PG8_LAS unsigned*)(lds + (bufoff) + ldsw + _i * 8192), 16, 0, 0); } while (0)
; template <class Epi, class Sched, bool ALIGN_EPI = false, bool SP2 = false>
; __device__ __forceinline__ void gemm_phase(PG8_LAS unsigned char* lds, const Gemm g, const Sched& S, const Epi& E) {
;     const int tid = opaque_tid(), wid = __builtin_amdgcn_readfirstlane(tid >> 6), lane = tid & 63, wr = wid >> 2, wc = wid & 3, fr = lane & 15, fq = lane >> 4;
;     const int K = g.K, nt = K / BK;
;     unsigned voffA[2], voffB[2];
; #pragma unroll
;     for (int i = 0; i < 2; ++i) { int R, C; stage_rc(tid * 16 + i * 8192, R, C); const int Rb = Epi::PERM ? ((R & ~31) + perm32(R & 31)) : R;
;         voffA[i] = (unsigned)(R * K + C) * 2u; voffB[i] = (unsigned)(Rb * K + C) * 2u; }
;     const size_t kstep = (size_t)(BK * 2);
;     const size_t hstep = (size_t)HALF * K * 2;
;     const size_t tstep = 2 * hstep;
;     const unsigned ldsw = (unsigned)wid * 1024u;
;     const int aoff = lds_byte(wr * 64 + fr, fq * 8), boff = lds_byte(wc * 32 + fr, fq * 8);
;     ...
;     const char* cA = (const char*)g.A + (size_t)cur.pm * tstep; const char* cB = (const char*)g.Bt + (size_t)cur.pn * tstep;
;     S.a_ready(cur);
;     if constexpr (SP2) {
;         PG8_STAGE(PG8_SB(0, 0), cB, voffB); PG8_STAGE(PG8_SB(0, 1), cB + hstep, voffB); PG8_STAGE(PG8_SA(0, 0), cA, voffA); PG8_STAGE(PG8_SA(0, 1), cA + hstep, voffA);
;         if (wr == 1) PG8_BAR;
;         PG8_WAIT_V(2); PG8_BAR;
;         PG8_STAGE(PG8_SB(1, 0), cB + kstep, voffB); PG8_STAGE(PG8_SA(1, 0), cA + kstep, voffA); PG8_STAGE(PG8_SB(1, 1), cB + hstep + kstep, voffB);
;         PG8_WAIT_V(6); PG8_BAR;
;     } else {
;         PG8_STAGE(PG8_SB(0, 0), cB, voffB); PG8_STAGE(PG8_SA(0, 0), cA, voffA); PG8_STAGE(PG8_SB(0, 1), cB + hstep, voffB); PG8_STAGE(PG8_SA(0, 1), cA + hstep, voffA);
;         if (wr == 1) PG8_BAR;
;         PG8_WAIT_V(4); PG8_BAR;
;         PG8_STAGE(PG8_SB(1, 0), cB + kstep, voffB); PG8_STAGE(PG8_SA(1, 0), cA + kstep, voffA); PG8_STAGE(PG8_SB(1, 1), cB + hstep + kstep, voffB);
;         PG8_WAIT_V(6); PG8_BAR;
;     }
.LBB0_319:
	s_add_u32 s10, s4, 0x6400000
	s_addc_u32 s11, s5, 0
	s_add_u32 s12, s4, 0x1a600000
	s_addc_u32 s13, s5, 0
	s_and_b32 s48, s6, 3
	s_add_i32 m0, s42, 0x18000
	v_lshl_add_u64 v[10:11], v[10:11], 0, s[82:83]
	s_lshl_b32 s6, s7, 13
	s_lshl_b32 s14, s48, 12
	s_waitcnt vmcnt(2)
	s_barrier
	global_load_lds_dwordx4 v[10:11], off
	v_lshl_add_u64 v[8:9], v[8:9], 0, s[82:83]
	s_add_i32 m0, s42, 0x1a000
	s_add_i32 s49, s42, 0x8000
	s_add_i32 s50, s42, 0xa000
	global_load_lds_dwordx4 v[8:9], off
	v_lshl_add_u64 v[4:5], v[4:5], 0, s[82:83]
	s_mov_b32 m0, s49
	s_add_u32 s4, s30, 0x40080
	global_load_lds_dwordx4 v[4:5], off
	v_lshl_add_u64 v[4:5], v[6:7], 0, s[82:83]
	s_mov_b32 m0, s50
	s_addc_u32 s5, s31, 0
	global_load_lds_dwordx4 v[4:5], off
	s_add_i32 m0, s42, 0x1c000
	v_lshl_add_u64 v[4:5], s[4:5], 0, v[202:203]
	global_load_lds_dwordx4 v[4:5], off
	v_lshl_add_u64 v[4:5], s[4:5], 0, v[206:207]
	s_add_i32 m0, s42, 0x1e000
	s_cmpk_lt_u32 s3, 0x100
	global_load_lds_dwordx4 v[4:5], off
	v_bfe_u32 v4, v12, 4, 2
	v_and_b32_e32 v5, 15, v12
	v_lshlrev_b32_e32 v7, 4, v4
	v_lshl_or_b32 v3, s7, 6, v5
	v_lshlrev_b32_e32 v6, 3, v4
	v_lshl_or_b32 v5, v5, 6, v7
	v_lshlrev_b32_e32 v7, 2, v12
	v_cmp_eq_u32_e64 s[4:5], 0, v4
	v_lshlrev_b32_e32 v4, 14, v13
	v_and_b32_e32 v7, 32, v7
	v_and_b32_e32 v4, 0xffff8000, v4
	v_bitop3_b32 v8, v5, s6, v7 bitop3:0xde
	v_bitop3_b32 v251, v5, s14, v7 bitop3:0xde
	v_add_u32_e32 v251, 0x10000, v251
	v_lshl_add_u32 v4, v14, 11, v4
	v_and_b32_e32 v5, 1, v13
	v_lshl_or_b32 v4, v5, 6, v4
	v_lshl_add_u32 v208, v15, 1, v4
	v_lshlrev_b32_e32 v4, 14, v16
	v_and_b32_e32 v4, 0xffff8000, v4
	s_waitcnt vmcnt(6)
	v_lshl_add_u32 v4, v17, 11, v4
	v_and_b32_e32 v5, 1, v16
	v_lshl_or_b32 v4, v5, 6, v4
	v_lshl_or_b32 v252, s48, 5, v6
	s_cselect_b64 s[14:15], -1, 0
	s_mov_b32 s72, 0
	s_ashr_i32 s51, s36, 31
	v_mov_b32_e32 v209, v2
	v_lshl_add_u32 v210, v18, 1, v4
	v_mov_b32_e32 v211, v2
	v_add_u32_e32 v253, 0, v8
	s_waitcnt vmcnt(0)
	s_barrier
	v_readfirstlane_b32 s100, v197
	s_cmp_lt_u32 s100, 0x100
	s_cbranch_scc1 .Lsp_1
	s_setprio 1
.Lsp_1:
	s_branch .LBB0_322
.LBB0_320:
	s_mov_b64 s[6:7], 0

; #define PG8_STAGE(bufoff, gbase, voff) do { _Pragma("unroll") for (int _i = 0; _i < 2; ++_i) \
;         __builtin_amdgcn_global_load_lds((const unsigned*)((const char*)(gbase) + (voff)[_i]), (PG8_LAS unsigned*)(lds + (bufoff) + ldsw + _i * 8192), 16, 0, 0); } while (0)
; #define PG8_LDA(dst, b, h) do { _Pragma("unroll") for (int m = 0; m < 4; ++m) _Pragma("unroll") for (int k = 0; k < 2; ++k) dst[m][k] = *(const PG8_LAS bf16x8*)(lds + PG8_SA(b, h) + aoff + m * 2048 + k * 1024); } while (0)
; #define PG8_LDB(dst, b, h) do { _Pragma("unroll") for (int n = 0; n < 2; ++n) _Pragma("unroll") for (int k = 0; k < 2; ++k) dst[n][k] = *(const PG8_LAS bf16x8*)(lds + PG8_SB(b, h) + boff + n * 2048 + k * 1024); } while (0)
; #define PG8_WAIT_V(n) asm volatile("s_waitcnt vmcnt(" #n ")" ::: "memory")
; #define PG8_WAIT_L(n) asm volatile("s_waitcnt lgkmcnt(" #n ")" ::: "memory")
; #define PG8_BAR __builtin_amdgcn_s_barrier()
; #define PG8_SCHED __builtin_amdgcn_sched_barrier(0)
; template <class Epi, class Sched, bool ALIGN_EPI = false, bool SP2 = false>
; __device__ __forceinline__ void gemm_phase(PG8_LAS unsigned char* lds, const Gemm g, const Sched& S, const Epi& E) {
;     ...
;         const bool has_next = S.next(ui + 1, nxt);
;         const char* nA = has_next ? (const char*)g.A + (size_t)nxt.pm * tstep : cA; const char* nB = has_next ? (const char*)g.Bt + (size_t)nxt.pn * tstep : cB;
;         for (int t = 0; t < nt; t += 2) {
;             const bool last = (t == nt - 2);
;             const char* a1 = cA + (size_t)(t + 1) * kstep;
;             const char* a2 = last ? nA : cA + (size_t)(t + 2) * kstep; const char* b2 = last ? nB : cB + (size_t)(t + 2) * kstep;
;             const char* a3 = a2 + kstep; const char* b3 = b2 + kstep;
;             if (last && has_next) S.a_ready(nxt);
;             if constexpr (SP2) {
;             PG8_LDB(B0, 0, 0); PG8_LDB(B1, 0, 1); PG8_SCHED; PG8_LDA(At, 0, 0); PG8_STAGE(PG8_SA(1, 1), a1 + hstep, voffA);
;             PG8_WAIT_V(8); PG8_WAIT_L(0); PG8_BAR; PG8_MMA(0, 0, At, B0); PG8_MMA(0, 1, At, B1); PG8_BAR; PG8_SCHED;
;             PG8_LDA(At, 0, 1); PG8_STAGE(PG8_SB(0, 0), b2, voffB); PG8_STAGE(PG8_SB(0, 1), b2 + hstep, voffB); PG8_STAGE(PG8_SA(0, 0), a2, voffA);
;             PG8_WAIT_V(8); PG8_WAIT_L(0); PG8_BAR; PG8_MMA(1, 0, At, B0); PG8_MMA(1, 1, At, B1); PG8_BAR; PG8_SCHED;
.LBB0_328:
	s_ashr_i32 s17, s16, 31
	s_lshl_b64 s[20:21], s[16:17], 19
	s_add_u32 s20, s37, s20
	s_addc_u32 s21, s38, s21
	s_and_b64 s[22:23], s[6:7], exec
	s_cselect_b32 s3, s21, s29
	s_cselect_b32 s17, s20, s28
	s_ashr_i32 s19, s18, 31
	s_lshl_b64 s[22:23], s[18:19], 19
	s_add_u32 s22, s39, s22
	s_addc_u32 s23, s40, s23
	s_and_b64 s[34:35], s[6:7], exec
	s_cselect_b32 s19, s23, s31
	s_cselect_b32 s25, s22, s30
	s_add_u32 s28, s28, 0x40080
	s_addc_u32 s29, s29, 0
	s_add_u32 s27, s30, 0x100
	s_addc_u32 s44, s31, 0
	s_mov_b32 s45, -2
	s_add_u32 s30, s28, 0xfffc0080
	s_addc_u32 s31, s29, -1
	s_cmp_eq_u32 s45, 12
	s_cselect_b32 s35, s3, s31
	s_cselect_b32 s34, s17, s30
	s_cselect_b32 s31, s19, s44
	s_cselect_b32 s30, s25, s27
	ds_read_b128 v[108:111], v251
	ds_read_b128 v[112:115], v251 offset:1024
	ds_read_b128 v[124:127], v251 offset:2048
	ds_read_b128 v[128:131], v251 offset:3072
	ds_read_b128 v[132:135], v251 offset:16384
	ds_read_b128 v[140:143], v251 offset:17408
	ds_read_b128 v[148:151], v251 offset:18432
	ds_read_b128 v[156:159], v251 offset:19456
	v_lshl_add_u64 v[212:213], s[28:29], 0, v[208:209]
	s_add_i32 m0, s42, 0xc000
	ds_read_b128 v[164:167], v253
	ds_read_b128 v[168:171], v253 offset:1024
	ds_read_b128 v[172:175], v253 offset:2048
	ds_read_b128 v[176:179], v253 offset:3072
	ds_read_b128 v[180:183], v253 offset:4096
	ds_read_b128 v[184:187], v253 offset:5120
	ds_read_b128 v[188:191], v253 offset:6144
	ds_read_b128 v[192:195], v253 offset:7168
	global_load_lds_dwordx4 v[212:213], off
	s_add_i32 m0, s42, 0xe000
	v_lshl_add_u64 v[212:213], s[28:29], 0, v[210:211]
	global_load_lds_dwordx4 v[212:213], off
	s_waitcnt vmcnt(8) lgkmcnt(0)
	s_barrier
	v_mfma_f32_16x16x32_bf16 v[160:163], v[108:111], v[164:167], 0
	v_mfma_f32_16x16x32_bf16 v[152:155], v[124:127], v[164:167], 0
	v_mfma_f32_16x16x32_bf16 v[120:123], v[108:111], v[172:175], 0
	v_mfma_f32_16x16x32_bf16 v[116:119], v[124:127], v[172:175], 0
	v_mfma_f32_16x16x32_bf16 v[96:99], v[108:111], v[180:183], 0
	v_mfma_f32_16x16x32_bf16 v[92:95], v[124:127], v[180:183], 0
	v_mfma_f32_16x16x32_bf16 v[80:83], v[108:111], v[188:191], 0
	v_mfma_f32_16x16x32_bf16 v[76:79], v[124:127], v[188:191], 0
	v_mfma_f32_16x16x32_bf16 v[160:163], v[112:115], v[168:171], v[160:163]
	v_mfma_f32_16x16x32_bf16 v[152:155], v[128:131], v[168:171], v[152:155]
	v_mfma_f32_16x16x32_bf16 v[120:123], v[112:115], v[176:179], v[120:123]
	v_mfma_f32_16x16x32_bf16 v[116:119], v[128:131], v[176:179], v[116:119]
	v_mfma_f32_16x16x32_bf16 v[96:99], v[112:115], v[184:187], v[96:99]
	v_mfma_f32_16x16x32_bf16 v[92:95], v[128:131], v[184:187], v[92:95]
	v_mfma_f32_16x16x32_bf16 v[80:83], v[112:115], v[192:195], v[80:83]
	v_mfma_f32_16x16x32_bf16 v[76:79], v[128:131], v[192:195], v[76:79]
	v_mfma_f32_16x16x32_bf16 v[144:147], v[132:135], v[164:167], 0
	v_mfma_f32_16x16x32_bf16 v[136:139], v[148:151], v[164:167], 0
	v_mfma_f32_16x16x32_bf16 v[104:107], v[132:135], v[172:175], 0
	v_mfma_f32_16x16x32_bf16 v[100:103], v[148:151], v[172:175], 0
	v_mfma_f32_16x16x32_bf16 v[88:91], v[132:135], v[180:183], 0
	v_mfma_f32_16x16x32_bf16 v[84:87], v[148:151], v[180:183], 0
	v_mfma_f32_16x16x32_bf16 v[72:75], v[132:135], v[188:191], 0
	v_mfma_f32_16x16x32_bf16 v[68:71], v[148:151], v[188:191], 0
	v_mfma_f32_16x16x32_bf16 v[144:147], v[140:143], v[168:171], v[144:147]
	v_mfma_f32_16x16x32_bf16 v[136:139], v[156:159], v[168:171], v[136:139]
	v_mfma_f32_16x16x32_bf16 v[104:107], v[140:143], v[176:179], v[104:107]
	v_mfma_f32_16x16x32_bf16 v[100:103], v[156:159], v[176:179], v[100:103]
	v_mfma_f32_16x16x32_bf16 v[88:91], v[140:143], v[184:187], v[88:91]
	v_mfma_f32_16x16x32_bf16 v[84:87], v[156:159], v[184:187], v[84:87]
	v_mfma_f32_16x16x32_bf16 v[72:75], v[140:143], v[192:195], v[72:75]
	v_mfma_f32_16x16x32_bf16 v[68:71], v[156:159], v[192:195], v[68:71]
	s_barrier
	v_lshl_add_u64 v[212:213], s[30:31], 0, v[202:203]
	s_add_i32 m0, s41, 0x10000
	ds_read_b128 v[164:167], v253 offset:16384
	ds_read_b128 v[168:171], v253 offset:17408
	ds_read_b128 v[172:175], v253 offset:18432
	ds_read_b128 v[176:179], v253 offset:19456
	ds_read_b128 v[180:183], v253 offset:20480
	ds_read_b128 v[184:187], v253 offset:21504
	ds_read_b128 v[188:191], v253 offset:22528
	ds_read_b128 v[192:195], v253 offset:23552
	global_load_lds_dwordx4 v[212:213], off
	s_add_i32 m0, s41, 0x12000
	s_add_u32 s52, s30, 0x40000
	v_lshl_add_u64 v[214:215], s[30:31], 0, v[206:207]
	s_addc_u32 s53, s31, 0
	global_load_lds_dwordx4 v[214:215], off
	v_lshl_add_u64 v[216:217], s[52:53], 0, v[202:203]
	s_add_i32 m0, s41, 0x14000
	v_lshl_add_u64 v[218:219], s[34:35], 0, v[204:205]
	global_load_lds_dwordx4 v[216:217], off
	s_add_i32 m0, s41, 0x16000
	v_lshl_add_u64 v[216:217], s[52:53], 0, v[206:207]
	global_load_lds_dwordx4 v[216:217], off
	s_mov_b32 m0, s42
	v_lshl_add_u64 v[216:217], s[34:35], 0, v[0:1]
	global_load_lds_dwordx4 v[216:217], off
	s_mov_b32 m0, s43
	s_add_i32 s52, 0, 0x18000
	global_load_lds_dwordx4 v[218:219], off
	s_waitcnt vmcnt(8) lgkmcnt(0)
	s_barrier
; #define PG8_STAGE(bufoff, gbase, voff) do { _Pragma("unroll") for (int _i = 0; _i < 2; ++_i) \
;         __builtin_amdgcn_global_load_lds((const unsigned*)((const char*)(gbase) + (voff)[_i]), (PG8_LAS unsigned*)(lds + (bufoff) + ldsw + _i * 8192), 16, 0, 0); } while (0)
; #define PG8_LDA(dst, b, h) do { _Pragma("unroll") for (int m = 0; m < 4; ++m) _Pragma("unroll") for (int k = 0; k < 2; ++k) dst[m][k] = *(const PG8_LAS bf16x8*)(lds + PG8_SA(b, h) + aoff + m * 2048 + k * 1024); } while (0)
; #define PG8_LDB(dst, b, h) do { _Pragma("unroll") for (int n = 0; n < 2; ++n) _Pragma("unroll") for (int k = 0; k < 2; ++k) dst[n][k] = *(const PG8_LAS bf16x8*)(lds + PG8_SB(b, h) + boff + n * 2048 + k * 1024); } while (0)
; #define PG8_MMA(ai, bj, At, Bt) do { __builtin_amdgcn_s_setprio(1); _Pragma("unroll") for (int m = 0; m < 4; ++m) _Pragma("unroll") for (int n = 0; n < 2; ++n) _Pragma("unroll") for (int k = 0; k < 2; ++k) \
;         acc[ai][bj][m][n] = __builtin_amdgcn_mfma_f32_16x16x32_bf16(Bt[n][k], At[m][k], acc[ai][bj][m][n], 0, 0, 0); __builtin_amdgcn_s_setprio(0); } while (0)
; #define PG8_WAIT_V(n) asm volatile("s_waitcnt vmcnt(" #n ")" ::: "memory")
; #define PG8_WAIT_L(n) asm volatile("s_waitcnt lgkmcnt(" #n ")" ::: "memory")
; #define PG8_BAR __builtin_amdgcn_s_barrier()
; #define PG8_SCHED __builtin_amdgcn_sched_barrier(0)
; template <class Epi, class Sched, bool ALIGN_EPI = false, bool SP2 = false>
; __device__ __forceinline__ void gemm_phase(PG8_LAS unsigned char* lds, const Gemm g, const Sched& S, const Epi& E) {
;     ...
;             PG8_LDB(B0, 0, 0); PG8_LDB(B1, 0, 1); PG8_SCHED; PG8_LDA(At, 0, 0); PG8_STAGE(PG8_SA(1, 1), a1 + hstep, voffA);
;             PG8_WAIT_V(8); PG8_WAIT_L(0); PG8_BAR; PG8_MMA(0, 0, At, B0); PG8_MMA(0, 1, At, B1); PG8_BAR; PG8_SCHED;
;             PG8_LDA(At, 0, 1); PG8_STAGE(PG8_SB(0, 0), b2, voffB); PG8_STAGE(PG8_SB(0, 1), b2 + hstep, voffB); PG8_STAGE(PG8_SA(0, 0), a2, voffA);
;             PG8_WAIT_V(8); PG8_WAIT_L(0); PG8_BAR; PG8_MMA(1, 0, At, B0); PG8_MMA(1, 1, At, B1); PG8_BAR; PG8_SCHED;
	v_mfma_f32_16x16x32_bf16 v[64:67], v[108:111], v[164:167], 0
	v_mfma_f32_16x16x32_bf16 v[60:63], v[124:127], v[164:167], 0
	v_mfma_f32_16x16x32_bf16 v[48:51], v[108:111], v[172:175], 0
	v_mfma_f32_16x16x32_bf16 v[44:47], v[124:127], v[172:175], 0
	v_mfma_f32_16x16x32_bf16 v[32:35], v[108:111], v[180:183], 0
	v_mfma_f32_16x16x32_bf16 v[28:31], v[124:127], v[180:183], 0
	v_mfma_f32_16x16x32_bf16 v[16:19], v[108:111], v[188:191], 0
	v_mfma_f32_16x16x32_bf16 v[12:15], v[124:127], v[188:191], 0
	v_mfma_f32_16x16x32_bf16 v[64:67], v[112:115], v[168:171], v[64:67]
	v_mfma_f32_16x16x32_bf16 v[60:63], v[128:131], v[168:171], v[60:63]
	v_mfma_f32_16x16x32_bf16 v[48:51], v[112:115], v[176:179], v[48:51]
	v_mfma_f32_16x16x32_bf16 v[44:47], v[128:131], v[176:179], v[44:47]
	v_mfma_f32_16x16x32_bf16 v[32:35], v[112:115], v[184:187], v[32:35]
	v_mfma_f32_16x16x32_bf16 v[28:31], v[128:131], v[184:187], v[28:31]
	v_mfma_f32_16x16x32_bf16 v[16:19], v[112:115], v[192:195], v[16:19]
	v_mfma_f32_16x16x32_bf16 v[12:15], v[128:131], v[192:195], v[12:15]
	v_mfma_f32_16x16x32_bf16 v[56:59], v[132:135], v[164:167], 0
	v_mfma_f32_16x16x32_bf16 v[52:55], v[148:151], v[164:167], 0
	v_mfma_f32_16x16x32_bf16 v[40:43], v[132:135], v[172:175], 0
	v_mfma_f32_16x16x32_bf16 v[36:39], v[148:151], v[172:175], 0
	v_mfma_f32_16x16x32_bf16 v[24:27], v[132:135], v[180:183], 0
	v_mfma_f32_16x16x32_bf16 v[20:23], v[148:151], v[180:183], 0
	v_mfma_f32_16x16x32_bf16 v[8:11], v[132:135], v[188:191], 0
	v_mfma_f32_16x16x32_bf16 v[4:7], v[148:151], v[188:191], 0
	v_mfma_f32_16x16x32_bf16 v[56:59], v[140:143], v[168:171], v[56:59]
	v_mfma_f32_16x16x32_bf16 v[52:55], v[156:159], v[168:171], v[52:55]
	v_mfma_f32_16x16x32_bf16 v[40:43], v[140:143], v[176:179], v[40:43]
	v_mfma_f32_16x16x32_bf16 v[36:39], v[156:159], v[176:179], v[36:39]
	v_mfma_f32_16x16x32_bf16 v[24:27], v[140:143], v[184:187], v[24:27]
	v_mfma_f32_16x16x32_bf16 v[20:23], v[156:159], v[184:187], v[20:23]
	v_mfma_f32_16x16x32_bf16 v[8:11], v[140:143], v[192:195], v[8:11]
	v_mfma_f32_16x16x32_bf16 v[4:7], v[156:159], v[192:195], v[4:7]
	s_barrier
	s_branch .Lkmid_1
.LBB0_329:
	s_add_u32 s30, s28, 0xfffc0080
	s_addc_u32 s31, s29, -1
	s_cmp_eq_u32 s45, 12
	s_cselect_b32 s35, s3, s31
	s_cselect_b32 s34, s17, s30
	s_cselect_b32 s31, s19, s44
	s_cselect_b32 s30, s25, s27
	ds_read_b128 v[108:111], v251
	ds_read_b128 v[112:115], v251 offset:1024
	ds_read_b128 v[124:127], v251 offset:2048
	ds_read_b128 v[128:131], v251 offset:3072
	ds_read_b128 v[132:135], v251 offset:16384
	ds_read_b128 v[140:143], v251 offset:17408
	ds_read_b128 v[148:151], v251 offset:18432
	ds_read_b128 v[156:159], v251 offset:19456
	v_lshl_add_u64 v[212:213], s[28:29], 0, v[208:209]
	s_add_i32 m0, s42, 0xc000
	ds_read_b128 v[164:167], v253
	ds_read_b128 v[168:171], v253 offset:1024
	ds_read_b128 v[172:175], v253 offset:2048
	ds_read_b128 v[176:179], v253 offset:3072
	ds_read_b128 v[180:183], v253 offset:4096
	ds_read_b128 v[184:187], v253 offset:5120
	ds_read_b128 v[188:191], v253 offset:6144
	ds_read_b128 v[192:195], v253 offset:7168
	global_load_lds_dwordx4 v[212:213], off
	s_add_i32 m0, s42, 0xe000
	v_lshl_add_u64 v[212:213], s[28:29], 0, v[210:211]
	global_load_lds_dwordx4 v[212:213], off
	s_waitcnt vmcnt(8) lgkmcnt(0)
	s_barrier
	v_mfma_f32_16x16x32_bf16 v[160:163], v[108:111], v[164:167], v[160:163]
	v_mfma_f32_16x16x32_bf16 v[152:155], v[124:127], v[164:167], v[152:155]
	v_mfma_f32_16x16x32_bf16 v[120:123], v[108:111], v[172:175], v[120:123]
	v_mfma_f32_16x16x32_bf16 v[116:119], v[124:127], v[172:175], v[116:119]
	v_mfma_f32_16x16x32_bf16 v[96:99], v[108:111], v[180:183], v[96:99]
	v_mfma_f32_16x16x32_bf16 v[92:95], v[124:127], v[180:183], v[92:95]
	v_mfma_f32_16x16x32_bf16 v[80:83], v[108:111], v[188:191], v[80:83]
	v_mfma_f32_16x16x32_bf16 v[76:79], v[124:127], v[188:191], v[76:79]
	v_mfma_f32_16x16x32_bf16 v[160:163], v[112:115], v[168:171], v[160:163]
	v_mfma_f32_16x16x32_bf16 v[152:155], v[128:131], v[168:171], v[152:155]
	v_mfma_f32_16x16x32_bf16 v[120:123], v[112:115], v[176:179], v[120:123]
	v_mfma_f32_16x16x32_bf16 v[116:119], v[128:131], v[176:179], v[116:119]
	v_mfma_f32_16x16x32_bf16 v[96:99], v[112:115], v[184:187], v[96:99]
	v_mfma_f32_16x16x32_bf16 v[92:95], v[128:131], v[184:187], v[92:95]
	v_mfma_f32_16x16x32_bf16 v[80:83], v[112:115], v[192:195], v[80:83]
	v_mfma_f32_16x16x32_bf16 v[76:79], v[128:131], v[192:195], v[76:79]
	v_mfma_f32_16x16x32_bf16 v[144:147], v[132:135], v[164:167], v[144:147]
	v_mfma_f32_16x16x32_bf16 v[136:139], v[148:151], v[164:167], v[136:139]
	v_mfma_f32_16x16x32_bf16 v[104:107], v[132:135], v[172:175], v[104:107]
	v_mfma_f32_16x16x32_bf16 v[100:103], v[148:151], v[172:175], v[100:103]
	v_mfma_f32_16x16x32_bf16 v[88:91], v[132:135], v[180:183], v[88:91]
	v_mfma_f32_16x16x32_bf16 v[84:87], v[148:151], v[180:183], v[84:87]
	v_mfma_f32_16x16x32_bf16 v[72:75], v[132:135], v[188:191], v[72:75]
	v_mfma_f32_16x16x32_bf16 v[68:71], v[148:151], v[188:191], v[68:71]
	v_mfma_f32_16x16x32_bf16 v[144:147], v[140:143], v[168:171], v[144:147]
	v_mfma_f32_16x16x32_bf16 v[136:139], v[156:159], v[168:171], v[136:139]
	v_mfma_f32_16x16x32_bf16 v[104:107], v[140:143], v[176:179], v[104:107]
	v_mfma_f32_16x16x32_bf16 v[100:103], v[156:159], v[176:179], v[100:103]
	v_mfma_f32_16x16x32_bf16 v[88:91], v[140:143], v[184:187], v[88:91]
	v_mfma_f32_16x16x32_bf16 v[84:87], v[156:159], v[184:187], v[84:87]
	v_mfma_f32_16x16x32_bf16 v[72:75], v[140:143], v[192:195], v[72:75]
	v_mfma_f32_16x16x32_bf16 v[68:71], v[156:159], v[192:195], v[68:71]
	s_barrier
; #define PG8_STAGE(bufoff, gbase, voff) do { _Pragma("unroll") for (int _i = 0; _i < 2; ++_i) \
;         __builtin_amdgcn_global_load_lds((const unsigned*)((const char*)(gbase) + (voff)[_i]), (PG8_LAS unsigned*)(lds + (bufoff) + ldsw + _i * 8192), 16, 0, 0); } while (0)
; #define PG8_LDA(dst, b, h) do { _Pragma("unroll") for (int m = 0; m < 4; ++m) _Pragma("unroll") for (int k = 0; k < 2; ++k) dst[m][k] = *(const PG8_LAS bf16x8*)(lds + PG8_SA(b, h) + aoff + m * 2048 + k * 1024); } while (0)
; #define PG8_MMA(ai, bj, At, Bt) do { __builtin_amdgcn_s_setprio(1); _Pragma("unroll") for (int m = 0; m < 4; ++m) _Pragma("unroll") for (int n = 0; n < 2; ++n) _Pragma("unroll") for (int k = 0; k < 2; ++k) \
;         acc[ai][bj][m][n] = __builtin_amdgcn_mfma_f32_16x16x32_bf16(Bt[n][k], At[m][k], acc[ai][bj][m][n], 0, 0, 0); __builtin_amdgcn_s_setprio(0); } while (0)
; #define PG8_WAIT_V(n) asm volatile("s_waitcnt vmcnt(" #n ")" ::: "memory")
; #define PG8_WAIT_L(n) asm volatile("s_waitcnt lgkmcnt(" #n ")" ::: "memory")
; #define PG8_BAR __builtin_amdgcn_s_barrier()
; #define PG8_SCHED __builtin_amdgcn_sched_barrier(0)
; template <class Epi, class Sched, bool ALIGN_EPI = false, bool SP2 = false>
; __device__ __forceinline__ void gemm_phase(PG8_LAS unsigned char* lds, const Gemm g, const Sched& S, const Epi& E) {
;     ...
;             PG8_LDA(At, 0, 1); PG8_STAGE(PG8_SB(0, 0), b2, voffB); PG8_STAGE(PG8_SB(0, 1), b2 + hstep, voffB); PG8_STAGE(PG8_SA(0, 0), a2, voffA);
;             PG8_WAIT_V(8); PG8_WAIT_L(0); PG8_BAR; PG8_MMA(1, 0, At, B0); PG8_MMA(1, 1, At, B1); PG8_BAR; PG8_SCHED;
	v_lshl_add_u64 v[212:213], s[30:31], 0, v[202:203]
	s_add_i32 m0, s41, 0x10000
	ds_read_b128 v[164:167], v253 offset:16384
	ds_read_b128 v[168:171], v253 offset:17408
	ds_read_b128 v[172:175], v253 offset:18432
	ds_read_b128 v[176:179], v253 offset:19456
	ds_read_b128 v[180:183], v253 offset:20480
	ds_read_b128 v[184:187], v253 offset:21504
	ds_read_b128 v[188:191], v253 offset:22528
	ds_read_b128 v[192:195], v253 offset:23552
	global_load_lds_dwordx4 v[212:213], off
	s_add_i32 m0, s41, 0x12000
	s_add_u32 s52, s30, 0x40000
	v_lshl_add_u64 v[214:215], s[30:31], 0, v[206:207]
	s_addc_u32 s53, s31, 0
	global_load_lds_dwordx4 v[214:215], off
	v_lshl_add_u64 v[216:217], s[52:53], 0, v[202:203]
	s_add_i32 m0, s41, 0x14000
	v_lshl_add_u64 v[218:219], s[34:35], 0, v[204:205]
	global_load_lds_dwordx4 v[216:217], off
	s_add_i32 m0, s41, 0x16000
	v_lshl_add_u64 v[216:217], s[52:53], 0, v[206:207]
	global_load_lds_dwordx4 v[216:217], off
	s_mov_b32 m0, s42
	v_lshl_add_u64 v[216:217], s[34:35], 0, v[0:1]
	global_load_lds_dwordx4 v[216:217], off
	s_mov_b32 m0, s43
	s_add_i32 s52, 0, 0x18000
	global_load_lds_dwordx4 v[218:219], off
	s_waitcnt vmcnt(8) lgkmcnt(0)
	s_barrier
	v_mfma_f32_16x16x32_bf16 v[64:67], v[108:111], v[164:167], v[64:67]
	v_mfma_f32_16x16x32_bf16 v[60:63], v[124:127], v[164:167], v[60:63]
	v_mfma_f32_16x16x32_bf16 v[48:51], v[108:111], v[172:175], v[48:51]
	v_mfma_f32_16x16x32_bf16 v[44:47], v[124:127], v[172:175], v[44:47]
	v_mfma_f32_16x16x32_bf16 v[32:35], v[108:111], v[180:183], v[32:35]
	v_mfma_f32_16x16x32_bf16 v[28:31], v[124:127], v[180:183], v[28:31]
	v_mfma_f32_16x16x32_bf16 v[16:19], v[108:111], v[188:191], v[16:19]
	v_mfma_f32_16x16x32_bf16 v[12:15], v[124:127], v[188:191], v[12:15]
	v_mfma_f32_16x16x32_bf16 v[64:67], v[112:115], v[168:171], v[64:67]
	v_mfma_f32_16x16x32_bf16 v[60:63], v[128:131], v[168:171], v[60:63]
	v_mfma_f32_16x16x32_bf16 v[48:51], v[112:115], v[176:179], v[48:51]
	v_mfma_f32_16x16x32_bf16 v[44:47], v[128:131], v[176:179], v[44:47]
	v_mfma_f32_16x16x32_bf16 v[32:35], v[112:115], v[184:187], v[32:35]
	v_mfma_f32_16x16x32_bf16 v[28:31], v[128:131], v[184:187], v[28:31]
	v_mfma_f32_16x16x32_bf16 v[16:19], v[112:115], v[192:195], v[16:19]
	v_mfma_f32_16x16x32_bf16 v[12:15], v[128:131], v[192:195], v[12:15]
	v_mfma_f32_16x16x32_bf16 v[56:59], v[132:135], v[164:167], v[56:59]
	v_mfma_f32_16x16x32_bf16 v[52:55], v[148:151], v[164:167], v[52:55]
	v_mfma_f32_16x16x32_bf16 v[40:43], v[132:135], v[172:175], v[40:43]
	v_mfma_f32_16x16x32_bf16 v[36:39], v[148:151], v[172:175], v[36:39]
	v_mfma_f32_16x16x32_bf16 v[24:27], v[132:135], v[180:183], v[24:27]
	v_mfma_f32_16x16x32_bf16 v[20:23], v[148:151], v[180:183], v[20:23]
	v_mfma_f32_16x16x32_bf16 v[8:11], v[132:135], v[188:191], v[8:11]
	v_mfma_f32_16x16x32_bf16 v[4:7], v[148:151], v[188:191], v[4:7]
	v_mfma_f32_16x16x32_bf16 v[56:59], v[140:143], v[168:171], v[56:59]
	v_mfma_f32_16x16x32_bf16 v[52:55], v[156:159], v[168:171], v[52:55]
	v_mfma_f32_16x16x32_bf16 v[40:43], v[140:143], v[176:179], v[40:43]
	v_mfma_f32_16x16x32_bf16 v[36:39], v[156:159], v[176:179], v[36:39]
	v_mfma_f32_16x16x32_bf16 v[24:27], v[140:143], v[184:187], v[24:27]
	v_mfma_f32_16x16x32_bf16 v[20:23], v[156:159], v[184:187], v[20:23]
	v_mfma_f32_16x16x32_bf16 v[8:11], v[140:143], v[192:195], v[8:11]
	v_mfma_f32_16x16x32_bf16 v[4:7], v[156:159], v[192:195], v[4:7]
	s_barrier
; #define PG8_STAGE(bufoff, gbase, voff) do { _Pragma("unroll") for (int _i = 0; _i < 2; ++_i) \
;         __builtin_amdgcn_global_load_lds((const unsigned*)((const char*)(gbase) + (voff)[_i]), (PG8_LAS unsigned*)(lds + (bufoff) + ldsw + _i * 8192), 16, 0, 0); } while (0)
; #define PG8_LDA(dst, b, h) do { _Pragma("unroll") for (int m = 0; m < 4; ++m) _Pragma("unroll") for (int k = 0; k < 2; ++k) dst[m][k] = *(const PG8_LAS bf16x8*)(lds + PG8_SA(b, h) + aoff + m * 2048 + k * 1024); } while (0)
; #define PG8_LDB(dst, b, h) do { _Pragma("unroll") for (int n = 0; n < 2; ++n) _Pragma("unroll") for (int k = 0; k < 2; ++k) dst[n][k] = *(const PG8_LAS bf16x8*)(lds + PG8_SB(b, h) + boff + n * 2048 + k * 1024); } while (0)
; #define PG8_MMA(ai, bj, At, Bt) do { __builtin_amdgcn_s_setprio(1); _Pragma("unroll") for (int m = 0; m < 4; ++m) _Pragma("unroll") for (int n = 0; n < 2; ++n) _Pragma("unroll") for (int k = 0; k < 2; ++k) \
;         acc[ai][bj][m][n] = __builtin_amdgcn_mfma_f32_16x16x32_bf16(Bt[n][k], At[m][k], acc[ai][bj][m][n], 0, 0, 0); __builtin_amdgcn_s_setprio(0); } while (0)
; #define PG8_WAIT_V(n) asm volatile("s_waitcnt vmcnt(" #n ")" ::: "memory")
; #define PG8_WAIT_L(n) asm volatile("s_waitcnt lgkmcnt(" #n ")" ::: "memory")
; #define PG8_BAR __builtin_amdgcn_s_barrier()
; #define PG8_SCHED __builtin_amdgcn_sched_barrier(0)
; template <class Epi, class Sched, bool ALIGN_EPI = false, bool SP2 = false>
; __device__ __forceinline__ void gemm_phase(PG8_LAS unsigned char* lds, const Gemm g, const Sched& S, const Epi& E) {
;     ...
;             PG8_LDB(B0, 1, 0); PG8_LDB(B1, 1, 1); PG8_SCHED; PG8_LDA(At, 1, 0); PG8_STAGE(PG8_SA(0, 1), a2 + hstep, voffA);
;             PG8_WAIT_V(8); PG8_WAIT_L(0); PG8_BAR; PG8_MMA(0, 0, At, B0); PG8_MMA(0, 1, At, B1); PG8_BAR; PG8_SCHED;
;             PG8_LDA(At, 1, 1); PG8_STAGE(PG8_SB(1, 0), b3, voffB); PG8_STAGE(PG8_SB(1, 1), b3 + hstep, voffB); PG8_STAGE(PG8_SA(1, 0), a3, voffA);
;             PG8_WAIT_V(8); PG8_WAIT_L(0); PG8_BAR; PG8_MMA(1, 0, At, B0); PG8_MMA(1, 1, At, B1); PG8_BAR; PG8_SCHED;
;     ...
;         if constexpr (ALIGN_EPI) { if (wr == 0) PG8_BAR; }
.Lkmid_1:
	ds_read_b128 v[108:111], v251 offset:32768
	ds_read_b128 v[112:115], v251 offset:33792
	ds_read_b128 v[124:127], v251 offset:34816
	ds_read_b128 v[128:131], v251 offset:35840
	ds_read_b128 v[132:135], v251 offset:49152
	ds_read_b128 v[140:143], v251 offset:50176
	ds_read_b128 v[148:151], v251 offset:51200
	ds_read_b128 v[156:159], v251 offset:52224
	s_add_u32 s34, s34, 0x40000
	s_addc_u32 s35, s35, 0
	s_mov_b32 m0, s46
	v_lshl_add_u64 v[220:221], s[34:35], 0, v[0:1]
	ds_read_b128 v[164:167], v253 offset:32768
	ds_read_b128 v[168:171], v253 offset:33792
	ds_read_b128 v[172:175], v253 offset:34816
	ds_read_b128 v[176:179], v253 offset:35840
	ds_read_b128 v[180:183], v253 offset:36864
	ds_read_b128 v[184:187], v253 offset:37888
	ds_read_b128 v[188:191], v253 offset:38912
	ds_read_b128 v[192:195], v253 offset:39936
	global_load_lds_dwordx4 v[220:221], off
	s_mov_b32 m0, s47
	v_lshl_add_u64 v[220:221], s[34:35], 0, v[204:205]
	global_load_lds_dwordx4 v[220:221], off
	s_waitcnt vmcnt(8) lgkmcnt(0)
	s_barrier
	v_mfma_f32_16x16x32_bf16 v[160:163], v[108:111], v[164:167], v[160:163]
	v_mfma_f32_16x16x32_bf16 v[152:155], v[124:127], v[164:167], v[152:155]
	v_mfma_f32_16x16x32_bf16 v[120:123], v[108:111], v[172:175], v[120:123]
	v_mfma_f32_16x16x32_bf16 v[116:119], v[124:127], v[172:175], v[116:119]
	v_mfma_f32_16x16x32_bf16 v[96:99], v[108:111], v[180:183], v[96:99]
	v_mfma_f32_16x16x32_bf16 v[92:95], v[124:127], v[180:183], v[92:95]
	v_mfma_f32_16x16x32_bf16 v[80:83], v[108:111], v[188:191], v[80:83]
	v_mfma_f32_16x16x32_bf16 v[76:79], v[124:127], v[188:191], v[76:79]
	v_mfma_f32_16x16x32_bf16 v[160:163], v[112:115], v[168:171], v[160:163]
	v_mfma_f32_16x16x32_bf16 v[152:155], v[128:131], v[168:171], v[152:155]
	v_mfma_f32_16x16x32_bf16 v[120:123], v[112:115], v[176:179], v[120:123]
	v_mfma_f32_16x16x32_bf16 v[116:119], v[128:131], v[176:179], v[116:119]
	v_mfma_f32_16x16x32_bf16 v[96:99], v[112:115], v[184:187], v[96:99]
	v_mfma_f32_16x16x32_bf16 v[92:95], v[128:131], v[184:187], v[92:95]
	v_mfma_f32_16x16x32_bf16 v[80:83], v[112:115], v[192:195], v[80:83]
	v_mfma_f32_16x16x32_bf16 v[76:79], v[128:131], v[192:195], v[76:79]
	v_mfma_f32_16x16x32_bf16 v[144:147], v[132:135], v[164:167], v[144:147]
	v_mfma_f32_16x16x32_bf16 v[136:139], v[148:151], v[164:167], v[136:139]
	v_mfma_f32_16x16x32_bf16 v[104:107], v[132:135], v[172:175], v[104:107]
	v_mfma_f32_16x16x32_bf16 v[100:103], v[148:151], v[172:175], v[100:103]
	v_mfma_f32_16x16x32_bf16 v[88:91], v[132:135], v[180:183], v[88:91]
	v_mfma_f32_16x16x32_bf16 v[84:87], v[148:151], v[180:183], v[84:87]
	v_mfma_f32_16x16x32_bf16 v[72:75], v[132:135], v[188:191], v[72:75]
	v_mfma_f32_16x16x32_bf16 v[68:71], v[148:151], v[188:191], v[68:71]
	v_mfma_f32_16x16x32_bf16 v[144:147], v[140:143], v[168:171], v[144:147]
	v_mfma_f32_16x16x32_bf16 v[136:139], v[156:159], v[168:171], v[136:139]
	v_mfma_f32_16x16x32_bf16 v[104:107], v[140:143], v[176:179], v[104:107]
	v_mfma_f32_16x16x32_bf16 v[100:103], v[156:159], v[176:179], v[100:103]
	v_mfma_f32_16x16x32_bf16 v[88:91], v[140:143], v[184:187], v[88:91]
	v_mfma_f32_16x16x32_bf16 v[84:87], v[156:159], v[184:187], v[84:87]
	v_mfma_f32_16x16x32_bf16 v[72:75], v[140:143], v[192:195], v[72:75]
	v_mfma_f32_16x16x32_bf16 v[68:71], v[156:159], v[192:195], v[68:71]
	s_barrier
	s_add_i32 m0, s41, 0x17f80
	ds_read_b128 v[164:167], v253 offset:49152
	ds_read_b128 v[168:171], v253 offset:50176
	ds_read_b128 v[172:175], v253 offset:51200
	ds_read_b128 v[176:179], v253 offset:52224
	ds_read_b128 v[180:183], v253 offset:53248
	ds_read_b128 v[184:187], v253 offset:54272
	ds_read_b128 v[188:191], v253 offset:55296
	ds_read_b128 v[192:195], v253 offset:56320
	global_load_lds_dwordx4 v[212:213], off offset:128
	s_add_i32 m0, s41, 0x19f80
	s_add_u32 s30, s30, 0x40080
	s_addc_u32 s31, s31, 0
	global_load_lds_dwordx4 v[214:215], off offset:128
	s_add_i32 m0, s41, 0x1c000
	v_lshl_add_u64 v[212:213], s[30:31], 0, v[202:203]
	global_load_lds_dwordx4 v[212:213], off
	s_add_i32 m0, s41, 0x1e000
	v_lshl_add_u64 v[212:213], s[30:31], 0, v[206:207]
	global_load_lds_dwordx4 v[212:213], off
	s_add_i32 m0, s49, 0xffffff80
	s_add_u32 s28, s28, 0x100
	s_addc_u32 s29, s29, 0
	global_load_lds_dwordx4 v[216:217], off offset:128
	s_add_i32 m0, s50, 0xffffff80
	s_add_u32 s27, s27, 0x100
	s_addc_u32 s44, s44, 0
	global_load_lds_dwordx4 v[218:219], off offset:128
	s_waitcnt vmcnt(8) lgkmcnt(0)
	s_barrier
	v_mfma_f32_16x16x32_bf16 v[64:67], v[108:111], v[164:167], v[64:67]
	v_mfma_f32_16x16x32_bf16 v[60:63], v[124:127], v[164:167], v[60:63]
	v_mfma_f32_16x16x32_bf16 v[48:51], v[108:111], v[172:175], v[48:51]
	v_mfma_f32_16x16x32_bf16 v[44:47], v[124:127], v[172:175], v[44:47]
	v_mfma_f32_16x16x32_bf16 v[32:35], v[108:111], v[180:183], v[32:35]
	v_mfma_f32_16x16x32_bf16 v[28:31], v[124:127], v[180:183], v[28:31]
	v_mfma_f32_16x16x32_bf16 v[16:19], v[108:111], v[188:191], v[16:19]
	v_mfma_f32_16x16x32_bf16 v[12:15], v[124:127], v[188:191], v[12:15]
	v_mfma_f32_16x16x32_bf16 v[64:67], v[112:115], v[168:171], v[64:67]
	v_mfma_f32_16x16x32_bf16 v[60:63], v[128:131], v[168:171], v[60:63]
	v_mfma_f32_16x16x32_bf16 v[48:51], v[112:115], v[176:179], v[48:51]
	v_mfma_f32_16x16x32_bf16 v[44:47], v[128:131], v[176:179], v[44:47]
	v_mfma_f32_16x16x32_bf16 v[32:35], v[112:115], v[184:187], v[32:35]
	v_mfma_f32_16x16x32_bf16 v[28:31], v[128:131], v[184:187], v[28:31]
	v_mfma_f32_16x16x32_bf16 v[16:19], v[112:115], v[192:195], v[16:19]
	v_mfma_f32_16x16x32_bf16 v[12:15], v[128:131], v[192:195], v[12:15]
	v_mfma_f32_16x16x32_bf16 v[56:59], v[132:135], v[164:167], v[56:59]
	v_mfma_f32_16x16x32_bf16 v[52:55], v[148:151], v[164:167], v[52:55]
	v_mfma_f32_16x16x32_bf16 v[40:43], v[132:135], v[172:175], v[40:43]
	v_mfma_f32_16x16x32_bf16 v[36:39], v[148:151], v[172:175], v[36:39]
	v_mfma_f32_16x16x32_bf16 v[24:27], v[132:135], v[180:183], v[24:27]
	v_mfma_f32_16x16x32_bf16 v[20:23], v[148:151], v[180:183], v[20:23]
	v_mfma_f32_16x16x32_bf16 v[8:11], v[132:135], v[188:191], v[8:11]
	v_mfma_f32_16x16x32_bf16 v[4:7], v[148:151], v[188:191], v[4:7]
	v_mfma_f32_16x16x32_bf16 v[56:59], v[140:143], v[168:171], v[56:59]
	v_mfma_f32_16x16x32_bf16 v[52:55], v[156:159], v[168:171], v[52:55]
	v_mfma_f32_16x16x32_bf16 v[40:43], v[140:143], v[176:179], v[40:43]
	v_mfma_f32_16x16x32_bf16 v[36:39], v[156:159], v[176:179], v[36:39]
	v_mfma_f32_16x16x32_bf16 v[24:27], v[140:143], v[184:187], v[24:27]
	v_mfma_f32_16x16x32_bf16 v[20:23], v[156:159], v[184:187], v[20:23]
	v_mfma_f32_16x16x32_bf16 v[8:11], v[140:143], v[192:195], v[8:11]
	v_mfma_f32_16x16x32_bf16 v[4:7], v[156:159], v[192:195], v[4:7]
	s_barrier
	s_add_i32 s45, s45, 2
	s_cmp_gt_u32 s45, 13
	s_cbranch_scc0 .LBB0_329
	s_and_b64 vcc, exec, s[14:15]
	s_cbranch_vccz .LBB0_332
	s_barrier

; #define PG8_WAIT_V(n) asm volatile("s_waitcnt vmcnt(" #n ")" ::: "memory")
; #define PG8_BAR __builtin_amdgcn_s_barrier()
; template <class Epi, class Sched, bool ALIGN_EPI = false, bool SP2 = false>
; __device__ __forceinline__ void gemm_phase(PG8_LAS unsigned char* lds, const Gemm g, const Sched& S, const Epi& E) {
;     ...
;     PG8_WAIT_V(0);
;     if constexpr (!ALIGN_EPI) { if (wr == 0) PG8_BAR; }
;     PG8_BAR;
; __device__ __forceinline__ void xcd_barrier(const XcdBarrier& b) {
;     asm volatile("s_waitcnt vmcnt(0)" ::: "memory");
;     __syncthreads();
;     if (threadIdx.x == 0) {
;         unsigned* bar = b.bar; unsigned bx_ = b.x;
;         asm volatile("" : "+s"(bar), "+s"(bx_));
;         __builtin_amdgcn_s_waitcnt(0);
;         unsigned nloc = b.st[0], nx = b.st[1];
;         if (nloc == 0u) { xcd_barrier_complete(bar, bx_, nloc, nx); b.st[0] = nloc; b.st[1] = nx; }
.LBB0_352:
	s_setprio 0
	s_waitcnt vmcnt(0)
	s_waitcnt lgkmcnt(0)
	s_barrier
	s_and_saveexec_b64 s[36:37], s[62:63]
	s_cbranch_execz .LBB0_396
	s_mov_b32 s3, s99
	s_mov_b64 s[38:39], s[58:59]
	v_mov_b32_e32 v0, s70
	s_waitcnt vmcnt(0) expcnt(0) lgkmcnt(0)
	ds_read_b32 v4, v0
	v_mov_b32_e32 v0, s71
	ds_read_b32 v0, v0
	s_waitcnt lgkmcnt(1)
	v_cmp_ne_u32_e32 vcc, 0, v4
	s_cbranch_vccnz .LBB0_367
	s_add_u32 s4, s38, 0x1000
	s_addc_u32 s5, s39, 0
	s_add_u32 s6, s38, 0x1100
	s_addc_u32 s7, s39, 0
	s_add_u32 s8, s38, 0x1200
	s_addc_u32 s9, s39, 0
	s_add_u32 s10, s38, 0x1300
	s_addc_u32 s11, s39, 0
	s_mov_b32 s30, 1
	s_mov_b64 s[12:13], 0
	s_branch .LBB0_357

; __device__ __forceinline__ int opaque_tid() { int t = (int)threadIdx.x; asm volatile("" : "+v"(t)); return t; }
; #define PG8_STAGE(bufoff, gbase, voff) do { _Pragma("unroll") for (int _i = 0; _i < 2; ++_i) \
;         __builtin_amdgcn_global_load_lds((const unsigned*)((const char*)(gbase) + (voff)[_i]), (PG8_LAS unsigned*)(lds + (bufoff) + ldsw + _i * 8192), 16, 0, 0); } while (0)
; template <class Epi, class Sched, bool ALIGN_EPI = false, bool SP2 = false>
; __device__ __forceinline__ void gemm_phase(PG8_LAS unsigned char* lds, const Gemm g, const Sched& S, const Epi& E) {
;     const int tid = opaque_tid(), wid = __builtin_amdgcn_readfirstlane(tid >> 6), lane = tid & 63, wr = wid >> 2, wc = wid & 3, fr = lane & 15, fq = lane >> 4;
;     const int K = g.K, nt = K / BK;
;     unsigned voffA[2], voffB[2];
; #pragma unroll
;     for (int i = 0; i < 2; ++i) { int R, C; stage_rc(tid * 16 + i * 8192, R, C); const int Rb = Epi::PERM ? ((R & ~31) + perm32(R & 31)) : R;
;         voffA[i] = (unsigned)(R * K + C) * 2u; voffB[i] = (unsigned)(Rb * K + C) * 2u; }
;     const size_t kstep = (size_t)(BK * 2);
;     const size_t hstep = (size_t)HALF * K * 2;
;     const size_t tstep = 2 * hstep;
;     const unsigned ldsw = (unsigned)wid * 1024u;
;     const int aoff = lds_byte(wr * 64 + fr, fq * 8), boff = lds_byte(wc * 32 + fr, fq * 8);
;     ...
;     const char* cA = (const char*)g.A + (size_t)cur.pm * tstep; const char* cB = (const char*)g.Bt + (size_t)cur.pn * tstep;
;     S.a_ready(cur);
;     if constexpr (SP2) {
;         PG8_STAGE(PG8_SB(0, 0), cB, voffB); PG8_STAGE(PG8_SB(0, 1), cB + hstep, voffB); PG8_STAGE(PG8_SA(0, 0), cA, voffA); PG8_STAGE(PG8_SA(0, 1), cA + hstep, voffA);
;         if (wr == 1) PG8_BAR;
;         PG8_WAIT_V(2); PG8_BAR;
;         PG8_STAGE(PG8_SB(1, 0), cB + kstep, voffB); PG8_STAGE(PG8_SA(1, 0), cA + kstep, voffA); PG8_STAGE(PG8_SB(1, 1), cB + hstep + kstep, voffB);
;         PG8_WAIT_V(6); PG8_BAR;
;     } else {
;         PG8_STAGE(PG8_SB(0, 0), cB, voffB); PG8_STAGE(PG8_SA(0, 0), cA, voffA); PG8_STAGE(PG8_SB(0, 1), cB + hstep, voffB); PG8_STAGE(PG8_SA(0, 1), cA + hstep, voffA);
;         if (wr == 1) PG8_BAR;
;         PG8_WAIT_V(4); PG8_BAR;
;         PG8_STAGE(PG8_SB(1, 0), cB + kstep, voffB); PG8_STAGE(PG8_SA(1, 0), cA + kstep, voffA); PG8_STAGE(PG8_SB(1, 1), cB + hstep + kstep, voffB);
;         PG8_WAIT_V(6); PG8_BAR;
;     }
.LBB0_399:
	s_add_u32 s12, s4, 0xa400000
	s_addc_u32 s13, s5, 0
	s_lshl_b32 s3, s3, 5
	s_and_b32 s17, s3, 0x60
	s_add_i32 m0, s37, 0x18000
	v_lshl_add_u64 v[10:11], v[10:11], 0, s[82:83]
	s_lshl_b32 s7, s16, 13
	s_lshl_b32 s20, s17, 7
	s_waitcnt vmcnt(2)
	s_barrier
	global_load_lds_dwordx4 v[10:11], off
	v_lshl_add_u64 v[8:9], v[8:9], 0, s[82:83]
	s_add_i32 m0, s37, 0x1a000
	s_add_i32 s41, s37, 0x8000
	s_add_i32 s42, s37, 0xa000
	global_load_lds_dwordx4 v[8:9], off
	v_lshl_add_u64 v[4:5], v[4:5], 0, s[82:83]
	s_mov_b32 m0, s41
	s_add_u32 s18, s24, 0x40080
	global_load_lds_dwordx4 v[4:5], off
	v_lshl_add_u64 v[4:5], v[6:7], 0, s[82:83]
	s_mov_b32 m0, s42
	s_addc_u32 s19, s25, 0
	global_load_lds_dwordx4 v[4:5], off
	s_add_i32 m0, s37, 0x1c000
	v_lshl_add_u64 v[4:5], s[18:19], 0, v[134:135]
	global_load_lds_dwordx4 v[4:5], off
	v_lshl_add_u64 v[4:5], s[18:19], 0, v[0:1]
	s_add_i32 m0, s37, 0x1e000
	v_bfe_u32 v6, v12, 4, 2
	global_load_lds_dwordx4 v[4:5], off
	v_and_b32_e32 v5, 15, v12
	v_lshlrev_b32_e32 v4, 4, v6
	v_lshlrev_b32_e32 v7, 2, v12
	v_lshl_or_b32 v3, s16, 6, v5
	v_lshl_or_b32 v5, v5, 6, v4
	v_and_b32_e32 v7, 32, v7
	v_bitop3_b32 v8, v5, s7, v7 bitop3:0xde
	v_bitop3_b32 v164, v5, s20, v7 bitop3:0xde
	v_add_u32_e32 v164, 0x10000, v164
	v_mov_b32_e32 v5, v2
	v_lshl_add_u64 v[4:5], s[4:5], 0, v[4:5]
	s_mov_b64 s[4:5], 0x1a600000
	v_lshl_add_u64 v[138:139], v[4:5], 0, s[4:5]
	v_lshlrev_b32_e32 v4, 14, v17
	v_and_b32_e32 v4, 0xffff8000, v4
	v_lshl_add_u32 v4, v16, 11, v4
	v_and_b32_e32 v5, 1, v17
	v_lshl_or_b32 v4, v5, 6, v4
	v_lshl_add_u32 v140, v18, 1, v4
	v_lshlrev_b32_e32 v4, 14, v13
	v_and_b32_e32 v4, 0xffff8000, v4
	s_waitcnt vmcnt(6)
	v_lshl_add_u32 v4, v14, 11, v4
	v_and_b32_e32 v5, 1, v13
	s_cmpk_lt_u32 s15, 0x100
	v_lshl_or_b32 v4, v5, 6, v4
	s_sext_i32_i16 s3, s14
	s_cselect_b64 s[14:15], -1, 0
	v_lshl_or_b32 v165, v6, 3, s17
	v_mov_b32_e32 v141, v2
	v_lshl_add_u32 v142, v15, 1, v4
	v_mov_b32_e32 v143, v2
	s_mov_b32 s72, 0
	v_add_u32_e32 v166, 0, v8
	s_barrier
	v_readfirstlane_b32 s100, v197
	s_cmp_lt_u32 s100, 0x100
	s_cbranch_scc1 .Lsp_2
	s_setprio 1
.Lsp_2:
	s_branch .LBB0_402
.LBB0_400:
	s_mov_b64 s[4:5], 0

; #define PG8_STAGE(bufoff, gbase, voff) do { _Pragma("unroll") for (int _i = 0; _i < 2; ++_i) \
;         __builtin_amdgcn_global_load_lds((const unsigned*)((const char*)(gbase) + (voff)[_i]), (PG8_LAS unsigned*)(lds + (bufoff) + ldsw + _i * 8192), 16, 0, 0); } while (0)
; #define PG8_LDA(dst, b, h) do { _Pragma("unroll") for (int m = 0; m < 4; ++m) _Pragma("unroll") for (int k = 0; k < 2; ++k) dst[m][k] = *(const PG8_LAS bf16x8*)(lds + PG8_SA(b, h) + aoff + m * 2048 + k * 1024); } while (0)
; #define PG8_LDB(dst, b, h) do { _Pragma("unroll") for (int n = 0; n < 2; ++n) _Pragma("unroll") for (int k = 0; k < 2; ++k) dst[n][k] = *(const PG8_LAS bf16x8*)(lds + PG8_SB(b, h) + boff + n * 2048 + k * 1024); } while (0)
; #define PG8_WAIT_V(n) asm volatile("s_waitcnt vmcnt(" #n ")" ::: "memory")
; #define PG8_WAIT_L(n) asm volatile("s_waitcnt lgkmcnt(" #n ")" ::: "memory")
; #define PG8_BAR __builtin_amdgcn_s_barrier()
; #define PG8_SCHED __builtin_amdgcn_sched_barrier(0)
; template <class Epi, class Sched, bool ALIGN_EPI = false, bool SP2 = false>
; __device__ __forceinline__ void gemm_phase(PG8_LAS unsigned char* lds, const Gemm g, const Sched& S, const Epi& E) {
;     ...
;         const bool has_next = S.next(ui + 1, nxt);
;         const char* nA = has_next ? (const char*)g.A + (size_t)nxt.pm * tstep : cA; const char* nB = has_next ? (const char*)g.Bt + (size_t)nxt.pn * tstep : cB;
;         for (int t = 0; t < nt; t += 2) {
;             const bool last = (t == nt - 2);
;             const char* a1 = cA + (size_t)(t + 1) * kstep;
;             const char* a2 = last ? nA : cA + (size_t)(t + 2) * kstep; const char* b2 = last ? nB : cB + (size_t)(t + 2) * kstep;
;             const char* a3 = a2 + kstep; const char* b3 = b2 + kstep;
;             if (last && has_next) S.a_ready(nxt);
;             if constexpr (SP2) {
;             PG8_LDB(B0, 0, 0); PG8_LDB(B1, 0, 1); PG8_SCHED; PG8_LDA(At, 0, 0); PG8_STAGE(PG8_SA(1, 1), a1 + hstep, voffA);
;             PG8_WAIT_V(8); PG8_WAIT_L(0); PG8_BAR; PG8_MMA(0, 0, At, B0); PG8_MMA(0, 1, At, B1); PG8_BAR; PG8_SCHED;
;             PG8_LDA(At, 0, 1); PG8_STAGE(PG8_SB(0, 0), b2, voffB); PG8_STAGE(PG8_SB(0, 1), b2 + hstep, voffB); PG8_STAGE(PG8_SA(0, 0), a2, voffA);
;             PG8_WAIT_V(8); PG8_WAIT_L(0); PG8_BAR; PG8_MMA(1, 0, At, B0); PG8_MMA(1, 1, At, B1); PG8_BAR; PG8_SCHED;
.LBB0_404:
	s_ashr_i32 s17, s16, 31
	s_lshl_b64 s[20:21], s[16:17], 19
	s_add_u32 s20, s29, s20
	s_addc_u32 s21, s30, s21
	s_and_b64 s[22:23], s[4:5], exec
	s_cselect_b32 s7, s21, s9
	s_cselect_b32 s17, s20, s8
	s_ashr_i32 s19, s18, 31
	s_lshl_b64 s[22:23], s[18:19], 19
	s_add_u32 s22, s31, s22
	s_addc_u32 s23, s34, s23
	s_and_b64 s[26:27], s[4:5], exec
	s_cselect_b32 s19, s23, s25
	s_cselect_b32 s43, s22, s24
	s_add_u32 s8, s8, 0x40080
	s_addc_u32 s9, s9, 0
	s_add_u32 s44, s24, 0x100
	s_addc_u32 s45, s25, 0
	s_mov_b32 s46, -2
	s_add_u32 s24, s8, 0xfffc0080
	s_addc_u32 s25, s9, -1
	s_cmp_eq_u32 s46, 12
	s_cselect_b32 s27, s7, s25
	s_cselect_b32 s26, s17, s24
	s_cselect_b32 s25, s19, s45
	s_cselect_b32 s24, s43, s44
	s_add_i32 s50, 0, 0x14000
	ds_read_b128 v[144:147], v164
	ds_read_b128 v[148:151], v164 offset:1024
	ds_read_b128 v[152:155], v164 offset:2048
	ds_read_b128 v[156:159], v164 offset:3072
	ds_read_b128 v[160:163], v164 offset:16384
	ds_read_b128 v[168:171], v164 offset:17408
	ds_read_b128 v[172:175], v164 offset:18432
	ds_read_b128 v[176:179], v164 offset:19456
	v_lshl_add_u64 v[198:199], s[8:9], 0, v[140:141]
	s_add_i32 m0, s37, 0xc000
	ds_read_b128 v[180:183], v166
	ds_read_b128 v[184:187], v166 offset:1024
	ds_read_b128 v[188:191], v166 offset:2048
	ds_read_b128 v[192:195], v166 offset:3072
	ds_read_b128 v[202:205], v166 offset:4096
	ds_read_b128 v[206:209], v166 offset:5120
	ds_read_b128 v[210:213], v166 offset:6144
	ds_read_b128 v[214:217], v166 offset:7168
	global_load_lds_dwordx4 v[198:199], off
	s_add_i32 m0, s37, 0xe000
	v_lshl_add_u64 v[198:199], s[8:9], 0, v[142:143]
	global_load_lds_dwordx4 v[198:199], off
	s_waitcnt vmcnt(8) lgkmcnt(0)
	s_barrier
	v_mfma_f32_16x16x32_bf16 v[128:131], v[144:147], v[180:183], 0
	v_mfma_f32_16x16x32_bf16 v[120:123], v[152:155], v[180:183], 0
	v_mfma_f32_16x16x32_bf16 v[112:115], v[144:147], v[188:191], 0
	v_mfma_f32_16x16x32_bf16 v[104:107], v[152:155], v[188:191], 0
	v_mfma_f32_16x16x32_bf16 v[96:99], v[144:147], v[202:205], 0
	v_mfma_f32_16x16x32_bf16 v[88:91], v[152:155], v[202:205], 0
	v_mfma_f32_16x16x32_bf16 v[80:83], v[144:147], v[210:213], 0
	v_mfma_f32_16x16x32_bf16 v[72:75], v[152:155], v[210:213], 0
	v_mfma_f32_16x16x32_bf16 v[128:131], v[148:151], v[184:187], v[128:131]
	v_mfma_f32_16x16x32_bf16 v[120:123], v[156:159], v[184:187], v[120:123]
	v_mfma_f32_16x16x32_bf16 v[112:115], v[148:151], v[192:195], v[112:115]
	v_mfma_f32_16x16x32_bf16 v[104:107], v[156:159], v[192:195], v[104:107]
	v_mfma_f32_16x16x32_bf16 v[96:99], v[148:151], v[206:209], v[96:99]
	v_mfma_f32_16x16x32_bf16 v[88:91], v[156:159], v[206:209], v[88:91]
	v_mfma_f32_16x16x32_bf16 v[80:83], v[148:151], v[214:217], v[80:83]
	v_mfma_f32_16x16x32_bf16 v[72:75], v[156:159], v[214:217], v[72:75]
	v_mfma_f32_16x16x32_bf16 v[124:127], v[160:163], v[180:183], 0
	v_mfma_f32_16x16x32_bf16 v[116:119], v[172:175], v[180:183], 0
	v_mfma_f32_16x16x32_bf16 v[108:111], v[160:163], v[188:191], 0
	v_mfma_f32_16x16x32_bf16 v[100:103], v[172:175], v[188:191], 0
	v_mfma_f32_16x16x32_bf16 v[92:95], v[160:163], v[202:205], 0
	v_mfma_f32_16x16x32_bf16 v[84:87], v[172:175], v[202:205], 0
	v_mfma_f32_16x16x32_bf16 v[76:79], v[160:163], v[210:213], 0
	v_mfma_f32_16x16x32_bf16 v[68:71], v[172:175], v[210:213], 0
	v_mfma_f32_16x16x32_bf16 v[124:127], v[168:171], v[184:187], v[124:127]
	v_mfma_f32_16x16x32_bf16 v[116:119], v[176:179], v[184:187], v[116:119]
	v_mfma_f32_16x16x32_bf16 v[108:111], v[168:171], v[192:195], v[108:111]
	v_mfma_f32_16x16x32_bf16 v[100:103], v[176:179], v[192:195], v[100:103]
	v_mfma_f32_16x16x32_bf16 v[92:95], v[168:171], v[206:209], v[92:95]
	v_mfma_f32_16x16x32_bf16 v[84:87], v[176:179], v[206:209], v[84:87]
	v_mfma_f32_16x16x32_bf16 v[76:79], v[168:171], v[214:217], v[76:79]
	v_mfma_f32_16x16x32_bf16 v[68:71], v[176:179], v[214:217], v[68:71]
	s_barrier
	v_lshl_add_u64 v[198:199], s[24:25], 0, v[134:135]
	s_add_i32 m0, s35, 0x10000
	ds_read_b128 v[180:183], v166 offset:16384
	ds_read_b128 v[184:187], v166 offset:17408
	ds_read_b128 v[188:191], v166 offset:18432
	ds_read_b128 v[192:195], v166 offset:19456
	ds_read_b128 v[202:205], v166 offset:20480
	ds_read_b128 v[206:209], v166 offset:21504
	ds_read_b128 v[210:213], v166 offset:22528
	ds_read_b128 v[214:217], v166 offset:23552
	global_load_lds_dwordx4 v[198:199], off
	s_add_i32 m0, s35, 0x12000
	s_add_u32 s48, s24, 0x40000
	v_lshl_add_u64 v[218:219], s[24:25], 0, v[0:1]
	s_addc_u32 s49, s25, 0
	global_load_lds_dwordx4 v[218:219], off
	v_lshl_add_u64 v[220:221], s[48:49], 0, v[134:135]
	s_add_i32 m0, s35, 0x14000
	v_lshl_add_u64 v[222:223], s[26:27], 0, v[132:133]
	global_load_lds_dwordx4 v[220:221], off
	s_add_i32 m0, s35, 0x16000
	v_lshl_add_u64 v[220:221], s[48:49], 0, v[0:1]
	global_load_lds_dwordx4 v[220:221], off
	s_mov_b32 m0, s37
	v_lshl_add_u64 v[220:221], s[26:27], 0, v[136:137]
	global_load_lds_dwordx4 v[220:221], off
	s_mov_b32 m0, s38
	s_add_i32 s47, 0, 0x18000
	global_load_lds_dwordx4 v[222:223], off
	s_waitcnt vmcnt(8) lgkmcnt(0)
	s_barrier
; #define PG8_STAGE(bufoff, gbase, voff) do { _Pragma("unroll") for (int _i = 0; _i < 2; ++_i) \
;         __builtin_amdgcn_global_load_lds((const unsigned*)((const char*)(gbase) + (voff)[_i]), (PG8_LAS unsigned*)(lds + (bufoff) + ldsw + _i * 8192), 16, 0, 0); } while (0)
; #define PG8_LDA(dst, b, h) do { _Pragma("unroll") for (int m = 0; m < 4; ++m) _Pragma("unroll") for (int k = 0; k < 2; ++k) dst[m][k] = *(const PG8_LAS bf16x8*)(lds + PG8_SA(b, h) + aoff + m * 2048 + k * 1024); } while (0)
; #define PG8_LDB(dst, b, h) do { _Pragma("unroll") for (int n = 0; n < 2; ++n) _Pragma("unroll") for (int k = 0; k < 2; ++k) dst[n][k] = *(const PG8_LAS bf16x8*)(lds + PG8_SB(b, h) + boff + n * 2048 + k * 1024); } while (0)
; #define PG8_MMA(ai, bj, At, Bt) do { __builtin_amdgcn_s_setprio(1); _Pragma("unroll") for (int m = 0; m < 4; ++m) _Pragma("unroll") for (int n = 0; n < 2; ++n) _Pragma("unroll") for (int k = 0; k < 2; ++k) \
;         acc[ai][bj][m][n] = __builtin_amdgcn_mfma_f32_16x16x32_bf16(Bt[n][k], At[m][k], acc[ai][bj][m][n], 0, 0, 0); __builtin_amdgcn_s_setprio(0); } while (0)
; #define PG8_WAIT_V(n) asm volatile("s_waitcnt vmcnt(" #n ")" ::: "memory")
; #define PG8_WAIT_L(n) asm volatile("s_waitcnt lgkmcnt(" #n ")" ::: "memory")
; #define PG8_BAR __builtin_amdgcn_s_barrier()
; #define PG8_SCHED __builtin_amdgcn_sched_barrier(0)
; template <class Epi, class Sched, bool ALIGN_EPI = false, bool SP2 = false>
; __device__ __forceinline__ void gemm_phase(PG8_LAS unsigned char* lds, const Gemm g, const Sched& S, const Epi& E) {
;     ...
;             PG8_LDB(B0, 0, 0); PG8_LDB(B1, 0, 1); PG8_SCHED; PG8_LDA(At, 0, 0); PG8_STAGE(PG8_SA(1, 1), a1 + hstep, voffA);
;             PG8_WAIT_V(8); PG8_WAIT_L(0); PG8_BAR; PG8_MMA(0, 0, At, B0); PG8_MMA(0, 1, At, B1); PG8_BAR; PG8_SCHED;
;             PG8_LDA(At, 0, 1); PG8_STAGE(PG8_SB(0, 0), b2, voffB); PG8_STAGE(PG8_SB(0, 1), b2 + hstep, voffB); PG8_STAGE(PG8_SA(0, 0), a2, voffA);
;             PG8_WAIT_V(8); PG8_WAIT_L(0); PG8_BAR; PG8_MMA(1, 0, At, B0); PG8_MMA(1, 1, At, B1); PG8_BAR; PG8_SCHED;
	v_mfma_f32_16x16x32_bf16 v[64:67], v[144:147], v[180:183], 0
	v_mfma_f32_16x16x32_bf16 v[56:59], v[152:155], v[180:183], 0
	v_mfma_f32_16x16x32_bf16 v[48:51], v[144:147], v[188:191], 0
	v_mfma_f32_16x16x32_bf16 v[40:43], v[152:155], v[188:191], 0
	v_mfma_f32_16x16x32_bf16 v[32:35], v[144:147], v[202:205], 0
	v_mfma_f32_16x16x32_bf16 v[24:27], v[152:155], v[202:205], 0
	v_mfma_f32_16x16x32_bf16 v[16:19], v[144:147], v[210:213], 0
	v_mfma_f32_16x16x32_bf16 v[8:11], v[152:155], v[210:213], 0
	v_mfma_f32_16x16x32_bf16 v[64:67], v[148:151], v[184:187], v[64:67]
	v_mfma_f32_16x16x32_bf16 v[56:59], v[156:159], v[184:187], v[56:59]
	v_mfma_f32_16x16x32_bf16 v[48:51], v[148:151], v[192:195], v[48:51]
	v_mfma_f32_16x16x32_bf16 v[40:43], v[156:159], v[192:195], v[40:43]
	v_mfma_f32_16x16x32_bf16 v[32:35], v[148:151], v[206:209], v[32:35]
	v_mfma_f32_16x16x32_bf16 v[24:27], v[156:159], v[206:209], v[24:27]
	v_mfma_f32_16x16x32_bf16 v[16:19], v[148:151], v[214:217], v[16:19]
	v_mfma_f32_16x16x32_bf16 v[8:11], v[156:159], v[214:217], v[8:11]
	v_mfma_f32_16x16x32_bf16 v[60:63], v[160:163], v[180:183], 0
	v_mfma_f32_16x16x32_bf16 v[52:55], v[172:175], v[180:183], 0
	v_mfma_f32_16x16x32_bf16 v[44:47], v[160:163], v[188:191], 0
	v_mfma_f32_16x16x32_bf16 v[36:39], v[172:175], v[188:191], 0
	v_mfma_f32_16x16x32_bf16 v[28:31], v[160:163], v[202:205], 0
	v_mfma_f32_16x16x32_bf16 v[20:23], v[172:175], v[202:205], 0
	v_mfma_f32_16x16x32_bf16 v[12:15], v[160:163], v[210:213], 0
	v_mfma_f32_16x16x32_bf16 v[4:7], v[172:175], v[210:213], 0
	v_mfma_f32_16x16x32_bf16 v[60:63], v[168:171], v[184:187], v[60:63]
	v_mfma_f32_16x16x32_bf16 v[52:55], v[176:179], v[184:187], v[52:55]
	v_mfma_f32_16x16x32_bf16 v[44:47], v[168:171], v[192:195], v[44:47]
	v_mfma_f32_16x16x32_bf16 v[36:39], v[176:179], v[192:195], v[36:39]
	v_mfma_f32_16x16x32_bf16 v[28:31], v[168:171], v[206:209], v[28:31]
	v_mfma_f32_16x16x32_bf16 v[20:23], v[176:179], v[206:209], v[20:23]
	v_mfma_f32_16x16x32_bf16 v[12:15], v[168:171], v[214:217], v[12:15]
	v_mfma_f32_16x16x32_bf16 v[4:7], v[176:179], v[214:217], v[4:7]
	s_barrier
	s_branch .Lkmid_2
.LBB0_405:
	s_add_u32 s24, s8, 0xfffc0080
	s_addc_u32 s25, s9, -1
	s_cmp_eq_u32 s46, 12
	s_cselect_b32 s27, s7, s25
	s_cselect_b32 s26, s17, s24
	s_cselect_b32 s25, s19, s45
	s_cselect_b32 s24, s43, s44
	s_add_i32 s50, 0, 0x14000
	ds_read_b128 v[144:147], v164
	ds_read_b128 v[148:151], v164 offset:1024
	ds_read_b128 v[152:155], v164 offset:2048
	ds_read_b128 v[156:159], v164 offset:3072
	ds_read_b128 v[160:163], v164 offset:16384
	ds_read_b128 v[168:171], v164 offset:17408
	ds_read_b128 v[172:175], v164 offset:18432
	ds_read_b128 v[176:179], v164 offset:19456
	v_lshl_add_u64 v[198:199], s[8:9], 0, v[140:141]
	s_add_i32 m0, s37, 0xc000
	ds_read_b128 v[180:183], v166
	ds_read_b128 v[184:187], v166 offset:1024
	ds_read_b128 v[188:191], v166 offset:2048
	ds_read_b128 v[192:195], v166 offset:3072
	ds_read_b128 v[202:205], v166 offset:4096
	ds_read_b128 v[206:209], v166 offset:5120
	ds_read_b128 v[210:213], v166 offset:6144
	ds_read_b128 v[214:217], v166 offset:7168
	global_load_lds_dwordx4 v[198:199], off
	s_add_i32 m0, s37, 0xe000
	v_lshl_add_u64 v[198:199], s[8:9], 0, v[142:143]
	global_load_lds_dwordx4 v[198:199], off
	s_waitcnt vmcnt(8) lgkmcnt(0)
	s_barrier
	v_mfma_f32_16x16x32_bf16 v[128:131], v[144:147], v[180:183], v[128:131]
	v_mfma_f32_16x16x32_bf16 v[120:123], v[152:155], v[180:183], v[120:123]
	v_mfma_f32_16x16x32_bf16 v[112:115], v[144:147], v[188:191], v[112:115]
	v_mfma_f32_16x16x32_bf16 v[104:107], v[152:155], v[188:191], v[104:107]
	v_mfma_f32_16x16x32_bf16 v[96:99], v[144:147], v[202:205], v[96:99]
	v_mfma_f32_16x16x32_bf16 v[88:91], v[152:155], v[202:205], v[88:91]
	v_mfma_f32_16x16x32_bf16 v[80:83], v[144:147], v[210:213], v[80:83]
	v_mfma_f32_16x16x32_bf16 v[72:75], v[152:155], v[210:213], v[72:75]
	v_mfma_f32_16x16x32_bf16 v[128:131], v[148:151], v[184:187], v[128:131]
	v_mfma_f32_16x16x32_bf16 v[120:123], v[156:159], v[184:187], v[120:123]
	v_mfma_f32_16x16x32_bf16 v[112:115], v[148:151], v[192:195], v[112:115]
	v_mfma_f32_16x16x32_bf16 v[104:107], v[156:159], v[192:195], v[104:107]
	v_mfma_f32_16x16x32_bf16 v[96:99], v[148:151], v[206:209], v[96:99]
	v_mfma_f32_16x16x32_bf16 v[88:91], v[156:159], v[206:209], v[88:91]
	v_mfma_f32_16x16x32_bf16 v[80:83], v[148:151], v[214:217], v[80:83]
	v_mfma_f32_16x16x32_bf16 v[72:75], v[156:159], v[214:217], v[72:75]
	v_mfma_f32_16x16x32_bf16 v[124:127], v[160:163], v[180:183], v[124:127]
	v_mfma_f32_16x16x32_bf16 v[116:119], v[172:175], v[180:183], v[116:119]
	v_mfma_f32_16x16x32_bf16 v[108:111], v[160:163], v[188:191], v[108:111]
	v_mfma_f32_16x16x32_bf16 v[100:103], v[172:175], v[188:191], v[100:103]
	v_mfma_f32_16x16x32_bf16 v[92:95], v[160:163], v[202:205], v[92:95]
	v_mfma_f32_16x16x32_bf16 v[84:87], v[172:175], v[202:205], v[84:87]
	v_mfma_f32_16x16x32_bf16 v[76:79], v[160:163], v[210:213], v[76:79]
	v_mfma_f32_16x16x32_bf16 v[68:71], v[172:175], v[210:213], v[68:71]
	v_mfma_f32_16x16x32_bf16 v[124:127], v[168:171], v[184:187], v[124:127]
	v_mfma_f32_16x16x32_bf16 v[116:119], v[176:179], v[184:187], v[116:119]
	v_mfma_f32_16x16x32_bf16 v[108:111], v[168:171], v[192:195], v[108:111]
	v_mfma_f32_16x16x32_bf16 v[100:103], v[176:179], v[192:195], v[100:103]
	v_mfma_f32_16x16x32_bf16 v[92:95], v[168:171], v[206:209], v[92:95]
	v_mfma_f32_16x16x32_bf16 v[84:87], v[176:179], v[206:209], v[84:87]
	v_mfma_f32_16x16x32_bf16 v[76:79], v[168:171], v[214:217], v[76:79]
	v_mfma_f32_16x16x32_bf16 v[68:71], v[176:179], v[214:217], v[68:71]
	s_barrier
; #define PG8_STAGE(bufoff, gbase, voff) do { _Pragma("unroll") for (int _i = 0; _i < 2; ++_i) \
;         __builtin_amdgcn_global_load_lds((const unsigned*)((const char*)(gbase) + (voff)[_i]), (PG8_LAS unsigned*)(lds + (bufoff) + ldsw + _i * 8192), 16, 0, 0); } while (0)
; #define PG8_LDA(dst, b, h) do { _Pragma("unroll") for (int m = 0; m < 4; ++m) _Pragma("unroll") for (int k = 0; k < 2; ++k) dst[m][k] = *(const PG8_LAS bf16x8*)(lds + PG8_SA(b, h) + aoff + m * 2048 + k * 1024); } while (0)
; #define PG8_MMA(ai, bj, At, Bt) do { __builtin_amdgcn_s_setprio(1); _Pragma("unroll") for (int m = 0; m < 4; ++m) _Pragma("unroll") for (int n = 0; n < 2; ++n) _Pragma("unroll") for (int k = 0; k < 2; ++k) \
;         acc[ai][bj][m][n] = __builtin_amdgcn_mfma_f32_16x16x32_bf16(Bt[n][k], At[m][k], acc[ai][bj][m][n], 0, 0, 0); __builtin_amdgcn_s_setprio(0); } while (0)
; #define PG8_WAIT_V(n) asm volatile("s_waitcnt vmcnt(" #n ")" ::: "memory")
; #define PG8_WAIT_L(n) asm volatile("s_waitcnt lgkmcnt(" #n ")" ::: "memory")
; #define PG8_BAR __builtin_amdgcn_s_barrier()
; #define PG8_SCHED __builtin_amdgcn_sched_barrier(0)
; template <class Epi, class Sched, bool ALIGN_EPI = false, bool SP2 = false>
; __device__ __forceinline__ void gemm_phase(PG8_LAS unsigned char* lds, const Gemm g, const Sched& S, const Epi& E) {
;     ...
;             PG8_LDA(At, 0, 1); PG8_STAGE(PG8_SB(0, 0), b2, voffB); PG8_STAGE(PG8_SB(0, 1), b2 + hstep, voffB); PG8_STAGE(PG8_SA(0, 0), a2, voffA);
;             PG8_WAIT_V(8); PG8_WAIT_L(0); PG8_BAR; PG8_MMA(1, 0, At, B0); PG8_MMA(1, 1, At, B1); PG8_BAR; PG8_SCHED;
	v_lshl_add_u64 v[198:199], s[24:25], 0, v[134:135]
	s_add_i32 m0, s35, 0x10000
	ds_read_b128 v[180:183], v166 offset:16384
	ds_read_b128 v[184:187], v166 offset:17408
	ds_read_b128 v[188:191], v166 offset:18432
	ds_read_b128 v[192:195], v166 offset:19456
	ds_read_b128 v[202:205], v166 offset:20480
	ds_read_b128 v[206:209], v166 offset:21504
	ds_read_b128 v[210:213], v166 offset:22528
	ds_read_b128 v[214:217], v166 offset:23552
	global_load_lds_dwordx4 v[198:199], off
	s_add_i32 m0, s35, 0x12000
	s_add_u32 s48, s24, 0x40000
	v_lshl_add_u64 v[218:219], s[24:25], 0, v[0:1]
	s_addc_u32 s49, s25, 0
	global_load_lds_dwordx4 v[218:219], off
	v_lshl_add_u64 v[220:221], s[48:49], 0, v[134:135]
	s_add_i32 m0, s35, 0x14000
	v_lshl_add_u64 v[222:223], s[26:27], 0, v[132:133]
	global_load_lds_dwordx4 v[220:221], off
	s_add_i32 m0, s35, 0x16000
	v_lshl_add_u64 v[220:221], s[48:49], 0, v[0:1]
	global_load_lds_dwordx4 v[220:221], off
	s_mov_b32 m0, s37
	v_lshl_add_u64 v[220:221], s[26:27], 0, v[136:137]
	global_load_lds_dwordx4 v[220:221], off
	s_mov_b32 m0, s38
	s_add_i32 s47, 0, 0x18000
	global_load_lds_dwordx4 v[222:223], off
	s_waitcnt vmcnt(8) lgkmcnt(0)
	s_barrier
	v_mfma_f32_16x16x32_bf16 v[64:67], v[144:147], v[180:183], v[64:67]
	v_mfma_f32_16x16x32_bf16 v[56:59], v[152:155], v[180:183], v[56:59]
	v_mfma_f32_16x16x32_bf16 v[48:51], v[144:147], v[188:191], v[48:51]
	v_mfma_f32_16x16x32_bf16 v[40:43], v[152:155], v[188:191], v[40:43]
	v_mfma_f32_16x16x32_bf16 v[32:35], v[144:147], v[202:205], v[32:35]
	v_mfma_f32_16x16x32_bf16 v[24:27], v[152:155], v[202:205], v[24:27]
	v_mfma_f32_16x16x32_bf16 v[16:19], v[144:147], v[210:213], v[16:19]
	v_mfma_f32_16x16x32_bf16 v[8:11], v[152:155], v[210:213], v[8:11]
	v_mfma_f32_16x16x32_bf16 v[64:67], v[148:151], v[184:187], v[64:67]
	v_mfma_f32_16x16x32_bf16 v[56:59], v[156:159], v[184:187], v[56:59]
	v_mfma_f32_16x16x32_bf16 v[48:51], v[148:151], v[192:195], v[48:51]
	v_mfma_f32_16x16x32_bf16 v[40:43], v[156:159], v[192:195], v[40:43]
	v_mfma_f32_16x16x32_bf16 v[32:35], v[148:151], v[206:209], v[32:35]
	v_mfma_f32_16x16x32_bf16 v[24:27], v[156:159], v[206:209], v[24:27]
	v_mfma_f32_16x16x32_bf16 v[16:19], v[148:151], v[214:217], v[16:19]
	v_mfma_f32_16x16x32_bf16 v[8:11], v[156:159], v[214:217], v[8:11]
	v_mfma_f32_16x16x32_bf16 v[60:63], v[160:163], v[180:183], v[60:63]
	v_mfma_f32_16x16x32_bf16 v[52:55], v[172:175], v[180:183], v[52:55]
	v_mfma_f32_16x16x32_bf16 v[44:47], v[160:163], v[188:191], v[44:47]
	v_mfma_f32_16x16x32_bf16 v[36:39], v[172:175], v[188:191], v[36:39]
	v_mfma_f32_16x16x32_bf16 v[28:31], v[160:163], v[202:205], v[28:31]
	v_mfma_f32_16x16x32_bf16 v[20:23], v[172:175], v[202:205], v[20:23]
	v_mfma_f32_16x16x32_bf16 v[12:15], v[160:163], v[210:213], v[12:15]
	v_mfma_f32_16x16x32_bf16 v[4:7], v[172:175], v[210:213], v[4:7]
	v_mfma_f32_16x16x32_bf16 v[60:63], v[168:171], v[184:187], v[60:63]
	v_mfma_f32_16x16x32_bf16 v[52:55], v[176:179], v[184:187], v[52:55]
	v_mfma_f32_16x16x32_bf16 v[44:47], v[168:171], v[192:195], v[44:47]
	v_mfma_f32_16x16x32_bf16 v[36:39], v[176:179], v[192:195], v[36:39]
	v_mfma_f32_16x16x32_bf16 v[28:31], v[168:171], v[206:209], v[28:31]
	v_mfma_f32_16x16x32_bf16 v[20:23], v[176:179], v[206:209], v[20:23]
	v_mfma_f32_16x16x32_bf16 v[12:15], v[168:171], v[214:217], v[12:15]
	v_mfma_f32_16x16x32_bf16 v[4:7], v[176:179], v[214:217], v[4:7]
	s_barrier
; #define PG8_STAGE(bufoff, gbase, voff) do { _Pragma("unroll") for (int _i = 0; _i < 2; ++_i) \
;         __builtin_amdgcn_global_load_lds((const unsigned*)((const char*)(gbase) + (voff)[_i]), (PG8_LAS unsigned*)(lds + (bufoff) + ldsw + _i * 8192), 16, 0, 0); } while (0)
; #define PG8_LDA(dst, b, h) do { _Pragma("unroll") for (int m = 0; m < 4; ++m) _Pragma("unroll") for (int k = 0; k < 2; ++k) dst[m][k] = *(const PG8_LAS bf16x8*)(lds + PG8_SA(b, h) + aoff + m * 2048 + k * 1024); } while (0)
; #define PG8_LDB(dst, b, h) do { _Pragma("unroll") for (int n = 0; n < 2; ++n) _Pragma("unroll") for (int k = 0; k < 2; ++k) dst[n][k] = *(const PG8_LAS bf16x8*)(lds + PG8_SB(b, h) + boff + n * 2048 + k * 1024); } while (0)
; #define PG8_MMA(ai, bj, At, Bt) do { __builtin_amdgcn_s_setprio(1); _Pragma("unroll") for (int m = 0; m < 4; ++m) _Pragma("unroll") for (int n = 0; n < 2; ++n) _Pragma("unroll") for (int k = 0; k < 2; ++k) \
;         acc[ai][bj][m][n] = __builtin_amdgcn_mfma_f32_16x16x32_bf16(Bt[n][k], At[m][k], acc[ai][bj][m][n], 0, 0, 0); __builtin_amdgcn_s_setprio(0); } while (0)
; #define PG8_WAIT_V(n) asm volatile("s_waitcnt vmcnt(" #n ")" ::: "memory")
; #define PG8_WAIT_L(n) asm volatile("s_waitcnt lgkmcnt(" #n ")" ::: "memory")
; #define PG8_BAR __builtin_amdgcn_s_barrier()
; #define PG8_SCHED __builtin_amdgcn_sched_barrier(0)
; template <class Epi, class Sched, bool ALIGN_EPI = false, bool SP2 = false>
; __device__ __forceinline__ void gemm_phase(PG8_LAS unsigned char* lds, const Gemm g, const Sched& S, const Epi& E) {
;     ...
;             PG8_LDB(B0, 1, 0); PG8_LDB(B1, 1, 1); PG8_SCHED; PG8_LDA(At, 1, 0); PG8_STAGE(PG8_SA(0, 1), a2 + hstep, voffA);
;             PG8_WAIT_V(8); PG8_WAIT_L(0); PG8_BAR; PG8_MMA(0, 0, At, B0); PG8_MMA(0, 1, At, B1); PG8_BAR; PG8_SCHED;
;             PG8_LDA(At, 1, 1); PG8_STAGE(PG8_SB(1, 0), b3, voffB); PG8_STAGE(PG8_SB(1, 1), b3 + hstep, voffB); PG8_STAGE(PG8_SA(1, 0), a3, voffA);
;             PG8_WAIT_V(8); PG8_WAIT_L(0); PG8_BAR; PG8_MMA(1, 0, At, B0); PG8_MMA(1, 1, At, B1); PG8_BAR; PG8_SCHED;
;     ...
;         if constexpr (ALIGN_EPI) { if (wr == 0) PG8_BAR; }
.Lkmid_2:
	ds_read_b128 v[144:147], v164 offset:32768
	ds_read_b128 v[148:151], v164 offset:33792
	ds_read_b128 v[152:155], v164 offset:34816
	ds_read_b128 v[156:159], v164 offset:35840
	ds_read_b128 v[160:163], v164 offset:49152
	ds_read_b128 v[168:171], v164 offset:50176
	ds_read_b128 v[172:175], v164 offset:51200
	ds_read_b128 v[176:179], v164 offset:52224
	s_add_u32 s26, s26, 0x40000
	s_addc_u32 s27, s27, 0
	s_mov_b32 m0, s39
	v_lshl_add_u64 v[224:225], s[26:27], 0, v[136:137]
	ds_read_b128 v[180:183], v166 offset:32768
	ds_read_b128 v[184:187], v166 offset:33792
	ds_read_b128 v[188:191], v166 offset:34816
	ds_read_b128 v[192:195], v166 offset:35840
	ds_read_b128 v[202:205], v166 offset:36864
	ds_read_b128 v[206:209], v166 offset:37888
	ds_read_b128 v[210:213], v166 offset:38912
	ds_read_b128 v[214:217], v166 offset:39936
	global_load_lds_dwordx4 v[224:225], off
	s_mov_b32 m0, s40
	v_lshl_add_u64 v[224:225], s[26:27], 0, v[132:133]
	global_load_lds_dwordx4 v[224:225], off
	s_waitcnt vmcnt(8) lgkmcnt(0)
	s_barrier
	v_mfma_f32_16x16x32_bf16 v[128:131], v[144:147], v[180:183], v[128:131]
	v_mfma_f32_16x16x32_bf16 v[120:123], v[152:155], v[180:183], v[120:123]
	v_mfma_f32_16x16x32_bf16 v[112:115], v[144:147], v[188:191], v[112:115]
	v_mfma_f32_16x16x32_bf16 v[104:107], v[152:155], v[188:191], v[104:107]
	v_mfma_f32_16x16x32_bf16 v[96:99], v[144:147], v[202:205], v[96:99]
	v_mfma_f32_16x16x32_bf16 v[88:91], v[152:155], v[202:205], v[88:91]
	v_mfma_f32_16x16x32_bf16 v[80:83], v[144:147], v[210:213], v[80:83]
	v_mfma_f32_16x16x32_bf16 v[72:75], v[152:155], v[210:213], v[72:75]
	v_mfma_f32_16x16x32_bf16 v[128:131], v[148:151], v[184:187], v[128:131]
	v_mfma_f32_16x16x32_bf16 v[120:123], v[156:159], v[184:187], v[120:123]
	v_mfma_f32_16x16x32_bf16 v[112:115], v[148:151], v[192:195], v[112:115]
	v_mfma_f32_16x16x32_bf16 v[104:107], v[156:159], v[192:195], v[104:107]
	v_mfma_f32_16x16x32_bf16 v[96:99], v[148:151], v[206:209], v[96:99]
	v_mfma_f32_16x16x32_bf16 v[88:91], v[156:159], v[206:209], v[88:91]
	v_mfma_f32_16x16x32_bf16 v[80:83], v[148:151], v[214:217], v[80:83]
	v_mfma_f32_16x16x32_bf16 v[72:75], v[156:159], v[214:217], v[72:75]
	v_mfma_f32_16x16x32_bf16 v[124:127], v[160:163], v[180:183], v[124:127]
	v_mfma_f32_16x16x32_bf16 v[116:119], v[172:175], v[180:183], v[116:119]
	v_mfma_f32_16x16x32_bf16 v[108:111], v[160:163], v[188:191], v[108:111]
	v_mfma_f32_16x16x32_bf16 v[100:103], v[172:175], v[188:191], v[100:103]
	v_mfma_f32_16x16x32_bf16 v[92:95], v[160:163], v[202:205], v[92:95]
	v_mfma_f32_16x16x32_bf16 v[84:87], v[172:175], v[202:205], v[84:87]
	v_mfma_f32_16x16x32_bf16 v[76:79], v[160:163], v[210:213], v[76:79]
	v_mfma_f32_16x16x32_bf16 v[68:71], v[172:175], v[210:213], v[68:71]
	v_mfma_f32_16x16x32_bf16 v[124:127], v[168:171], v[184:187], v[124:127]
	v_mfma_f32_16x16x32_bf16 v[116:119], v[176:179], v[184:187], v[116:119]
	v_mfma_f32_16x16x32_bf16 v[108:111], v[168:171], v[192:195], v[108:111]
	v_mfma_f32_16x16x32_bf16 v[100:103], v[176:179], v[192:195], v[100:103]
	v_mfma_f32_16x16x32_bf16 v[92:95], v[168:171], v[206:209], v[92:95]
	v_mfma_f32_16x16x32_bf16 v[84:87], v[176:179], v[206:209], v[84:87]
	v_mfma_f32_16x16x32_bf16 v[76:79], v[168:171], v[214:217], v[76:79]
	v_mfma_f32_16x16x32_bf16 v[68:71], v[176:179], v[214:217], v[68:71]
	s_barrier
	s_add_i32 m0, s35, 0x17f80
	ds_read_b128 v[180:183], v166 offset:49152
	ds_read_b128 v[184:187], v166 offset:50176
	ds_read_b128 v[188:191], v166 offset:51200
	ds_read_b128 v[192:195], v166 offset:52224
	ds_read_b128 v[202:205], v166 offset:53248
	ds_read_b128 v[206:209], v166 offset:54272
	ds_read_b128 v[210:213], v166 offset:55296
	ds_read_b128 v[214:217], v166 offset:56320
	global_load_lds_dwordx4 v[198:199], off offset:128
	s_add_i32 m0, s35, 0x19f80
	s_add_u32 s24, s24, 0x40080
	s_addc_u32 s25, s25, 0
	global_load_lds_dwordx4 v[218:219], off offset:128
	s_add_i32 m0, s35, 0x1c000
	v_lshl_add_u64 v[198:199], s[24:25], 0, v[134:135]
	global_load_lds_dwordx4 v[198:199], off
	s_add_i32 m0, s35, 0x1e000
	v_lshl_add_u64 v[198:199], s[24:25], 0, v[0:1]
	global_load_lds_dwordx4 v[198:199], off
	s_add_i32 m0, s41, 0xffffff80
	s_add_u32 s8, s8, 0x100
	s_addc_u32 s9, s9, 0
	global_load_lds_dwordx4 v[220:221], off offset:128
	s_add_i32 m0, s42, 0xffffff80
	s_add_u32 s44, s44, 0x100
	s_addc_u32 s45, s45, 0
	global_load_lds_dwordx4 v[222:223], off offset:128
	s_waitcnt vmcnt(8) lgkmcnt(0)
	s_barrier
	v_mfma_f32_16x16x32_bf16 v[64:67], v[144:147], v[180:183], v[64:67]
	v_mfma_f32_16x16x32_bf16 v[56:59], v[152:155], v[180:183], v[56:59]
	v_mfma_f32_16x16x32_bf16 v[48:51], v[144:147], v[188:191], v[48:51]
	v_mfma_f32_16x16x32_bf16 v[40:43], v[152:155], v[188:191], v[40:43]
	v_mfma_f32_16x16x32_bf16 v[32:35], v[144:147], v[202:205], v[32:35]
	v_mfma_f32_16x16x32_bf16 v[24:27], v[152:155], v[202:205], v[24:27]
	v_mfma_f32_16x16x32_bf16 v[16:19], v[144:147], v[210:213], v[16:19]
	v_mfma_f32_16x16x32_bf16 v[8:11], v[152:155], v[210:213], v[8:11]
	v_mfma_f32_16x16x32_bf16 v[64:67], v[148:151], v[184:187], v[64:67]
	v_mfma_f32_16x16x32_bf16 v[56:59], v[156:159], v[184:187], v[56:59]
	v_mfma_f32_16x16x32_bf16 v[48:51], v[148:151], v[192:195], v[48:51]
	v_mfma_f32_16x16x32_bf16 v[40:43], v[156:159], v[192:195], v[40:43]
	v_mfma_f32_16x16x32_bf16 v[32:35], v[148:151], v[206:209], v[32:35]
	v_mfma_f32_16x16x32_bf16 v[24:27], v[156:159], v[206:209], v[24:27]
	v_mfma_f32_16x16x32_bf16 v[16:19], v[148:151], v[214:217], v[16:19]
	v_mfma_f32_16x16x32_bf16 v[8:11], v[156:159], v[214:217], v[8:11]
	v_mfma_f32_16x16x32_bf16 v[60:63], v[160:163], v[180:183], v[60:63]
	v_mfma_f32_16x16x32_bf16 v[52:55], v[172:175], v[180:183], v[52:55]
	v_mfma_f32_16x16x32_bf16 v[44:47], v[160:163], v[188:191], v[44:47]
	v_mfma_f32_16x16x32_bf16 v[36:39], v[172:175], v[188:191], v[36:39]
	v_mfma_f32_16x16x32_bf16 v[28:31], v[160:163], v[202:205], v[28:31]
	v_mfma_f32_16x16x32_bf16 v[20:23], v[172:175], v[202:205], v[20:23]
	v_mfma_f32_16x16x32_bf16 v[12:15], v[160:163], v[210:213], v[12:15]
	v_mfma_f32_16x16x32_bf16 v[4:7], v[172:175], v[210:213], v[4:7]
	v_mfma_f32_16x16x32_bf16 v[60:63], v[168:171], v[184:187], v[60:63]
	v_mfma_f32_16x16x32_bf16 v[52:55], v[176:179], v[184:187], v[52:55]
	v_mfma_f32_16x16x32_bf16 v[44:47], v[168:171], v[192:195], v[44:47]
	v_mfma_f32_16x16x32_bf16 v[36:39], v[176:179], v[192:195], v[36:39]
	v_mfma_f32_16x16x32_bf16 v[28:31], v[168:171], v[206:209], v[28:31]
	v_mfma_f32_16x16x32_bf16 v[20:23], v[176:179], v[206:209], v[20:23]
	v_mfma_f32_16x16x32_bf16 v[12:15], v[168:171], v[214:217], v[12:15]
	v_mfma_f32_16x16x32_bf16 v[4:7], v[176:179], v[214:217], v[4:7]
	s_barrier
	s_add_i32 s46, s46, 2
	s_cmp_gt_u32 s46, 13
	s_cbranch_scc0 .LBB0_405
	s_and_b64 vcc, exec, s[14:15]
	s_cbranch_vccz .LBB0_408
	s_barrier

; #define PG8_WAIT_V(n) asm volatile("s_waitcnt vmcnt(" #n ")" ::: "memory")
; #define PG8_BAR __builtin_amdgcn_s_barrier()
; template <class Epi, class Sched, bool ALIGN_EPI = false, bool SP2 = false>
; __device__ __forceinline__ void gemm_phase(PG8_LAS unsigned char* lds, const Gemm g, const Sched& S, const Epi& E) {
;     ...
;     PG8_WAIT_V(0);
;     if constexpr (!ALIGN_EPI) { if (wr == 0) PG8_BAR; }
;     PG8_BAR;
; __device__ __forceinline__ void xcd_barrier(const XcdBarrier& b) {
;     asm volatile("s_waitcnt vmcnt(0)" ::: "memory");
;     __syncthreads();
;     if (threadIdx.x == 0) {
;         unsigned* bar = b.bar; unsigned bx_ = b.x;
;         asm volatile("" : "+s"(bar), "+s"(bx_));
;         __builtin_amdgcn_s_waitcnt(0);
;         unsigned nloc = b.st[0], nx = b.st[1];
;         if (nloc == 0u) { xcd_barrier_complete(bar, bx_, nloc, nx); b.st[0] = nloc; b.st[1] = nx; }
.LBB0_412:
	s_setprio 0
	s_waitcnt vmcnt(0)
	s_barrier
	s_and_saveexec_b64 s[36:37], s[62:63]
	s_cbranch_execz .LBB0_456
	s_mov_b64 s[38:39], s[58:59]
	s_mov_b32 s3, s99
	v_mov_b32_e32 v0, s70
	s_waitcnt vmcnt(0) expcnt(0) lgkmcnt(0)
	ds_read_b32 v4, v0
	v_mov_b32_e32 v0, s71
	ds_read_b32 v0, v0
	s_waitcnt lgkmcnt(1)
	v_cmp_ne_u32_e32 vcc, 0, v4
	s_cbranch_vccnz .LBB0_427
	s_add_u32 s4, s38, 0x1000
	s_addc_u32 s5, s39, 0
	s_add_u32 s6, s38, 0x1100
	s_addc_u32 s7, s39, 0
	s_add_u32 s8, s38, 0x1200
	s_addc_u32 s9, s39, 0
	s_add_u32 s10, s38, 0x1300
	s_addc_u32 s11, s39, 0
	s_mov_b32 s30, 1
	s_mov_b64 s[12:13], 0
	s_branch .LBB0_417

; __device__ __forceinline__ int opaque_tid() { int t = (int)threadIdx.x; asm volatile("" : "+v"(t)); return t; }
; #define PG8_STAGE(bufoff, gbase, voff) do { _Pragma("unroll") for (int _i = 0; _i < 2; ++_i) \
;         __builtin_amdgcn_global_load_lds((const unsigned*)((const char*)(gbase) + (voff)[_i]), (PG8_LAS unsigned*)(lds + (bufoff) + ldsw + _i * 8192), 16, 0, 0); } while (0)
; template <class Epi, class Sched, bool ALIGN_EPI = false, bool SP2 = false>
; __device__ __forceinline__ void gemm_phase(PG8_LAS unsigned char* lds, const Gemm g, const Sched& S, const Epi& E) {
;     const int tid = opaque_tid(), wid = __builtin_amdgcn_readfirstlane(tid >> 6), lane = tid & 63, wr = wid >> 2, wc = wid & 3, fr = lane & 15, fq = lane >> 4;
;     const int K = g.K, nt = K / BK;
;     unsigned voffA[2], voffB[2];
; #pragma unroll
;     for (int i = 0; i < 2; ++i) { int R, C; stage_rc(tid * 16 + i * 8192, R, C); const int Rb = Epi::PERM ? ((R & ~31) + perm32(R & 31)) : R;
;         voffA[i] = (unsigned)(R * K + C) * 2u; voffB[i] = (unsigned)(Rb * K + C) * 2u; }
;     const size_t kstep = (size_t)(BK * 2);
;     const size_t hstep = (size_t)HALF * K * 2;
;     const size_t tstep = 2 * hstep;
;     const unsigned ldsw = (unsigned)wid * 1024u;
;     const int aoff = lds_byte(wr * 64 + fr, fq * 8), boff = lds_byte(wc * 32 + fr, fq * 8);
;     ...
;     const char* cA = (const char*)g.A + (size_t)cur.pm * tstep; const char* cB = (const char*)g.Bt + (size_t)cur.pn * tstep;
;     S.a_ready(cur);
;     if constexpr (SP2) {
;         PG8_STAGE(PG8_SB(0, 0), cB, voffB); PG8_STAGE(PG8_SB(0, 1), cB + hstep, voffB); PG8_STAGE(PG8_SA(0, 0), cA, voffA); PG8_STAGE(PG8_SA(0, 1), cA + hstep, voffA);
;         if (wr == 1) PG8_BAR;
;         PG8_WAIT_V(2); PG8_BAR;
;         PG8_STAGE(PG8_SB(1, 0), cB + kstep, voffB); PG8_STAGE(PG8_SA(1, 0), cA + kstep, voffA); PG8_STAGE(PG8_SB(1, 1), cB + hstep + kstep, voffB);
;         PG8_WAIT_V(6); PG8_BAR;
;     } else {
;         PG8_STAGE(PG8_SB(0, 0), cB, voffB); PG8_STAGE(PG8_SA(0, 0), cA, voffA); PG8_STAGE(PG8_SB(0, 1), cB + hstep, voffB); PG8_STAGE(PG8_SA(0, 1), cA + hstep, voffA);
;         if (wr == 1) PG8_BAR;
;         PG8_WAIT_V(4); PG8_BAR;
;         PG8_STAGE(PG8_SB(1, 0), cB + kstep, voffB); PG8_STAGE(PG8_SA(1, 0), cA + kstep, voffA); PG8_STAGE(PG8_SB(1, 1), cB + hstep + kstep, voffB);
;         PG8_WAIT_V(6); PG8_BAR;
;     }
.LBB0_466:
	s_add_u32 s18, s14, 0x6400000
	s_addc_u32 s19, s15, 0
	s_add_u32 s14, s14, 0x1a400000
	s_addc_u32 s15, s15, 0
	s_and_b32 s46, s5, 3
	s_add_i32 m0, s40, 0x18000
	v_lshl_add_u64 v[10:11], v[10:11], 0, s[82:83]
	s_lshl_b32 s5, s4, 13
	s_lshl_b32 s9, s46, 12
	s_waitcnt vmcnt(2)
	s_barrier
	global_load_lds_dwordx4 v[10:11], off
	v_lshl_add_u64 v[8:9], v[8:9], 0, s[82:83]
	s_add_i32 m0, s40, 0x1a000
	s_add_i32 s47, s40, 0x8000
	s_add_i32 s48, s40, 0xa000
	global_load_lds_dwordx4 v[8:9], off
	v_lshl_add_u64 v[4:5], v[4:5], 0, s[82:83]
	s_mov_b32 m0, s47
	s_add_u32 s6, s28, 0xb0080
	global_load_lds_dwordx4 v[4:5], off
	v_lshl_add_u64 v[4:5], v[6:7], 0, s[82:83]
	s_mov_b32 m0, s48
	s_addc_u32 s7, s29, 0
	global_load_lds_dwordx4 v[4:5], off
	s_add_i32 m0, s40, 0x1c000
	v_lshl_add_u64 v[4:5], s[6:7], 0, v[192:193]
	global_load_lds_dwordx4 v[4:5], off
	v_lshl_add_u64 v[4:5], s[6:7], 0, v[202:203]
	s_add_i32 m0, s40, 0x1e000
	s_mov_b32 s1, 0xb000
	global_load_lds_dwordx4 v[4:5], off
	v_bfe_u32 v4, v12, 4, 2
	v_and_b32_e32 v5, 15, v12
	v_lshlrev_b32_e32 v7, 4, v4
	v_lshl_or_b32 v3, s4, 6, v5
	v_lshl_or_b32 v5, v5, 6, v7
	v_lshlrev_b32_e32 v7, 2, v12
	v_and_b32_e32 v7, 32, v7
	v_lshlrev_b32_e32 v6, 3, v4
	v_bitop3_b32 v8, v5, s5, v7 bitop3:0xde
	v_bitop3_b32 v234, v5, s9, v7 bitop3:0xde
	v_add_u32_e32 v234, 0x10000, v234
	v_cmp_eq_u32_e64 s[4:5], 0, v4
	v_lshrrev_b32_e32 v5, 1, v13
	v_mul_lo_u32 v4, v15, s77
	v_mad_u64_u32 v[4:5], s[6:7], v5, s1, v[4:5]
	v_or_b32_e32 v4, v4, v14
	s_cmpk_lt_u32 s8, 0x100
	v_add_lshl_u32 v4, v4, v16, 1
	v_mov_b32_e32 v5, v2
	s_mov_b64 s[8:9], 0xb0080
	v_lshl_add_u64 v[204:205], v[4:5], 0, s[8:9]
	v_lshrrev_b32_e32 v5, 1, v17
	v_mul_lo_u32 v4, v19, s77
	v_mad_u64_u32 v[4:5], s[6:7], v5, s1, v[4:5]
	s_waitcnt vmcnt(6)
	v_or_b32_e32 v4, v4, v18
	v_add_lshl_u32 v4, v4, v20, 1
	v_mov_b32_e32 v5, v2
	v_lshl_or_b32 v235, s46, 5, v6
	s_cselect_b64 s[20:21], -1, 0
	s_mov_b32 s72, 0
	s_ashr_i32 s49, s34, 31
	v_lshl_add_u64 v[206:207], v[4:5], 0, s[8:9]
	v_add_u32_e32 v236, 0, v8
	s_waitcnt vmcnt(0)
	s_barrier
	v_readfirstlane_b32 s100, v197
	s_cmp_lt_u32 s100, 0x100
	s_cbranch_scc1 .Lsp_3
	s_setprio 1
.Lsp_3:
	s_branch .LBB0_469
.LBB0_467:
	s_mov_b64 s[6:7], 0

; #define PG8_STAGE(bufoff, gbase, voff) do { _Pragma("unroll") for (int _i = 0; _i < 2; ++_i) \
;         __builtin_amdgcn_global_load_lds((const unsigned*)((const char*)(gbase) + (voff)[_i]), (PG8_LAS unsigned*)(lds + (bufoff) + ldsw + _i * 8192), 16, 0, 0); } while (0)
; #define PG8_LDA(dst, b, h) do { _Pragma("unroll") for (int m = 0; m < 4; ++m) _Pragma("unroll") for (int k = 0; k < 2; ++k) dst[m][k] = *(const PG8_LAS bf16x8*)(lds + PG8_SA(b, h) + aoff + m * 2048 + k * 1024); } while (0)
; #define PG8_LDB(dst, b, h) do { _Pragma("unroll") for (int n = 0; n < 2; ++n) _Pragma("unroll") for (int k = 0; k < 2; ++k) dst[n][k] = *(const PG8_LAS bf16x8*)(lds + PG8_SB(b, h) + boff + n * 2048 + k * 1024); } while (0)
; #define PG8_WAIT_V(n) asm volatile("s_waitcnt vmcnt(" #n ")" ::: "memory")
; #define PG8_WAIT_L(n) asm volatile("s_waitcnt lgkmcnt(" #n ")" ::: "memory")
; #define PG8_BAR __builtin_amdgcn_s_barrier()
; #define PG8_SCHED __builtin_amdgcn_sched_barrier(0)
; template <class Epi, class Sched, bool ALIGN_EPI = false, bool SP2 = false>
; __device__ __forceinline__ void gemm_phase(PG8_LAS unsigned char* lds, const Gemm g, const Sched& S, const Epi& E) {
;     ...
;         const bool has_next = S.next(ui + 1, nxt);
;         const char* nA = has_next ? (const char*)g.A + (size_t)nxt.pm * tstep : cA; const char* nB = has_next ? (const char*)g.Bt + (size_t)nxt.pn * tstep : cB;
;         for (int t = 0; t < nt; t += 2) {
;             const bool last = (t == nt - 2);
;             const char* a1 = cA + (size_t)(t + 1) * kstep;
;             const char* a2 = last ? nA : cA + (size_t)(t + 2) * kstep; const char* b2 = last ? nB : cB + (size_t)(t + 2) * kstep;
;             const char* a3 = a2 + kstep; const char* b3 = b2 + kstep;
;             if (last && has_next) S.a_ready(nxt);
;             if constexpr (SP2) {
;             PG8_LDB(B0, 0, 0); PG8_LDB(B1, 0, 1); PG8_SCHED; PG8_LDA(At, 0, 0); PG8_STAGE(PG8_SA(1, 1), a1 + hstep, voffA);
;             PG8_WAIT_V(8); PG8_WAIT_L(0); PG8_BAR; PG8_MMA(0, 0, At, B0); PG8_MMA(0, 1, At, B1); PG8_BAR; PG8_SCHED;
;             PG8_LDA(At, 0, 1); PG8_STAGE(PG8_SB(0, 0), b2, voffB); PG8_STAGE(PG8_SB(0, 1), b2 + hstep, voffB); PG8_STAGE(PG8_SA(0, 0), a2, voffA);
;             PG8_WAIT_V(8); PG8_WAIT_L(0); PG8_BAR; PG8_MMA(1, 0, At, B0); PG8_MMA(1, 1, At, B1); PG8_BAR; PG8_SCHED;
.LBB0_479:
	s_add_u32 s44, s28, 0x100
	s_addc_u32 s45, s29, 0
	s_mov_b32 s53, -2
	s_add_u32 s8, s26, 0x100
	s_addc_u32 s9, s27, 0
	s_cmp_eq_u32 s53, 40
	s_cselect_b32 s31, s23, s9
	s_cselect_b32 s30, s22, s8
	s_cselect_b32 s29, s25, s45
	s_cselect_b32 s28, s24, s44
	ds_read_b128 v[68:71], v234
	ds_read_b128 v[80:83], v234 offset:1024
	ds_read_b128 v[92:95], v234 offset:2048
	ds_read_b128 v[100:103], v234 offset:3072
	ds_read_b128 v[112:115], v234 offset:16384
	ds_read_b128 v[120:123], v234 offset:17408
	ds_read_b128 v[132:135], v234 offset:18432
	ds_read_b128 v[144:147], v234 offset:19456
	v_lshl_add_u64 v[198:199], s[26:27], 0, v[204:205]
	s_add_i32 m0, s40, 0xc000
	ds_read_b128 v[156:159], v236
	ds_read_b128 v[168:171], v236 offset:1024
	ds_read_b128 v[172:175], v236 offset:2048
	ds_read_b128 v[176:179], v236 offset:3072
	ds_read_b128 v[180:183], v236 offset:4096
	ds_read_b128 v[184:187], v236 offset:5120
	ds_read_b128 v[188:191], v236 offset:6144
	ds_read_b128 v[208:211], v236 offset:7168
	global_load_lds_dwordx4 v[198:199], off
	s_add_i32 m0, s40, 0xe000
	v_lshl_add_u64 v[198:199], s[26:27], 0, v[206:207]
	global_load_lds_dwordx4 v[198:199], off
	s_waitcnt vmcnt(8) lgkmcnt(0)
	s_barrier
	v_mfma_f32_16x16x32_bf16 v[164:167], v[68:71], v[156:159], 0
	v_mfma_f32_16x16x32_bf16 v[160:163], v[92:95], v[156:159], 0
	v_mfma_f32_16x16x32_bf16 v[140:143], v[68:71], v[172:175], 0
	v_mfma_f32_16x16x32_bf16 v[136:139], v[92:95], v[172:175], 0
	v_mfma_f32_16x16x32_bf16 v[116:119], v[68:71], v[180:183], 0
	v_mfma_f32_16x16x32_bf16 v[108:111], v[92:95], v[180:183], 0
	v_mfma_f32_16x16x32_bf16 v[88:91], v[68:71], v[188:191], 0
	v_mfma_f32_16x16x32_bf16 v[84:87], v[92:95], v[188:191], 0
	v_mfma_f32_16x16x32_bf16 v[164:167], v[80:83], v[168:171], v[164:167]
	v_mfma_f32_16x16x32_bf16 v[160:163], v[100:103], v[168:171], v[160:163]
	v_mfma_f32_16x16x32_bf16 v[140:143], v[80:83], v[176:179], v[140:143]
	v_mfma_f32_16x16x32_bf16 v[136:139], v[100:103], v[176:179], v[136:139]
	v_mfma_f32_16x16x32_bf16 v[116:119], v[80:83], v[184:187], v[116:119]
	v_mfma_f32_16x16x32_bf16 v[108:111], v[100:103], v[184:187], v[108:111]
	v_mfma_f32_16x16x32_bf16 v[88:91], v[80:83], v[208:211], v[88:91]
	v_mfma_f32_16x16x32_bf16 v[84:87], v[100:103], v[208:211], v[84:87]
	v_mfma_f32_16x16x32_bf16 v[152:155], v[112:115], v[156:159], 0
	v_mfma_f32_16x16x32_bf16 v[148:151], v[132:135], v[156:159], 0
	v_mfma_f32_16x16x32_bf16 v[128:131], v[112:115], v[172:175], 0
	v_mfma_f32_16x16x32_bf16 v[124:127], v[132:135], v[172:175], 0
	v_mfma_f32_16x16x32_bf16 v[104:107], v[112:115], v[180:183], 0
	v_mfma_f32_16x16x32_bf16 v[96:99], v[132:135], v[180:183], 0
	v_mfma_f32_16x16x32_bf16 v[76:79], v[112:115], v[188:191], 0
	v_mfma_f32_16x16x32_bf16 v[72:75], v[132:135], v[188:191], 0
	v_mfma_f32_16x16x32_bf16 v[152:155], v[120:123], v[168:171], v[152:155]
	v_mfma_f32_16x16x32_bf16 v[148:151], v[144:147], v[168:171], v[148:151]
	v_mfma_f32_16x16x32_bf16 v[128:131], v[120:123], v[176:179], v[128:131]
	v_mfma_f32_16x16x32_bf16 v[124:127], v[144:147], v[176:179], v[124:127]
	v_mfma_f32_16x16x32_bf16 v[104:107], v[120:123], v[184:187], v[104:107]
	v_mfma_f32_16x16x32_bf16 v[96:99], v[144:147], v[184:187], v[96:99]
	v_mfma_f32_16x16x32_bf16 v[76:79], v[120:123], v[208:211], v[76:79]
	v_mfma_f32_16x16x32_bf16 v[72:75], v[144:147], v[208:211], v[72:75]
	s_barrier
	v_lshl_add_u64 v[198:199], s[28:29], 0, v[192:193]
	s_add_i32 m0, s39, 0x10000
	ds_read_b128 v[156:159], v236 offset:16384
	ds_read_b128 v[168:171], v236 offset:17408
	ds_read_b128 v[172:175], v236 offset:18432
	ds_read_b128 v[176:179], v236 offset:19456
	ds_read_b128 v[180:183], v236 offset:20480
	ds_read_b128 v[184:187], v236 offset:21504
	ds_read_b128 v[188:191], v236 offset:22528
	ds_read_b128 v[208:211], v236 offset:23552
	global_load_lds_dwordx4 v[198:199], off
	s_add_i32 m0, s39, 0x12000
	s_add_u32 s26, s28, 0xb0000
	v_lshl_add_u64 v[212:213], s[28:29], 0, v[202:203]
	s_addc_u32 s27, s29, 0
	global_load_lds_dwordx4 v[212:213], off
	v_lshl_add_u64 v[214:215], s[26:27], 0, v[192:193]
	s_add_i32 m0, s39, 0x14000
	v_lshl_add_u64 v[216:217], s[30:31], 0, v[194:195]
	global_load_lds_dwordx4 v[214:215], off
	s_add_i32 m0, s39, 0x16000
	v_lshl_add_u64 v[214:215], s[26:27], 0, v[202:203]
	global_load_lds_dwordx4 v[214:215], off
	s_mov_b32 m0, s40
	v_lshl_add_u64 v[214:215], s[30:31], 0, v[0:1]
	global_load_lds_dwordx4 v[214:215], off
	s_mov_b32 m0, s41
	s_add_i32 s54, 0, 0x18000
	global_load_lds_dwordx4 v[216:217], off
	s_waitcnt vmcnt(8) lgkmcnt(0)
	s_barrier
	v_mfma_f32_16x16x32_bf16 v[64:67], v[68:71], v[156:159], 0
	v_mfma_f32_16x16x32_bf16 v[60:63], v[92:95], v[156:159], 0
	v_mfma_f32_16x16x32_bf16 v[48:51], v[68:71], v[172:175], 0
	v_mfma_f32_16x16x32_bf16 v[44:47], v[92:95], v[172:175], 0
	v_mfma_f32_16x16x32_bf16 v[32:35], v[68:71], v[180:183], 0
	v_mfma_f32_16x16x32_bf16 v[28:31], v[92:95], v[180:183], 0
	v_mfma_f32_16x16x32_bf16 v[16:19], v[68:71], v[188:191], 0
	v_mfma_f32_16x16x32_bf16 v[12:15], v[92:95], v[188:191], 0
	v_mfma_f32_16x16x32_bf16 v[64:67], v[80:83], v[168:171], v[64:67]
	v_mfma_f32_16x16x32_bf16 v[60:63], v[100:103], v[168:171], v[60:63]
	v_mfma_f32_16x16x32_bf16 v[48:51], v[80:83], v[176:179], v[48:51]
	v_mfma_f32_16x16x32_bf16 v[44:47], v[100:103], v[176:179], v[44:47]
	v_mfma_f32_16x16x32_bf16 v[32:35], v[80:83], v[184:187], v[32:35]
	v_mfma_f32_16x16x32_bf16 v[28:31], v[100:103], v[184:187], v[28:31]
	v_mfma_f32_16x16x32_bf16 v[16:19], v[80:83], v[208:211], v[16:19]
	v_mfma_f32_16x16x32_bf16 v[12:15], v[100:103], v[208:211], v[12:15]
	v_mfma_f32_16x16x32_bf16 v[56:59], v[112:115], v[156:159], 0
	v_mfma_f32_16x16x32_bf16 v[52:55], v[132:135], v[156:159], 0
	v_mfma_f32_16x16x32_bf16 v[40:43], v[112:115], v[172:175], 0
	v_mfma_f32_16x16x32_bf16 v[36:39], v[132:135], v[172:175], 0
	v_mfma_f32_16x16x32_bf16 v[24:27], v[112:115], v[180:183], 0
	v_mfma_f32_16x16x32_bf16 v[20:23], v[132:135], v[180:183], 0
	v_mfma_f32_16x16x32_bf16 v[8:11], v[112:115], v[188:191], 0
	v_mfma_f32_16x16x32_bf16 v[4:7], v[132:135], v[188:191], 0
	v_mfma_f32_16x16x32_bf16 v[56:59], v[120:123], v[168:171], v[56:59]
	v_mfma_f32_16x16x32_bf16 v[52:55], v[144:147], v[168:171], v[52:55]
	v_mfma_f32_16x16x32_bf16 v[40:43], v[120:123], v[176:179], v[40:43]
	v_mfma_f32_16x16x32_bf16 v[36:39], v[144:147], v[176:179], v[36:39]
	v_mfma_f32_16x16x32_bf16 v[24:27], v[120:123], v[184:187], v[24:27]
	v_mfma_f32_16x16x32_bf16 v[20:23], v[144:147], v[184:187], v[20:23]
	v_mfma_f32_16x16x32_bf16 v[8:11], v[120:123], v[208:211], v[8:11]
	v_mfma_f32_16x16x32_bf16 v[4:7], v[144:147], v[208:211], v[4:7]
	s_barrier
	s_branch .Lkmid_3
; #define PG8_STAGE(bufoff, gbase, voff) do { _Pragma("unroll") for (int _i = 0; _i < 2; ++_i) \
;         __builtin_amdgcn_global_load_lds((const unsigned*)((const char*)(gbase) + (voff)[_i]), (PG8_LAS unsigned*)(lds + (bufoff) + ldsw + _i * 8192), 16, 0, 0); } while (0)
; #define PG8_LDA(dst, b, h) do { _Pragma("unroll") for (int m = 0; m < 4; ++m) _Pragma("unroll") for (int k = 0; k < 2; ++k) dst[m][k] = *(const PG8_LAS bf16x8*)(lds + PG8_SA(b, h) + aoff + m * 2048 + k * 1024); } while (0)
; #define PG8_LDB(dst, b, h) do { _Pragma("unroll") for (int n = 0; n < 2; ++n) _Pragma("unroll") for (int k = 0; k < 2; ++k) dst[n][k] = *(const PG8_LAS bf16x8*)(lds + PG8_SB(b, h) + boff + n * 2048 + k * 1024); } while (0)
; template <class Epi, class Sched, bool ALIGN_EPI = false, bool SP2 = false>
; __device__ __forceinline__ void gemm_phase(PG8_LAS unsigned char* lds, const Gemm g, const Sched& S, const Epi& E) {
;     ...
;         for (int t = 0; t < nt; t += 2) {
;             const bool last = (t == nt - 2);
;             const char* a1 = cA + (size_t)(t + 1) * kstep;
;             const char* a2 = last ? nA : cA + (size_t)(t + 2) * kstep; const char* b2 = last ? nB : cB + (size_t)(t + 2) * kstep;
;             const char* a3 = a2 + kstep; const char* b3 = b2 + kstep;
;             if (last && has_next) S.a_ready(nxt);
;             if constexpr (SP2) {
;             PG8_LDB(B0, 0, 0); PG8_LDB(B1, 0, 1); PG8_SCHED; PG8_LDA(At, 0, 0); PG8_STAGE(PG8_SA(1, 1), a1 + hstep, voffA);
;             PG8_WAIT_V(8); PG8_WAIT_L(0); PG8_BAR; PG8_MMA(0, 0, At, B0); PG8_MMA(0, 1, At, B1); PG8_BAR; PG8_SCHED;
;             PG8_LDA(At, 0, 1); PG8_STAGE(PG8_SB(0, 0), b2, voffB); PG8_STAGE(PG8_SB(0, 1), b2 + hstep, voffB); PG8_STAGE(PG8_SA(0, 0), a2, voffA);
;             PG8_WAIT_V(8); PG8_WAIT_L(0); PG8_BAR; PG8_MMA(1, 0, At, B0); PG8_MMA(1, 1, At, B1); PG8_BAR; PG8_SCHED;
;             PG8_LDB(B0, 1, 0); PG8_LDB(B1, 1, 1); PG8_SCHED; PG8_LDA(At, 1, 0); PG8_STAGE(PG8_SA(0, 1), a2 + hstep, voffA);
;             PG8_WAIT_V(8); PG8_WAIT_L(0); PG8_BAR; PG8_MMA(0, 0, At, B0); PG8_MMA(0, 1, At, B1); PG8_BAR; PG8_SCHED;
;             PG8_LDA(At, 1, 1); PG8_STAGE(PG8_SB(1, 0), b3, voffB); PG8_STAGE(PG8_SB(1, 1), b3 + hstep, voffB); PG8_STAGE(PG8_SA(1, 0), a3, voffA);
;             PG8_WAIT_V(8); PG8_WAIT_L(0); PG8_BAR; PG8_MMA(1, 0, At, B0); PG8_MMA(1, 1, At, B1); PG8_BAR; PG8_SCHED;
.LBB0_480:
	s_add_u32 s8, s26, 0x100
	s_addc_u32 s9, s27, 0
	s_cmp_eq_u32 s53, 40
	s_cselect_b32 s31, s23, s9
	s_cselect_b32 s30, s22, s8
	s_cselect_b32 s29, s25, s45
	s_cselect_b32 s28, s24, s44
	ds_read_b128 v[68:71], v234
	ds_read_b128 v[80:83], v234 offset:1024
	ds_read_b128 v[92:95], v234 offset:2048
	ds_read_b128 v[100:103], v234 offset:3072
	ds_read_b128 v[112:115], v234 offset:16384
	ds_read_b128 v[120:123], v234 offset:17408
	ds_read_b128 v[132:135], v234 offset:18432
	ds_read_b128 v[144:147], v234 offset:19456
	v_lshl_add_u64 v[198:199], s[26:27], 0, v[204:205]
	s_add_i32 m0, s40, 0xc000
	ds_read_b128 v[156:159], v236
	ds_read_b128 v[168:171], v236 offset:1024
	ds_read_b128 v[172:175], v236 offset:2048
	ds_read_b128 v[176:179], v236 offset:3072
	ds_read_b128 v[180:183], v236 offset:4096
	ds_read_b128 v[184:187], v236 offset:5120
	ds_read_b128 v[188:191], v236 offset:6144
	ds_read_b128 v[208:211], v236 offset:7168
	global_load_lds_dwordx4 v[198:199], off
	s_add_i32 m0, s40, 0xe000
	v_lshl_add_u64 v[198:199], s[26:27], 0, v[206:207]
	global_load_lds_dwordx4 v[198:199], off
	s_waitcnt vmcnt(8) lgkmcnt(0)
	s_barrier
	v_mfma_f32_16x16x32_bf16 v[164:167], v[68:71], v[156:159], v[164:167]
	v_mfma_f32_16x16x32_bf16 v[160:163], v[92:95], v[156:159], v[160:163]
	v_mfma_f32_16x16x32_bf16 v[140:143], v[68:71], v[172:175], v[140:143]
	v_mfma_f32_16x16x32_bf16 v[136:139], v[92:95], v[172:175], v[136:139]
	v_mfma_f32_16x16x32_bf16 v[116:119], v[68:71], v[180:183], v[116:119]
	v_mfma_f32_16x16x32_bf16 v[108:111], v[92:95], v[180:183], v[108:111]
	v_mfma_f32_16x16x32_bf16 v[88:91], v[68:71], v[188:191], v[88:91]
	v_mfma_f32_16x16x32_bf16 v[84:87], v[92:95], v[188:191], v[84:87]
	v_mfma_f32_16x16x32_bf16 v[164:167], v[80:83], v[168:171], v[164:167]
	v_mfma_f32_16x16x32_bf16 v[160:163], v[100:103], v[168:171], v[160:163]
	v_mfma_f32_16x16x32_bf16 v[140:143], v[80:83], v[176:179], v[140:143]
	v_mfma_f32_16x16x32_bf16 v[136:139], v[100:103], v[176:179], v[136:139]
	v_mfma_f32_16x16x32_bf16 v[116:119], v[80:83], v[184:187], v[116:119]
	v_mfma_f32_16x16x32_bf16 v[108:111], v[100:103], v[184:187], v[108:111]
	v_mfma_f32_16x16x32_bf16 v[88:91], v[80:83], v[208:211], v[88:91]
	v_mfma_f32_16x16x32_bf16 v[84:87], v[100:103], v[208:211], v[84:87]
	v_mfma_f32_16x16x32_bf16 v[152:155], v[112:115], v[156:159], v[152:155]
	v_mfma_f32_16x16x32_bf16 v[148:151], v[132:135], v[156:159], v[148:151]
	v_mfma_f32_16x16x32_bf16 v[128:131], v[112:115], v[172:175], v[128:131]
	v_mfma_f32_16x16x32_bf16 v[124:127], v[132:135], v[172:175], v[124:127]
	v_mfma_f32_16x16x32_bf16 v[104:107], v[112:115], v[180:183], v[104:107]
	v_mfma_f32_16x16x32_bf16 v[96:99], v[132:135], v[180:183], v[96:99]
	v_mfma_f32_16x16x32_bf16 v[76:79], v[112:115], v[188:191], v[76:79]
	v_mfma_f32_16x16x32_bf16 v[72:75], v[132:135], v[188:191], v[72:75]
	v_mfma_f32_16x16x32_bf16 v[152:155], v[120:123], v[168:171], v[152:155]
	v_mfma_f32_16x16x32_bf16 v[148:151], v[144:147], v[168:171], v[148:151]
	v_mfma_f32_16x16x32_bf16 v[128:131], v[120:123], v[176:179], v[128:131]
	v_mfma_f32_16x16x32_bf16 v[124:127], v[144:147], v[176:179], v[124:127]
	v_mfma_f32_16x16x32_bf16 v[104:107], v[120:123], v[184:187], v[104:107]
	v_mfma_f32_16x16x32_bf16 v[96:99], v[144:147], v[184:187], v[96:99]
	v_mfma_f32_16x16x32_bf16 v[76:79], v[120:123], v[208:211], v[76:79]
	v_mfma_f32_16x16x32_bf16 v[72:75], v[144:147], v[208:211], v[72:75]
	s_barrier
	v_lshl_add_u64 v[198:199], s[28:29], 0, v[192:193]
	s_add_i32 m0, s39, 0x10000
	ds_read_b128 v[156:159], v236 offset:16384
	ds_read_b128 v[168:171], v236 offset:17408
	ds_read_b128 v[172:175], v236 offset:18432
	ds_read_b128 v[176:179], v236 offset:19456
	ds_read_b128 v[180:183], v236 offset:20480
	ds_read_b128 v[184:187], v236 offset:21504
	ds_read_b128 v[188:191], v236 offset:22528
	ds_read_b128 v[208:211], v236 offset:23552
	global_load_lds_dwordx4 v[198:199], off
	s_add_i32 m0, s39, 0x12000
	s_add_u32 s26, s28, 0xb0000
	v_lshl_add_u64 v[212:213], s[28:29], 0, v[202:203]
	s_addc_u32 s27, s29, 0
	global_load_lds_dwordx4 v[212:213], off
	v_lshl_add_u64 v[214:215], s[26:27], 0, v[192:193]
	s_add_i32 m0, s39, 0x14000
	v_lshl_add_u64 v[216:217], s[30:31], 0, v[194:195]
	global_load_lds_dwordx4 v[214:215], off
	s_add_i32 m0, s39, 0x16000
	v_lshl_add_u64 v[214:215], s[26:27], 0, v[202:203]
	global_load_lds_dwordx4 v[214:215], off
	s_mov_b32 m0, s40
	v_lshl_add_u64 v[214:215], s[30:31], 0, v[0:1]
	global_load_lds_dwordx4 v[214:215], off
	s_mov_b32 m0, s41
	s_add_i32 s54, 0, 0x18000
	global_load_lds_dwordx4 v[216:217], off
	s_waitcnt vmcnt(8) lgkmcnt(0)
	s_barrier
	v_mfma_f32_16x16x32_bf16 v[64:67], v[68:71], v[156:159], v[64:67]
	v_mfma_f32_16x16x32_bf16 v[60:63], v[92:95], v[156:159], v[60:63]
	v_mfma_f32_16x16x32_bf16 v[48:51], v[68:71], v[172:175], v[48:51]
	v_mfma_f32_16x16x32_bf16 v[44:47], v[92:95], v[172:175], v[44:47]
	v_mfma_f32_16x16x32_bf16 v[32:35], v[68:71], v[180:183], v[32:35]
	v_mfma_f32_16x16x32_bf16 v[28:31], v[92:95], v[180:183], v[28:31]
	v_mfma_f32_16x16x32_bf16 v[16:19], v[68:71], v[188:191], v[16:19]
	v_mfma_f32_16x16x32_bf16 v[12:15], v[92:95], v[188:191], v[12:15]
	v_mfma_f32_16x16x32_bf16 v[64:67], v[80:83], v[168:171], v[64:67]
	v_mfma_f32_16x16x32_bf16 v[60:63], v[100:103], v[168:171], v[60:63]
	v_mfma_f32_16x16x32_bf16 v[48:51], v[80:83], v[176:179], v[48:51]
	v_mfma_f32_16x16x32_bf16 v[44:47], v[100:103], v[176:179], v[44:47]
	v_mfma_f32_16x16x32_bf16 v[32:35], v[80:83], v[184:187], v[32:35]
	v_mfma_f32_16x16x32_bf16 v[28:31], v[100:103], v[184:187], v[28:31]
	v_mfma_f32_16x16x32_bf16 v[16:19], v[80:83], v[208:211], v[16:19]
	v_mfma_f32_16x16x32_bf16 v[12:15], v[100:103], v[208:211], v[12:15]
	v_mfma_f32_16x16x32_bf16 v[56:59], v[112:115], v[156:159], v[56:59]
	v_mfma_f32_16x16x32_bf16 v[52:55], v[132:135], v[156:159], v[52:55]
	v_mfma_f32_16x16x32_bf16 v[40:43], v[112:115], v[172:175], v[40:43]
	v_mfma_f32_16x16x32_bf16 v[36:39], v[132:135], v[172:175], v[36:39]
	v_mfma_f32_16x16x32_bf16 v[24:27], v[112:115], v[180:183], v[24:27]
	v_mfma_f32_16x16x32_bf16 v[20:23], v[132:135], v[180:183], v[20:23]
	v_mfma_f32_16x16x32_bf16 v[8:11], v[112:115], v[188:191], v[8:11]
	v_mfma_f32_16x16x32_bf16 v[4:7], v[132:135], v[188:191], v[4:7]
	v_mfma_f32_16x16x32_bf16 v[56:59], v[120:123], v[168:171], v[56:59]
	v_mfma_f32_16x16x32_bf16 v[52:55], v[144:147], v[168:171], v[52:55]
	v_mfma_f32_16x16x32_bf16 v[40:43], v[120:123], v[176:179], v[40:43]
	v_mfma_f32_16x16x32_bf16 v[36:39], v[144:147], v[176:179], v[36:39]
	v_mfma_f32_16x16x32_bf16 v[24:27], v[120:123], v[184:187], v[24:27]
	v_mfma_f32_16x16x32_bf16 v[20:23], v[144:147], v[184:187], v[20:23]
	v_mfma_f32_16x16x32_bf16 v[8:11], v[120:123], v[208:211], v[8:11]
	v_mfma_f32_16x16x32_bf16 v[4:7], v[144:147], v[208:211], v[4:7]
	s_barrier
; #define PG8_STAGE(bufoff, gbase, voff) do { _Pragma("unroll") for (int _i = 0; _i < 2; ++_i) \
;         __builtin_amdgcn_global_load_lds((const unsigned*)((const char*)(gbase) + (voff)[_i]), (PG8_LAS unsigned*)(lds + (bufoff) + ldsw + _i * 8192), 16, 0, 0); } while (0)
; #define PG8_LDA(dst, b, h) do { _Pragma("unroll") for (int m = 0; m < 4; ++m) _Pragma("unroll") for (int k = 0; k < 2; ++k) dst[m][k] = *(const PG8_LAS bf16x8*)(lds + PG8_SA(b, h) + aoff + m * 2048 + k * 1024); } while (0)
; #define PG8_LDB(dst, b, h) do { _Pragma("unroll") for (int n = 0; n < 2; ++n) _Pragma("unroll") for (int k = 0; k < 2; ++k) dst[n][k] = *(const PG8_LAS bf16x8*)(lds + PG8_SB(b, h) + boff + n * 2048 + k * 1024); } while (0)
; template <class Epi, class Sched, bool ALIGN_EPI = false, bool SP2 = false>
; __device__ __forceinline__ void gemm_phase(PG8_LAS unsigned char* lds, const Gemm g, const Sched& S, const Epi& E) {
;     ...
;         for (int t = 0; t < nt; t += 2) {
;             const bool last = (t == nt - 2);
;             const char* a1 = cA + (size_t)(t + 1) * kstep;
;             const char* a2 = last ? nA : cA + (size_t)(t + 2) * kstep; const char* b2 = last ? nB : cB + (size_t)(t + 2) * kstep;
;             const char* a3 = a2 + kstep; const char* b3 = b2 + kstep;
;             if (last && has_next) S.a_ready(nxt);
;             if constexpr (SP2) {
;             PG8_LDB(B0, 0, 0); PG8_LDB(B1, 0, 1); PG8_SCHED; PG8_LDA(At, 0, 0); PG8_STAGE(PG8_SA(1, 1), a1 + hstep, voffA);
;             PG8_WAIT_V(8); PG8_WAIT_L(0); PG8_BAR; PG8_MMA(0, 0, At, B0); PG8_MMA(0, 1, At, B1); PG8_BAR; PG8_SCHED;
;             PG8_LDA(At, 0, 1); PG8_STAGE(PG8_SB(0, 0), b2, voffB); PG8_STAGE(PG8_SB(0, 1), b2 + hstep, voffB); PG8_STAGE(PG8_SA(0, 0), a2, voffA);
;             PG8_WAIT_V(8); PG8_WAIT_L(0); PG8_BAR; PG8_MMA(1, 0, At, B0); PG8_MMA(1, 1, At, B1); PG8_BAR; PG8_SCHED;
;             PG8_LDB(B0, 1, 0); PG8_LDB(B1, 1, 1); PG8_SCHED; PG8_LDA(At, 1, 0); PG8_STAGE(PG8_SA(0, 1), a2 + hstep, voffA);
;             PG8_WAIT_V(8); PG8_WAIT_L(0); PG8_BAR; PG8_MMA(0, 0, At, B0); PG8_MMA(0, 1, At, B1); PG8_BAR; PG8_SCHED;
;             PG8_LDA(At, 1, 1); PG8_STAGE(PG8_SB(1, 0), b3, voffB); PG8_STAGE(PG8_SB(1, 1), b3 + hstep, voffB); PG8_STAGE(PG8_SA(1, 0), a3, voffA);
;             PG8_WAIT_V(8); PG8_WAIT_L(0); PG8_BAR; PG8_MMA(1, 0, At, B0); PG8_MMA(1, 1, At, B1); PG8_BAR; PG8_SCHED;
.Lkmid_3:
	ds_read_b128 v[68:71], v234 offset:32768
	ds_read_b128 v[80:83], v234 offset:33792
	ds_read_b128 v[92:95], v234 offset:34816
	ds_read_b128 v[100:103], v234 offset:35840
	ds_read_b128 v[112:115], v234 offset:49152
	ds_read_b128 v[120:123], v234 offset:50176
	ds_read_b128 v[132:135], v234 offset:51200
	ds_read_b128 v[144:147], v234 offset:52224
	s_add_u32 s26, s30, 0xb0000
	s_addc_u32 s27, s31, 0
	s_mov_b32 m0, s42
	v_lshl_add_u64 v[218:219], s[26:27], 0, v[0:1]
	ds_read_b128 v[156:159], v236 offset:32768
	ds_read_b128 v[168:171], v236 offset:33792
	ds_read_b128 v[172:175], v236 offset:34816
	ds_read_b128 v[176:179], v236 offset:35840
	ds_read_b128 v[180:183], v236 offset:36864
	ds_read_b128 v[184:187], v236 offset:37888
	ds_read_b128 v[188:191], v236 offset:38912
	ds_read_b128 v[208:211], v236 offset:39936
	global_load_lds_dwordx4 v[218:219], off
	s_mov_b32 m0, s43
	v_lshl_add_u64 v[218:219], s[26:27], 0, v[194:195]
	global_load_lds_dwordx4 v[218:219], off
	s_waitcnt vmcnt(8) lgkmcnt(0)
	s_barrier
	v_mfma_f32_16x16x32_bf16 v[164:167], v[68:71], v[156:159], v[164:167]
	v_mfma_f32_16x16x32_bf16 v[160:163], v[92:95], v[156:159], v[160:163]
	v_mfma_f32_16x16x32_bf16 v[140:143], v[68:71], v[172:175], v[140:143]
	v_mfma_f32_16x16x32_bf16 v[136:139], v[92:95], v[172:175], v[136:139]
	v_mfma_f32_16x16x32_bf16 v[116:119], v[68:71], v[180:183], v[116:119]
	v_mfma_f32_16x16x32_bf16 v[108:111], v[92:95], v[180:183], v[108:111]
	v_mfma_f32_16x16x32_bf16 v[88:91], v[68:71], v[188:191], v[88:91]
	v_mfma_f32_16x16x32_bf16 v[84:87], v[92:95], v[188:191], v[84:87]
	v_mfma_f32_16x16x32_bf16 v[164:167], v[80:83], v[168:171], v[164:167]
	v_mfma_f32_16x16x32_bf16 v[160:163], v[100:103], v[168:171], v[160:163]
	v_mfma_f32_16x16x32_bf16 v[140:143], v[80:83], v[176:179], v[140:143]
	v_mfma_f32_16x16x32_bf16 v[136:139], v[100:103], v[176:179], v[136:139]
	v_mfma_f32_16x16x32_bf16 v[116:119], v[80:83], v[184:187], v[116:119]
	v_mfma_f32_16x16x32_bf16 v[108:111], v[100:103], v[184:187], v[108:111]
	v_mfma_f32_16x16x32_bf16 v[88:91], v[80:83], v[208:211], v[88:91]
	v_mfma_f32_16x16x32_bf16 v[84:87], v[100:103], v[208:211], v[84:87]
	v_mfma_f32_16x16x32_bf16 v[152:155], v[112:115], v[156:159], v[152:155]
	v_mfma_f32_16x16x32_bf16 v[148:151], v[132:135], v[156:159], v[148:151]
	v_mfma_f32_16x16x32_bf16 v[128:131], v[112:115], v[172:175], v[128:131]
	v_mfma_f32_16x16x32_bf16 v[124:127], v[132:135], v[172:175], v[124:127]
	v_mfma_f32_16x16x32_bf16 v[104:107], v[112:115], v[180:183], v[104:107]
	v_mfma_f32_16x16x32_bf16 v[96:99], v[132:135], v[180:183], v[96:99]
	v_mfma_f32_16x16x32_bf16 v[76:79], v[112:115], v[188:191], v[76:79]
	v_mfma_f32_16x16x32_bf16 v[72:75], v[132:135], v[188:191], v[72:75]
	v_mfma_f32_16x16x32_bf16 v[152:155], v[120:123], v[168:171], v[152:155]
	v_mfma_f32_16x16x32_bf16 v[148:151], v[144:147], v[168:171], v[148:151]
	v_mfma_f32_16x16x32_bf16 v[128:131], v[120:123], v[176:179], v[128:131]
	v_mfma_f32_16x16x32_bf16 v[124:127], v[144:147], v[176:179], v[124:127]
	v_mfma_f32_16x16x32_bf16 v[104:107], v[120:123], v[184:187], v[104:107]
	v_mfma_f32_16x16x32_bf16 v[96:99], v[144:147], v[184:187], v[96:99]
	v_mfma_f32_16x16x32_bf16 v[76:79], v[120:123], v[208:211], v[76:79]
	v_mfma_f32_16x16x32_bf16 v[72:75], v[144:147], v[208:211], v[72:75]
	s_barrier
	s_add_i32 m0, s39, 0x17f80
	ds_read_b128 v[156:159], v236 offset:49152
	ds_read_b128 v[168:171], v236 offset:50176
	ds_read_b128 v[172:175], v236 offset:51200
	ds_read_b128 v[176:179], v236 offset:52224
	ds_read_b128 v[180:183], v236 offset:53248
	ds_read_b128 v[184:187], v236 offset:54272
	ds_read_b128 v[188:191], v236 offset:55296
	ds_read_b128 v[208:211], v236 offset:56320
	global_load_lds_dwordx4 v[198:199], off offset:128
	s_add_i32 m0, s39, 0x19f80
	s_add_u32 s26, s28, 0xb0080
	s_addc_u32 s27, s29, 0
	global_load_lds_dwordx4 v[212:213], off offset:128
	s_add_i32 m0, s39, 0x1c000
	v_lshl_add_u64 v[198:199], s[26:27], 0, v[192:193]
	global_load_lds_dwordx4 v[198:199], off
	s_add_i32 m0, s39, 0x1e000
	v_lshl_add_u64 v[198:199], s[26:27], 0, v[202:203]
	global_load_lds_dwordx4 v[198:199], off
	s_add_i32 m0, s47, 0xffffff80
	s_add_u32 s44, s44, 0x100
	s_addc_u32 s45, s45, 0
	global_load_lds_dwordx4 v[214:215], off offset:128
	s_add_i32 m0, s48, 0xffffff80
	s_mov_b64 s[26:27], s[8:9]
	global_load_lds_dwordx4 v[216:217], off offset:128
	s_waitcnt vmcnt(8) lgkmcnt(0)
	s_barrier
	v_mfma_f32_16x16x32_bf16 v[64:67], v[68:71], v[156:159], v[64:67]
	v_mfma_f32_16x16x32_bf16 v[60:63], v[92:95], v[156:159], v[60:63]
	v_mfma_f32_16x16x32_bf16 v[48:51], v[68:71], v[172:175], v[48:51]
	v_mfma_f32_16x16x32_bf16 v[44:47], v[92:95], v[172:175], v[44:47]
	v_mfma_f32_16x16x32_bf16 v[32:35], v[68:71], v[180:183], v[32:35]
	v_mfma_f32_16x16x32_bf16 v[28:31], v[92:95], v[180:183], v[28:31]
	v_mfma_f32_16x16x32_bf16 v[16:19], v[68:71], v[188:191], v[16:19]
	v_mfma_f32_16x16x32_bf16 v[12:15], v[92:95], v[188:191], v[12:15]
	v_mfma_f32_16x16x32_bf16 v[64:67], v[80:83], v[168:171], v[64:67]
	v_mfma_f32_16x16x32_bf16 v[60:63], v[100:103], v[168:171], v[60:63]
	v_mfma_f32_16x16x32_bf16 v[48:51], v[80:83], v[176:179], v[48:51]
	v_mfma_f32_16x16x32_bf16 v[44:47], v[100:103], v[176:179], v[44:47]
	v_mfma_f32_16x16x32_bf16 v[32:35], v[80:83], v[184:187], v[32:35]
	v_mfma_f32_16x16x32_bf16 v[28:31], v[100:103], v[184:187], v[28:31]
	v_mfma_f32_16x16x32_bf16 v[16:19], v[80:83], v[208:211], v[16:19]
	v_mfma_f32_16x16x32_bf16 v[12:15], v[100:103], v[208:211], v[12:15]
	v_mfma_f32_16x16x32_bf16 v[56:59], v[112:115], v[156:159], v[56:59]
	v_mfma_f32_16x16x32_bf16 v[52:55], v[132:135], v[156:159], v[52:55]
	v_mfma_f32_16x16x32_bf16 v[40:43], v[112:115], v[172:175], v[40:43]
	v_mfma_f32_16x16x32_bf16 v[36:39], v[132:135], v[172:175], v[36:39]
	v_mfma_f32_16x16x32_bf16 v[24:27], v[112:115], v[180:183], v[24:27]
	v_mfma_f32_16x16x32_bf16 v[20:23], v[132:135], v[180:183], v[20:23]
	v_mfma_f32_16x16x32_bf16 v[8:11], v[112:115], v[188:191], v[8:11]
	v_mfma_f32_16x16x32_bf16 v[4:7], v[132:135], v[188:191], v[4:7]
	v_mfma_f32_16x16x32_bf16 v[56:59], v[120:123], v[168:171], v[56:59]
	v_mfma_f32_16x16x32_bf16 v[52:55], v[144:147], v[168:171], v[52:55]
	v_mfma_f32_16x16x32_bf16 v[40:43], v[120:123], v[176:179], v[40:43]
	v_mfma_f32_16x16x32_bf16 v[36:39], v[144:147], v[176:179], v[36:39]
	v_mfma_f32_16x16x32_bf16 v[24:27], v[120:123], v[184:187], v[24:27]
	v_mfma_f32_16x16x32_bf16 v[20:23], v[144:147], v[184:187], v[20:23]
	v_mfma_f32_16x16x32_bf16 v[8:11], v[120:123], v[208:211], v[8:11]
	v_mfma_f32_16x16x32_bf16 v[4:7], v[144:147], v[208:211], v[4:7]
	s_barrier
	s_add_i32 s53, s53, 2
	s_cmp_gt_u32 s53, 41
	s_cbranch_scc0 .LBB0_480
	s_and_b64 vcc, exec, s[20:21]
	s_cbranch_vccz .LBB0_483
	s_barrier

; __device__ __forceinline__ void xcd_barrier(const XcdBarrier& b) {
;     asm volatile("s_waitcnt vmcnt(0)" ::: "memory");
;     __syncthreads();
;     if (threadIdx.x == 0) {
;         unsigned* bar = b.bar; unsigned bx_ = b.x;
;         asm volatile("" : "+s"(bar), "+s"(bx_));
;         __builtin_amdgcn_s_waitcnt(0);
;         unsigned nloc = b.st[0], nx = b.st[1];
;         if (nloc == 0u) { xcd_barrier_complete(bar, bx_, nloc, nx); b.st[0] = nloc; b.st[1] = nx; }
.LBB0_583:
	s_setprio 0
	s_waitcnt vmcnt(0)
	s_waitcnt lgkmcnt(0)
	s_barrier
	s_and_saveexec_b64 s[36:37], s[62:63]
	s_cbranch_execz .LBB0_78
	s_mov_b64 s[38:39], s[58:59]
	s_mov_b32 s3, s99
	v_mov_b32_e32 v0, s70
	s_waitcnt vmcnt(0) expcnt(0) lgkmcnt(0)
	ds_read_b32 v4, v0
	v_mov_b32_e32 v0, s71
	ds_read_b32 v0, v0
	s_waitcnt lgkmcnt(1)
	v_cmp_ne_u32_e32 vcc, 0, v4
	s_cbranch_vccnz .LBB0_598
	s_add_u32 s4, s38, 0x1000
	s_addc_u32 s5, s39, 0
	s_add_u32 s6, s38, 0x1100
	s_addc_u32 s7, s39, 0
	s_add_u32 s8, s38, 0x1200
	s_addc_u32 s9, s39, 0
	s_add_u32 s10, s38, 0x1300
	s_addc_u32 s11, s39, 0
	s_mov_b32 s30, 1
	s_mov_b64 s[12:13], 0
	s_branch .LBB0_588
